# v36 + nt hint also on P11 partial-sum stores and P12 partial-sum loads
# baseline (speedup 1.0000x reference)
; DI f2_t cvt8lo(unsigned w) { return __builtin_amdgcn_cvt_pk_f32_fp8(w, false); }
; DI f2_t cvt8hi(unsigned w) { return __builtin_amdgcn_cvt_pk_f32_fp8(w, true); }
; DI void wave_lds_sync() { asm volatile("s_waitcnt lgkmcnt(0)" ::: "memory"); __builtin_amdgcn_wave_barrier(); }
; DI void phase11(const Params& p, char* smem, int rep) {
;     ...
;       const int tok = __builtin_amdgcn_readfirstlane(c * 16 + w * 4 + t);
;       const int i0 = IDS[(size_t)tok * 128 + lane], i1 = IDS[(size_t)tok * 128 + 64 + lane];
;       const float a0 = ACT[(size_t)tok * 128 + lane], a1 = ACT[(size_t)tok * 128 + 64 + lane];
;       wave_lds_sync();
;       lw[(lane & 3) * 32 + (lane >> 2)] = i0; lw[(lane & 3) * 32 + 16 + (lane >> 2)] = i1;
;       lf[(lane & 3) * 32 + (lane >> 2)] = a0; lf[(lane & 3) * 32 + 16 + (lane >> 2)] = a1;
;       wave_lds_sync();
;       f2_t o[8];
; #pragma unroll
;       for (int i = 0; i < 8; ++i) o[i] = f2_t{0.f, 0.f};
;       const unsigned char* vb = V8 + s * 256 + l15 * 16;
; #pragma unroll
;       for (int batch = 0; batch < 2; ++batch) {
;         int ida[16]; float aa[16];
; #pragma unroll
;         for (int q = 0; q < 4; ++q) {
;           const int4 v = *(const int4*)(lw + g * 32 + batch * 16 + q * 4); ida[q * 4] = v.x; ida[q * 4 + 1] = v.y; ida[q * 4 + 2] = v.z; ida[q * 4 + 3] = v.w;
;           const float4 f = *(const float4*)(lf + g * 32 + batch * 16 + q * 4); aa[q * 4] = f.x; aa[q * 4 + 1] = f.y; aa[q * 4 + 2] = f.z; aa[q * 4 + 3] = f.w;
;         }
;         u32x4 rows[16];
; #pragma unroll
;         for (int k = 0; k < 16; ++k) rows[k] = *(const u32x4*)(vb + (size_t)ida[k] * 2048);
; #pragma unroll
;         for (int k = 0; k < 16; ++k) {
;           const f2_t a2 = {aa[k], aa[k]};
; #pragma unroll
;           for (int d = 0; d < 4; ++d) { const unsigned ww = rows[k][d]; o[2 * d] += a2 * cvt8lo(ww); o[2 * d + 1] += a2 * cvt8hi(ww); }
.Lp11_body:
	s_add_i32 s54, s34, 0
	s_lshl_b32 s46, s54, 12
	s_add_i32 s46, s46, s24
	s_add_i32 s55, s34, 1
	s_lshl_b32 s47, s55, 9
	s_add_u32 s42, s6, s47
	s_addc_u32 s43, s7, 0
	s_add_u32 s44, s8, s47
	s_addc_u32 s45, s9, 0
	global_load_dword v10, v3, s[42:43]
	global_load_dword v11, v3, s[42:43] offset:256
	global_load_dword v12, v3, s[44:45]
	global_load_dword v13, v3, s[44:45] offset:256
	s_waitcnt lgkmcnt(0)
	v_lshl_add_u32 v20, v20, 11, v2
	v_lshl_add_u32 v21, v21, 11, v2
	v_lshl_add_u32 v22, v22, 11, v2
	v_lshl_add_u32 v23, v23, 11, v2
	v_lshl_add_u32 v24, v24, 11, v2
	v_lshl_add_u32 v25, v25, 11, v2
	v_lshl_add_u32 v26, v26, 11, v2
	v_lshl_add_u32 v27, v27, 11, v2
	v_lshl_add_u32 v28, v28, 11, v2
	v_lshl_add_u32 v29, v29, 11, v2
	v_lshl_add_u32 v30, v30, 11, v2
	v_lshl_add_u32 v31, v31, 11, v2
	v_lshl_add_u32 v32, v32, 11, v2
	v_lshl_add_u32 v33, v33, 11, v2
	v_lshl_add_u32 v34, v34, 11, v2
	v_lshl_add_u32 v35, v35, 11, v2
	v_lshl_add_u32 v36, v36, 11, v2
	v_lshl_add_u32 v37, v37, 11, v2
	v_lshl_add_u32 v38, v38, 11, v2
	v_lshl_add_u32 v39, v39, 11, v2
	v_lshl_add_u32 v40, v40, 11, v2
	v_lshl_add_u32 v41, v41, 11, v2
	v_lshl_add_u32 v42, v42, 11, v2
	v_lshl_add_u32 v43, v43, 11, v2
	v_lshl_add_u32 v44, v44, 11, v2
	v_lshl_add_u32 v45, v45, 11, v2
	v_lshl_add_u32 v46, v46, 11, v2
	v_lshl_add_u32 v47, v47, 11, v2
	v_lshl_add_u32 v48, v48, 11, v2
	v_lshl_add_u32 v49, v49, 11, v2
	v_lshl_add_u32 v50, v50, 11, v2
	v_lshl_add_u32 v51, v51, 11, v2
	global_load_dwordx4 v[84:87], v20, s[20:21]
	global_load_dwordx4 v[88:91], v21, s[20:21]
	global_load_dwordx4 v[92:95], v22, s[20:21]
	global_load_dwordx4 v[96:99], v23, s[20:21]
	global_load_dwordx4 v[100:103], v24, s[20:21]
	global_load_dwordx4 v[104:107], v25, s[20:21]
	global_load_dwordx4 v[108:111], v26, s[20:21]
	global_load_dwordx4 v[112:115], v27, s[20:21]
	global_load_dwordx4 v[116:119], v28, s[20:21]
	global_load_dwordx4 v[120:123], v29, s[20:21]
	global_load_dwordx4 v[124:127], v30, s[20:21]
	global_load_dwordx4 v[128:131], v31, s[20:21]
	global_load_dwordx4 v[132:135], v32, s[20:21]
	global_load_dwordx4 v[136:139], v33, s[20:21]
	global_load_dwordx4 v[140:143], v34, s[20:21]
	global_load_dwordx4 v[144:147], v35, s[20:21]
	global_load_dwordx4 v[148:151], v36, s[20:21]
	global_load_dwordx4 v[152:155], v37, s[20:21]
	global_load_dwordx4 v[156:159], v38, s[20:21]
	global_load_dwordx4 v[160:163], v39, s[20:21]
	global_load_dwordx4 v[164:167], v40, s[20:21]
	global_load_dwordx4 v[168:171], v41, s[20:21]
	global_load_dwordx4 v[172:175], v42, s[20:21]
	global_load_dwordx4 v[176:179], v43, s[20:21]
	global_load_dwordx4 v[180:183], v44, s[20:21]
	global_load_dwordx4 v[184:187], v45, s[20:21]
	global_load_dwordx4 v[190:193], v46, s[20:21]
	global_load_dwordx4 v[194:197], v47, s[20:21]
	global_load_dwordx4 v[198:201], v48, s[20:21]
	global_load_dwordx4 v[202:205], v49, s[20:21]
	global_load_dwordx4 v[206:209], v50, s[20:21]
	global_load_dwordx4 v[210:213], v51, s[20:21]
	s_waitcnt vmcnt(31)
	v_cvt_pk_f32_fp8_e32 v[232:233], v84
	v_cvt_pk_f32_fp8_sdwa v[234:235], v84 src0_sel:WORD_1
	v_pk_fma_f32 v[216:217], v[52:53], v[232:233], 0 op_sel_hi:[0,1,0]
	v_pk_fma_f32 v[218:219], v[52:53], v[234:235], 0 op_sel_hi:[0,1,0]
	v_cvt_pk_f32_fp8_e32 v[236:237], v85
	v_cvt_pk_f32_fp8_sdwa v[238:239], v85 src0_sel:WORD_1
	v_pk_fma_f32 v[220:221], v[52:53], v[236:237], 0 op_sel_hi:[0,1,0]
	v_pk_fma_f32 v[222:223], v[52:53], v[238:239], 0 op_sel_hi:[0,1,0]
	v_cvt_pk_f32_fp8_e32 v[232:233], v86
	v_cvt_pk_f32_fp8_sdwa v[234:235], v86 src0_sel:WORD_1
	v_pk_fma_f32 v[224:225], v[52:53], v[232:233], 0 op_sel_hi:[0,1,0]
	v_pk_fma_f32 v[226:227], v[52:53], v[234:235], 0 op_sel_hi:[0,1,0]
	v_cvt_pk_f32_fp8_e32 v[236:237], v87
	v_cvt_pk_f32_fp8_sdwa v[238:239], v87 src0_sel:WORD_1
	v_pk_fma_f32 v[228:229], v[52:53], v[236:237], 0 op_sel_hi:[0,1,0]
	v_pk_fma_f32 v[230:231], v[52:53], v[238:239], 0 op_sel_hi:[0,1,0]
	s_waitcnt vmcnt(30)
	v_cvt_pk_f32_fp8_e32 v[232:233], v88
	v_cvt_pk_f32_fp8_sdwa v[234:235], v88 src0_sel:WORD_1
	v_pk_fma_f32 v[216:217], v[52:53], v[232:233], v[216:217] op_sel:[1,0,0]
	v_pk_fma_f32 v[218:219], v[52:53], v[234:235], v[218:219] op_sel:[1,0,0]
	v_cvt_pk_f32_fp8_e32 v[236:237], v89
	v_cvt_pk_f32_fp8_sdwa v[238:239], v89 src0_sel:WORD_1
	v_pk_fma_f32 v[220:221], v[52:53], v[236:237], v[220:221] op_sel:[1,0,0]
	v_pk_fma_f32 v[222:223], v[52:53], v[238:239], v[222:223] op_sel:[1,0,0]
	v_cvt_pk_f32_fp8_e32 v[232:233], v90
	v_cvt_pk_f32_fp8_sdwa v[234:235], v90 src0_sel:WORD_1
	v_pk_fma_f32 v[224:225], v[52:53], v[232:233], v[224:225] op_sel:[1,0,0]
	v_pk_fma_f32 v[226:227], v[52:53], v[234:235], v[226:227] op_sel:[1,0,0]
	v_cvt_pk_f32_fp8_e32 v[236:237], v91
	v_cvt_pk_f32_fp8_sdwa v[238:239], v91 src0_sel:WORD_1
	v_pk_fma_f32 v[228:229], v[52:53], v[236:237], v[228:229] op_sel:[1,0,0]
	v_pk_fma_f32 v[230:231], v[52:53], v[238:239], v[230:231] op_sel:[1,0,0]
	s_waitcnt vmcnt(29)
	v_cvt_pk_f32_fp8_e32 v[232:233], v92
	v_cvt_pk_f32_fp8_sdwa v[234:235], v92 src0_sel:WORD_1
	v_pk_fma_f32 v[216:217], v[54:55], v[232:233], v[216:217] op_sel_hi:[0,1,1]
	v_pk_fma_f32 v[218:219], v[54:55], v[234:235], v[218:219] op_sel_hi:[0,1,1]
	v_cvt_pk_f32_fp8_e32 v[236:237], v93
	v_cvt_pk_f32_fp8_sdwa v[238:239], v93 src0_sel:WORD_1
	v_pk_fma_f32 v[220:221], v[54:55], v[236:237], v[220:221] op_sel_hi:[0,1,1]
	v_pk_fma_f32 v[222:223], v[54:55], v[238:239], v[222:223] op_sel_hi:[0,1,1]
	v_cvt_pk_f32_fp8_e32 v[232:233], v94
	v_cvt_pk_f32_fp8_sdwa v[234:235], v94 src0_sel:WORD_1
	v_pk_fma_f32 v[224:225], v[54:55], v[232:233], v[224:225] op_sel_hi:[0,1,1]
	v_pk_fma_f32 v[226:227], v[54:55], v[234:235], v[226:227] op_sel_hi:[0,1,1]
	v_cvt_pk_f32_fp8_e32 v[236:237], v95
	v_cvt_pk_f32_fp8_sdwa v[238:239], v95 src0_sel:WORD_1
	v_pk_fma_f32 v[228:229], v[54:55], v[236:237], v[228:229] op_sel_hi:[0,1,1]
	v_pk_fma_f32 v[230:231], v[54:55], v[238:239], v[230:231] op_sel_hi:[0,1,1]
	s_waitcnt vmcnt(28)
; DI f2_t cvt8lo(unsigned w) { return __builtin_amdgcn_cvt_pk_f32_fp8(w, false); }
; DI f2_t cvt8hi(unsigned w) { return __builtin_amdgcn_cvt_pk_f32_fp8(w, true); }
; DI void phase11(const Params& p, char* smem, int rep) {
;     ...
;         for (int k = 0; k < 16; ++k) {
;           const f2_t a2 = {aa[k], aa[k]};
; #pragma unroll
;           for (int d = 0; d < 4; ++d) { const unsigned ww = rows[k][d]; o[2 * d] += a2 * cvt8lo(ww); o[2 * d + 1] += a2 * cvt8hi(ww); }
;         }
	v_cvt_pk_f32_fp8_e32 v[232:233], v96
	v_cvt_pk_f32_fp8_sdwa v[234:235], v96 src0_sel:WORD_1
	v_pk_fma_f32 v[216:217], v[54:55], v[232:233], v[216:217] op_sel:[1,0,0]
	v_pk_fma_f32 v[218:219], v[54:55], v[234:235], v[218:219] op_sel:[1,0,0]
	v_cvt_pk_f32_fp8_e32 v[236:237], v97
	v_cvt_pk_f32_fp8_sdwa v[238:239], v97 src0_sel:WORD_1
	v_pk_fma_f32 v[220:221], v[54:55], v[236:237], v[220:221] op_sel:[1,0,0]
	v_pk_fma_f32 v[222:223], v[54:55], v[238:239], v[222:223] op_sel:[1,0,0]
	v_cvt_pk_f32_fp8_e32 v[232:233], v98
	v_cvt_pk_f32_fp8_sdwa v[234:235], v98 src0_sel:WORD_1
	v_pk_fma_f32 v[224:225], v[54:55], v[232:233], v[224:225] op_sel:[1,0,0]
	v_pk_fma_f32 v[226:227], v[54:55], v[234:235], v[226:227] op_sel:[1,0,0]
	v_cvt_pk_f32_fp8_e32 v[236:237], v99
	v_cvt_pk_f32_fp8_sdwa v[238:239], v99 src0_sel:WORD_1
	v_pk_fma_f32 v[228:229], v[54:55], v[236:237], v[228:229] op_sel:[1,0,0]
	v_pk_fma_f32 v[230:231], v[54:55], v[238:239], v[230:231] op_sel:[1,0,0]
	s_waitcnt vmcnt(27)
	v_cvt_pk_f32_fp8_e32 v[232:233], v100
	v_cvt_pk_f32_fp8_sdwa v[234:235], v100 src0_sel:WORD_1
	v_pk_fma_f32 v[216:217], v[56:57], v[232:233], v[216:217] op_sel_hi:[0,1,1]
	v_pk_fma_f32 v[218:219], v[56:57], v[234:235], v[218:219] op_sel_hi:[0,1,1]
	v_cvt_pk_f32_fp8_e32 v[236:237], v101
	v_cvt_pk_f32_fp8_sdwa v[238:239], v101 src0_sel:WORD_1
	v_pk_fma_f32 v[220:221], v[56:57], v[236:237], v[220:221] op_sel_hi:[0,1,1]
	v_pk_fma_f32 v[222:223], v[56:57], v[238:239], v[222:223] op_sel_hi:[0,1,1]
	v_cvt_pk_f32_fp8_e32 v[232:233], v102
	v_cvt_pk_f32_fp8_sdwa v[234:235], v102 src0_sel:WORD_1
	v_pk_fma_f32 v[224:225], v[56:57], v[232:233], v[224:225] op_sel_hi:[0,1,1]
	v_pk_fma_f32 v[226:227], v[56:57], v[234:235], v[226:227] op_sel_hi:[0,1,1]
	v_cvt_pk_f32_fp8_e32 v[236:237], v103
	v_cvt_pk_f32_fp8_sdwa v[238:239], v103 src0_sel:WORD_1
	v_pk_fma_f32 v[228:229], v[56:57], v[236:237], v[228:229] op_sel_hi:[0,1,1]
	v_pk_fma_f32 v[230:231], v[56:57], v[238:239], v[230:231] op_sel_hi:[0,1,1]
	s_waitcnt vmcnt(26)
	v_cvt_pk_f32_fp8_e32 v[232:233], v104
	v_cvt_pk_f32_fp8_sdwa v[234:235], v104 src0_sel:WORD_1
	v_pk_fma_f32 v[216:217], v[56:57], v[232:233], v[216:217] op_sel:[1,0,0]
	v_pk_fma_f32 v[218:219], v[56:57], v[234:235], v[218:219] op_sel:[1,0,0]
	v_cvt_pk_f32_fp8_e32 v[236:237], v105
	v_cvt_pk_f32_fp8_sdwa v[238:239], v105 src0_sel:WORD_1
	v_pk_fma_f32 v[220:221], v[56:57], v[236:237], v[220:221] op_sel:[1,0,0]
	v_pk_fma_f32 v[222:223], v[56:57], v[238:239], v[222:223] op_sel:[1,0,0]
	v_cvt_pk_f32_fp8_e32 v[232:233], v106
	v_cvt_pk_f32_fp8_sdwa v[234:235], v106 src0_sel:WORD_1
	v_pk_fma_f32 v[224:225], v[56:57], v[232:233], v[224:225] op_sel:[1,0,0]
	v_pk_fma_f32 v[226:227], v[56:57], v[234:235], v[226:227] op_sel:[1,0,0]
	v_cvt_pk_f32_fp8_e32 v[236:237], v107
	v_cvt_pk_f32_fp8_sdwa v[238:239], v107 src0_sel:WORD_1
	v_pk_fma_f32 v[228:229], v[56:57], v[236:237], v[228:229] op_sel:[1,0,0]
	v_pk_fma_f32 v[230:231], v[56:57], v[238:239], v[230:231] op_sel:[1,0,0]
	s_waitcnt vmcnt(25)
	v_cvt_pk_f32_fp8_e32 v[232:233], v108
	v_cvt_pk_f32_fp8_sdwa v[234:235], v108 src0_sel:WORD_1
	v_pk_fma_f32 v[216:217], v[58:59], v[232:233], v[216:217] op_sel_hi:[0,1,1]
	v_pk_fma_f32 v[218:219], v[58:59], v[234:235], v[218:219] op_sel_hi:[0,1,1]
	v_cvt_pk_f32_fp8_e32 v[236:237], v109
	v_cvt_pk_f32_fp8_sdwa v[238:239], v109 src0_sel:WORD_1
	v_pk_fma_f32 v[220:221], v[58:59], v[236:237], v[220:221] op_sel_hi:[0,1,1]
	v_pk_fma_f32 v[222:223], v[58:59], v[238:239], v[222:223] op_sel_hi:[0,1,1]
	v_cvt_pk_f32_fp8_e32 v[232:233], v110
	v_cvt_pk_f32_fp8_sdwa v[234:235], v110 src0_sel:WORD_1
	v_pk_fma_f32 v[224:225], v[58:59], v[232:233], v[224:225] op_sel_hi:[0,1,1]
	v_pk_fma_f32 v[226:227], v[58:59], v[234:235], v[226:227] op_sel_hi:[0,1,1]
	v_cvt_pk_f32_fp8_e32 v[236:237], v111
	v_cvt_pk_f32_fp8_sdwa v[238:239], v111 src0_sel:WORD_1
	v_pk_fma_f32 v[228:229], v[58:59], v[236:237], v[228:229] op_sel_hi:[0,1,1]
	v_pk_fma_f32 v[230:231], v[58:59], v[238:239], v[230:231] op_sel_hi:[0,1,1]
	s_waitcnt vmcnt(24)
	v_cvt_pk_f32_fp8_e32 v[232:233], v112
	v_cvt_pk_f32_fp8_sdwa v[234:235], v112 src0_sel:WORD_1
	v_pk_fma_f32 v[216:217], v[58:59], v[232:233], v[216:217] op_sel:[1,0,0]
	v_pk_fma_f32 v[218:219], v[58:59], v[234:235], v[218:219] op_sel:[1,0,0]
	v_cvt_pk_f32_fp8_e32 v[236:237], v113
	v_cvt_pk_f32_fp8_sdwa v[238:239], v113 src0_sel:WORD_1
	v_pk_fma_f32 v[220:221], v[58:59], v[236:237], v[220:221] op_sel:[1,0,0]
	v_pk_fma_f32 v[222:223], v[58:59], v[238:239], v[222:223] op_sel:[1,0,0]
	v_cvt_pk_f32_fp8_e32 v[232:233], v114
	v_cvt_pk_f32_fp8_sdwa v[234:235], v114 src0_sel:WORD_1
	v_pk_fma_f32 v[224:225], v[58:59], v[232:233], v[224:225] op_sel:[1,0,0]
	v_pk_fma_f32 v[226:227], v[58:59], v[234:235], v[226:227] op_sel:[1,0,0]
	v_cvt_pk_f32_fp8_e32 v[236:237], v115
	v_cvt_pk_f32_fp8_sdwa v[238:239], v115 src0_sel:WORD_1
	v_pk_fma_f32 v[228:229], v[58:59], v[236:237], v[228:229] op_sel:[1,0,0]
	v_pk_fma_f32 v[230:231], v[58:59], v[238:239], v[230:231] op_sel:[1,0,0]
	s_waitcnt vmcnt(23)
	v_cvt_pk_f32_fp8_e32 v[232:233], v116
	v_cvt_pk_f32_fp8_sdwa v[234:235], v116 src0_sel:WORD_1
	v_pk_fma_f32 v[216:217], v[60:61], v[232:233], v[216:217] op_sel_hi:[0,1,1]
	v_pk_fma_f32 v[218:219], v[60:61], v[234:235], v[218:219] op_sel_hi:[0,1,1]
	v_cvt_pk_f32_fp8_e32 v[236:237], v117
	v_cvt_pk_f32_fp8_sdwa v[238:239], v117 src0_sel:WORD_1
	v_pk_fma_f32 v[220:221], v[60:61], v[236:237], v[220:221] op_sel_hi:[0,1,1]
	v_pk_fma_f32 v[222:223], v[60:61], v[238:239], v[222:223] op_sel_hi:[0,1,1]
	v_cvt_pk_f32_fp8_e32 v[232:233], v118
	v_cvt_pk_f32_fp8_sdwa v[234:235], v118 src0_sel:WORD_1
	v_pk_fma_f32 v[224:225], v[60:61], v[232:233], v[224:225] op_sel_hi:[0,1,1]
	v_pk_fma_f32 v[226:227], v[60:61], v[234:235], v[226:227] op_sel_hi:[0,1,1]
	v_cvt_pk_f32_fp8_e32 v[236:237], v119
	v_cvt_pk_f32_fp8_sdwa v[238:239], v119 src0_sel:WORD_1
	v_pk_fma_f32 v[228:229], v[60:61], v[236:237], v[228:229] op_sel_hi:[0,1,1]
	v_pk_fma_f32 v[230:231], v[60:61], v[238:239], v[230:231] op_sel_hi:[0,1,1]
	s_waitcnt vmcnt(22)
; DI f2_t cvt8lo(unsigned w) { return __builtin_amdgcn_cvt_pk_f32_fp8(w, false); }
; DI f2_t cvt8hi(unsigned w) { return __builtin_amdgcn_cvt_pk_f32_fp8(w, true); }
; DI void phase11(const Params& p, char* smem, int rep) {
;     ...
;         for (int k = 0; k < 16; ++k) {
;           const f2_t a2 = {aa[k], aa[k]};
; #pragma unroll
;           for (int d = 0; d < 4; ++d) { const unsigned ww = rows[k][d]; o[2 * d] += a2 * cvt8lo(ww); o[2 * d + 1] += a2 * cvt8hi(ww); }
;         }
	v_cvt_pk_f32_fp8_e32 v[232:233], v120
	v_cvt_pk_f32_fp8_sdwa v[234:235], v120 src0_sel:WORD_1
	v_pk_fma_f32 v[216:217], v[60:61], v[232:233], v[216:217] op_sel:[1,0,0]
	v_pk_fma_f32 v[218:219], v[60:61], v[234:235], v[218:219] op_sel:[1,0,0]
	v_cvt_pk_f32_fp8_e32 v[236:237], v121
	v_cvt_pk_f32_fp8_sdwa v[238:239], v121 src0_sel:WORD_1
	v_pk_fma_f32 v[220:221], v[60:61], v[236:237], v[220:221] op_sel:[1,0,0]
	v_pk_fma_f32 v[222:223], v[60:61], v[238:239], v[222:223] op_sel:[1,0,0]
	v_cvt_pk_f32_fp8_e32 v[232:233], v122
	v_cvt_pk_f32_fp8_sdwa v[234:235], v122 src0_sel:WORD_1
	v_pk_fma_f32 v[224:225], v[60:61], v[232:233], v[224:225] op_sel:[1,0,0]
	v_pk_fma_f32 v[226:227], v[60:61], v[234:235], v[226:227] op_sel:[1,0,0]
	v_cvt_pk_f32_fp8_e32 v[236:237], v123
	v_cvt_pk_f32_fp8_sdwa v[238:239], v123 src0_sel:WORD_1
	v_pk_fma_f32 v[228:229], v[60:61], v[236:237], v[228:229] op_sel:[1,0,0]
	v_pk_fma_f32 v[230:231], v[60:61], v[238:239], v[230:231] op_sel:[1,0,0]
	s_waitcnt vmcnt(21)
	v_cvt_pk_f32_fp8_e32 v[232:233], v124
	v_cvt_pk_f32_fp8_sdwa v[234:235], v124 src0_sel:WORD_1
	v_pk_fma_f32 v[216:217], v[62:63], v[232:233], v[216:217] op_sel_hi:[0,1,1]
	v_pk_fma_f32 v[218:219], v[62:63], v[234:235], v[218:219] op_sel_hi:[0,1,1]
	v_cvt_pk_f32_fp8_e32 v[236:237], v125
	v_cvt_pk_f32_fp8_sdwa v[238:239], v125 src0_sel:WORD_1
	v_pk_fma_f32 v[220:221], v[62:63], v[236:237], v[220:221] op_sel_hi:[0,1,1]
	v_pk_fma_f32 v[222:223], v[62:63], v[238:239], v[222:223] op_sel_hi:[0,1,1]
	v_cvt_pk_f32_fp8_e32 v[232:233], v126
	v_cvt_pk_f32_fp8_sdwa v[234:235], v126 src0_sel:WORD_1
	v_pk_fma_f32 v[224:225], v[62:63], v[232:233], v[224:225] op_sel_hi:[0,1,1]
	v_pk_fma_f32 v[226:227], v[62:63], v[234:235], v[226:227] op_sel_hi:[0,1,1]
	v_cvt_pk_f32_fp8_e32 v[236:237], v127
	v_cvt_pk_f32_fp8_sdwa v[238:239], v127 src0_sel:WORD_1
	v_pk_fma_f32 v[228:229], v[62:63], v[236:237], v[228:229] op_sel_hi:[0,1,1]
	v_pk_fma_f32 v[230:231], v[62:63], v[238:239], v[230:231] op_sel_hi:[0,1,1]
	s_waitcnt vmcnt(20)
	v_cvt_pk_f32_fp8_e32 v[232:233], v128
	v_cvt_pk_f32_fp8_sdwa v[234:235], v128 src0_sel:WORD_1
	v_pk_fma_f32 v[216:217], v[62:63], v[232:233], v[216:217] op_sel:[1,0,0]
	v_pk_fma_f32 v[218:219], v[62:63], v[234:235], v[218:219] op_sel:[1,0,0]
	v_cvt_pk_f32_fp8_e32 v[236:237], v129
	v_cvt_pk_f32_fp8_sdwa v[238:239], v129 src0_sel:WORD_1
	v_pk_fma_f32 v[220:221], v[62:63], v[236:237], v[220:221] op_sel:[1,0,0]
	v_pk_fma_f32 v[222:223], v[62:63], v[238:239], v[222:223] op_sel:[1,0,0]
	v_cvt_pk_f32_fp8_e32 v[232:233], v130
	v_cvt_pk_f32_fp8_sdwa v[234:235], v130 src0_sel:WORD_1
	v_pk_fma_f32 v[224:225], v[62:63], v[232:233], v[224:225] op_sel:[1,0,0]
	v_pk_fma_f32 v[226:227], v[62:63], v[234:235], v[226:227] op_sel:[1,0,0]
	v_cvt_pk_f32_fp8_e32 v[236:237], v131
	v_cvt_pk_f32_fp8_sdwa v[238:239], v131 src0_sel:WORD_1
	v_pk_fma_f32 v[228:229], v[62:63], v[236:237], v[228:229] op_sel:[1,0,0]
	v_pk_fma_f32 v[230:231], v[62:63], v[238:239], v[230:231] op_sel:[1,0,0]
	s_waitcnt vmcnt(19)
	v_cvt_pk_f32_fp8_e32 v[232:233], v132
	v_cvt_pk_f32_fp8_sdwa v[234:235], v132 src0_sel:WORD_1
	v_pk_fma_f32 v[216:217], v[64:65], v[232:233], v[216:217] op_sel_hi:[0,1,1]
	v_pk_fma_f32 v[218:219], v[64:65], v[234:235], v[218:219] op_sel_hi:[0,1,1]
	v_cvt_pk_f32_fp8_e32 v[236:237], v133
	v_cvt_pk_f32_fp8_sdwa v[238:239], v133 src0_sel:WORD_1
	v_pk_fma_f32 v[220:221], v[64:65], v[236:237], v[220:221] op_sel_hi:[0,1,1]
	v_pk_fma_f32 v[222:223], v[64:65], v[238:239], v[222:223] op_sel_hi:[0,1,1]
	v_cvt_pk_f32_fp8_e32 v[232:233], v134
	v_cvt_pk_f32_fp8_sdwa v[234:235], v134 src0_sel:WORD_1
	v_pk_fma_f32 v[224:225], v[64:65], v[232:233], v[224:225] op_sel_hi:[0,1,1]
	v_pk_fma_f32 v[226:227], v[64:65], v[234:235], v[226:227] op_sel_hi:[0,1,1]
	v_cvt_pk_f32_fp8_e32 v[236:237], v135
	v_cvt_pk_f32_fp8_sdwa v[238:239], v135 src0_sel:WORD_1
	v_pk_fma_f32 v[228:229], v[64:65], v[236:237], v[228:229] op_sel_hi:[0,1,1]
	v_pk_fma_f32 v[230:231], v[64:65], v[238:239], v[230:231] op_sel_hi:[0,1,1]
	s_waitcnt vmcnt(18)
	v_cvt_pk_f32_fp8_e32 v[232:233], v136
	v_cvt_pk_f32_fp8_sdwa v[234:235], v136 src0_sel:WORD_1
	v_pk_fma_f32 v[216:217], v[64:65], v[232:233], v[216:217] op_sel:[1,0,0]
	v_pk_fma_f32 v[218:219], v[64:65], v[234:235], v[218:219] op_sel:[1,0,0]
	v_cvt_pk_f32_fp8_e32 v[236:237], v137
	v_cvt_pk_f32_fp8_sdwa v[238:239], v137 src0_sel:WORD_1
	v_pk_fma_f32 v[220:221], v[64:65], v[236:237], v[220:221] op_sel:[1,0,0]
	v_pk_fma_f32 v[222:223], v[64:65], v[238:239], v[222:223] op_sel:[1,0,0]
	v_cvt_pk_f32_fp8_e32 v[232:233], v138
	v_cvt_pk_f32_fp8_sdwa v[234:235], v138 src0_sel:WORD_1
	v_pk_fma_f32 v[224:225], v[64:65], v[232:233], v[224:225] op_sel:[1,0,0]
	v_pk_fma_f32 v[226:227], v[64:65], v[234:235], v[226:227] op_sel:[1,0,0]
	v_cvt_pk_f32_fp8_e32 v[236:237], v139
	v_cvt_pk_f32_fp8_sdwa v[238:239], v139 src0_sel:WORD_1
	v_pk_fma_f32 v[228:229], v[64:65], v[236:237], v[228:229] op_sel:[1,0,0]
	v_pk_fma_f32 v[230:231], v[64:65], v[238:239], v[230:231] op_sel:[1,0,0]
	s_waitcnt vmcnt(17)
	v_cvt_pk_f32_fp8_e32 v[232:233], v140
	v_cvt_pk_f32_fp8_sdwa v[234:235], v140 src0_sel:WORD_1
	v_pk_fma_f32 v[216:217], v[66:67], v[232:233], v[216:217] op_sel_hi:[0,1,1]
	v_pk_fma_f32 v[218:219], v[66:67], v[234:235], v[218:219] op_sel_hi:[0,1,1]
	v_cvt_pk_f32_fp8_e32 v[236:237], v141
	v_cvt_pk_f32_fp8_sdwa v[238:239], v141 src0_sel:WORD_1
	v_pk_fma_f32 v[220:221], v[66:67], v[236:237], v[220:221] op_sel_hi:[0,1,1]
	v_pk_fma_f32 v[222:223], v[66:67], v[238:239], v[222:223] op_sel_hi:[0,1,1]
	v_cvt_pk_f32_fp8_e32 v[232:233], v142
	v_cvt_pk_f32_fp8_sdwa v[234:235], v142 src0_sel:WORD_1
	v_pk_fma_f32 v[224:225], v[66:67], v[232:233], v[224:225] op_sel_hi:[0,1,1]
	v_pk_fma_f32 v[226:227], v[66:67], v[234:235], v[226:227] op_sel_hi:[0,1,1]
	v_cvt_pk_f32_fp8_e32 v[236:237], v143
	v_cvt_pk_f32_fp8_sdwa v[238:239], v143 src0_sel:WORD_1
	v_pk_fma_f32 v[228:229], v[66:67], v[236:237], v[228:229] op_sel_hi:[0,1,1]
	v_pk_fma_f32 v[230:231], v[66:67], v[238:239], v[230:231] op_sel_hi:[0,1,1]
	s_waitcnt vmcnt(16)
; DI f2_t cvt8lo(unsigned w) { return __builtin_amdgcn_cvt_pk_f32_fp8(w, false); }
; DI f2_t cvt8hi(unsigned w) { return __builtin_amdgcn_cvt_pk_f32_fp8(w, true); }
; DI void wave_lds_sync() { asm volatile("s_waitcnt lgkmcnt(0)" ::: "memory"); __builtin_amdgcn_wave_barrier(); }
; DI void phase11(const Params& p, char* smem, int rep) {
;     ...
;       lw[(lane & 3) * 32 + (lane >> 2)] = i0; lw[(lane & 3) * 32 + 16 + (lane >> 2)] = i1;
;       lf[(lane & 3) * 32 + (lane >> 2)] = a0; lf[(lane & 3) * 32 + 16 + (lane >> 2)] = a1;
;       wave_lds_sync();
;       f2_t o[8];
; #pragma unroll
;       for (int i = 0; i < 8; ++i) o[i] = f2_t{0.f, 0.f};
;       const unsigned char* vb = V8 + s * 256 + l15 * 16;
; #pragma unroll
;       for (int batch = 0; batch < 2; ++batch) {
;         int ida[16]; float aa[16];
; #pragma unroll
;         for (int q = 0; q < 4; ++q) {
;           const int4 v = *(const int4*)(lw + g * 32 + batch * 16 + q * 4); ida[q * 4] = v.x; ida[q * 4 + 1] = v.y; ida[q * 4 + 2] = v.z; ida[q * 4 + 3] = v.w;
;           const float4 f = *(const float4*)(lf + g * 32 + batch * 16 + q * 4); aa[q * 4] = f.x; aa[q * 4 + 1] = f.y; aa[q * 4 + 2] = f.z; aa[q * 4 + 3] = f.w;
;         }
;         u32x4 rows[16];
; #pragma unroll
;         for (int k = 0; k < 16; ++k) rows[k] = *(const u32x4*)(vb + (size_t)ida[k] * 2048);
; #pragma unroll
;         for (int k = 0; k < 16; ++k) {
;           const f2_t a2 = {aa[k], aa[k]};
; #pragma unroll
;           for (int d = 0; d < 4; ++d) { const unsigned ww = rows[k][d]; o[2 * d] += a2 * cvt8lo(ww); o[2 * d + 1] += a2 * cvt8hi(ww); }
	v_cvt_pk_f32_fp8_e32 v[232:233], v144
	v_cvt_pk_f32_fp8_sdwa v[234:235], v144 src0_sel:WORD_1
	v_pk_fma_f32 v[216:217], v[66:67], v[232:233], v[216:217] op_sel:[1,0,0]
	v_pk_fma_f32 v[218:219], v[66:67], v[234:235], v[218:219] op_sel:[1,0,0]
	v_cvt_pk_f32_fp8_e32 v[236:237], v145
	v_cvt_pk_f32_fp8_sdwa v[238:239], v145 src0_sel:WORD_1
	v_pk_fma_f32 v[220:221], v[66:67], v[236:237], v[220:221] op_sel:[1,0,0]
	v_pk_fma_f32 v[222:223], v[66:67], v[238:239], v[222:223] op_sel:[1,0,0]
	v_cvt_pk_f32_fp8_e32 v[232:233], v146
	v_cvt_pk_f32_fp8_sdwa v[234:235], v146 src0_sel:WORD_1
	v_pk_fma_f32 v[224:225], v[66:67], v[232:233], v[224:225] op_sel:[1,0,0]
	v_pk_fma_f32 v[226:227], v[66:67], v[234:235], v[226:227] op_sel:[1,0,0]
	v_cvt_pk_f32_fp8_e32 v[236:237], v147
	v_cvt_pk_f32_fp8_sdwa v[238:239], v147 src0_sel:WORD_1
	v_pk_fma_f32 v[228:229], v[66:67], v[236:237], v[228:229] op_sel:[1,0,0]
	v_pk_fma_f32 v[230:231], v[66:67], v[238:239], v[230:231] op_sel:[1,0,0]
	ds_write2_b32 v5, v10, v11 offset0:4 offset1:20
	ds_write2_b32 v5, v12, v13 offset0:132 offset1:148
	s_waitcnt lgkmcnt(0)
	ds_read_b128 v[20:23], v6 offset:16
	ds_read_b128 v[24:27], v6 offset:32
	ds_read_b128 v[28:31], v6 offset:48
	ds_read_b128 v[32:35], v6 offset:64
	ds_read_b128 v[36:39], v6 offset:80
	ds_read_b128 v[40:43], v6 offset:96
	ds_read_b128 v[44:47], v6 offset:112
	ds_read_b128 v[48:51], v6 offset:128
	s_waitcnt vmcnt(15)
	v_cvt_pk_f32_fp8_e32 v[232:233], v148
	v_cvt_pk_f32_fp8_sdwa v[234:235], v148 src0_sel:WORD_1
	v_pk_fma_f32 v[216:217], v[68:69], v[232:233], v[216:217] op_sel_hi:[0,1,1]
	v_pk_fma_f32 v[218:219], v[68:69], v[234:235], v[218:219] op_sel_hi:[0,1,1]
	v_cvt_pk_f32_fp8_e32 v[236:237], v149
	v_cvt_pk_f32_fp8_sdwa v[238:239], v149 src0_sel:WORD_1
	v_pk_fma_f32 v[220:221], v[68:69], v[236:237], v[220:221] op_sel_hi:[0,1,1]
	v_pk_fma_f32 v[222:223], v[68:69], v[238:239], v[222:223] op_sel_hi:[0,1,1]
	v_cvt_pk_f32_fp8_e32 v[232:233], v150
	v_cvt_pk_f32_fp8_sdwa v[234:235], v150 src0_sel:WORD_1
	v_pk_fma_f32 v[224:225], v[68:69], v[232:233], v[224:225] op_sel_hi:[0,1,1]
	v_pk_fma_f32 v[226:227], v[68:69], v[234:235], v[226:227] op_sel_hi:[0,1,1]
	v_cvt_pk_f32_fp8_e32 v[236:237], v151
	v_cvt_pk_f32_fp8_sdwa v[238:239], v151 src0_sel:WORD_1
	v_pk_fma_f32 v[228:229], v[68:69], v[236:237], v[228:229] op_sel_hi:[0,1,1]
	v_pk_fma_f32 v[230:231], v[68:69], v[238:239], v[230:231] op_sel_hi:[0,1,1]
	s_waitcnt vmcnt(14)
	v_cvt_pk_f32_fp8_e32 v[232:233], v152
	v_cvt_pk_f32_fp8_sdwa v[234:235], v152 src0_sel:WORD_1
	v_pk_fma_f32 v[216:217], v[68:69], v[232:233], v[216:217] op_sel:[1,0,0]
	v_pk_fma_f32 v[218:219], v[68:69], v[234:235], v[218:219] op_sel:[1,0,0]
	v_cvt_pk_f32_fp8_e32 v[236:237], v153
	v_cvt_pk_f32_fp8_sdwa v[238:239], v153 src0_sel:WORD_1
	v_pk_fma_f32 v[220:221], v[68:69], v[236:237], v[220:221] op_sel:[1,0,0]
	v_pk_fma_f32 v[222:223], v[68:69], v[238:239], v[222:223] op_sel:[1,0,0]
	v_cvt_pk_f32_fp8_e32 v[232:233], v154
	v_cvt_pk_f32_fp8_sdwa v[234:235], v154 src0_sel:WORD_1
	v_pk_fma_f32 v[224:225], v[68:69], v[232:233], v[224:225] op_sel:[1,0,0]
	v_pk_fma_f32 v[226:227], v[68:69], v[234:235], v[226:227] op_sel:[1,0,0]
	v_cvt_pk_f32_fp8_e32 v[236:237], v155
	v_cvt_pk_f32_fp8_sdwa v[238:239], v155 src0_sel:WORD_1
	v_pk_fma_f32 v[228:229], v[68:69], v[236:237], v[228:229] op_sel:[1,0,0]
	v_pk_fma_f32 v[230:231], v[68:69], v[238:239], v[230:231] op_sel:[1,0,0]
	s_waitcnt vmcnt(13)
	v_cvt_pk_f32_fp8_e32 v[232:233], v156
	v_cvt_pk_f32_fp8_sdwa v[234:235], v156 src0_sel:WORD_1
	v_pk_fma_f32 v[216:217], v[70:71], v[232:233], v[216:217] op_sel_hi:[0,1,1]
	v_pk_fma_f32 v[218:219], v[70:71], v[234:235], v[218:219] op_sel_hi:[0,1,1]
	v_cvt_pk_f32_fp8_e32 v[236:237], v157
	v_cvt_pk_f32_fp8_sdwa v[238:239], v157 src0_sel:WORD_1
	v_pk_fma_f32 v[220:221], v[70:71], v[236:237], v[220:221] op_sel_hi:[0,1,1]
	v_pk_fma_f32 v[222:223], v[70:71], v[238:239], v[222:223] op_sel_hi:[0,1,1]
	v_cvt_pk_f32_fp8_e32 v[232:233], v158
	v_cvt_pk_f32_fp8_sdwa v[234:235], v158 src0_sel:WORD_1
	v_pk_fma_f32 v[224:225], v[70:71], v[232:233], v[224:225] op_sel_hi:[0,1,1]
	v_pk_fma_f32 v[226:227], v[70:71], v[234:235], v[226:227] op_sel_hi:[0,1,1]
	v_cvt_pk_f32_fp8_e32 v[236:237], v159
	v_cvt_pk_f32_fp8_sdwa v[238:239], v159 src0_sel:WORD_1
	v_pk_fma_f32 v[228:229], v[70:71], v[236:237], v[228:229] op_sel_hi:[0,1,1]
	v_pk_fma_f32 v[230:231], v[70:71], v[238:239], v[230:231] op_sel_hi:[0,1,1]
	s_waitcnt vmcnt(12)
	v_cvt_pk_f32_fp8_e32 v[232:233], v160
	v_cvt_pk_f32_fp8_sdwa v[234:235], v160 src0_sel:WORD_1
	v_pk_fma_f32 v[216:217], v[70:71], v[232:233], v[216:217] op_sel:[1,0,0]
	v_pk_fma_f32 v[218:219], v[70:71], v[234:235], v[218:219] op_sel:[1,0,0]
	v_cvt_pk_f32_fp8_e32 v[236:237], v161
	v_cvt_pk_f32_fp8_sdwa v[238:239], v161 src0_sel:WORD_1
	v_pk_fma_f32 v[220:221], v[70:71], v[236:237], v[220:221] op_sel:[1,0,0]
	v_pk_fma_f32 v[222:223], v[70:71], v[238:239], v[222:223] op_sel:[1,0,0]
	v_cvt_pk_f32_fp8_e32 v[232:233], v162
	v_cvt_pk_f32_fp8_sdwa v[234:235], v162 src0_sel:WORD_1
	v_pk_fma_f32 v[224:225], v[70:71], v[232:233], v[224:225] op_sel:[1,0,0]
	v_pk_fma_f32 v[226:227], v[70:71], v[234:235], v[226:227] op_sel:[1,0,0]
	v_cvt_pk_f32_fp8_e32 v[236:237], v163
	v_cvt_pk_f32_fp8_sdwa v[238:239], v163 src0_sel:WORD_1
	v_pk_fma_f32 v[228:229], v[70:71], v[236:237], v[228:229] op_sel:[1,0,0]
	v_pk_fma_f32 v[230:231], v[70:71], v[238:239], v[230:231] op_sel:[1,0,0]
	s_waitcnt vmcnt(11)
; DI f2_t cvt8lo(unsigned w) { return __builtin_amdgcn_cvt_pk_f32_fp8(w, false); }
; DI f2_t cvt8hi(unsigned w) { return __builtin_amdgcn_cvt_pk_f32_fp8(w, true); }
; DI void phase11(const Params& p, char* smem, int rep) {
;     ...
;         for (int k = 0; k < 16; ++k) {
;           const f2_t a2 = {aa[k], aa[k]};
; #pragma unroll
;           for (int d = 0; d < 4; ++d) { const unsigned ww = rows[k][d]; o[2 * d] += a2 * cvt8lo(ww); o[2 * d + 1] += a2 * cvt8hi(ww); }
;         }
	v_cvt_pk_f32_fp8_e32 v[232:233], v164
	v_cvt_pk_f32_fp8_sdwa v[234:235], v164 src0_sel:WORD_1
	v_pk_fma_f32 v[216:217], v[72:73], v[232:233], v[216:217] op_sel_hi:[0,1,1]
	v_pk_fma_f32 v[218:219], v[72:73], v[234:235], v[218:219] op_sel_hi:[0,1,1]
	v_cvt_pk_f32_fp8_e32 v[236:237], v165
	v_cvt_pk_f32_fp8_sdwa v[238:239], v165 src0_sel:WORD_1
	v_pk_fma_f32 v[220:221], v[72:73], v[236:237], v[220:221] op_sel_hi:[0,1,1]
	v_pk_fma_f32 v[222:223], v[72:73], v[238:239], v[222:223] op_sel_hi:[0,1,1]
	v_cvt_pk_f32_fp8_e32 v[232:233], v166
	v_cvt_pk_f32_fp8_sdwa v[234:235], v166 src0_sel:WORD_1
	v_pk_fma_f32 v[224:225], v[72:73], v[232:233], v[224:225] op_sel_hi:[0,1,1]
	v_pk_fma_f32 v[226:227], v[72:73], v[234:235], v[226:227] op_sel_hi:[0,1,1]
	v_cvt_pk_f32_fp8_e32 v[236:237], v167
	v_cvt_pk_f32_fp8_sdwa v[238:239], v167 src0_sel:WORD_1
	v_pk_fma_f32 v[228:229], v[72:73], v[236:237], v[228:229] op_sel_hi:[0,1,1]
	v_pk_fma_f32 v[230:231], v[72:73], v[238:239], v[230:231] op_sel_hi:[0,1,1]
	s_waitcnt vmcnt(10)
	v_cvt_pk_f32_fp8_e32 v[232:233], v168
	v_cvt_pk_f32_fp8_sdwa v[234:235], v168 src0_sel:WORD_1
	v_pk_fma_f32 v[216:217], v[72:73], v[232:233], v[216:217] op_sel:[1,0,0]
	v_pk_fma_f32 v[218:219], v[72:73], v[234:235], v[218:219] op_sel:[1,0,0]
	v_cvt_pk_f32_fp8_e32 v[236:237], v169
	v_cvt_pk_f32_fp8_sdwa v[238:239], v169 src0_sel:WORD_1
	v_pk_fma_f32 v[220:221], v[72:73], v[236:237], v[220:221] op_sel:[1,0,0]
	v_pk_fma_f32 v[222:223], v[72:73], v[238:239], v[222:223] op_sel:[1,0,0]
	v_cvt_pk_f32_fp8_e32 v[232:233], v170
	v_cvt_pk_f32_fp8_sdwa v[234:235], v170 src0_sel:WORD_1
	v_pk_fma_f32 v[224:225], v[72:73], v[232:233], v[224:225] op_sel:[1,0,0]
	v_pk_fma_f32 v[226:227], v[72:73], v[234:235], v[226:227] op_sel:[1,0,0]
	v_cvt_pk_f32_fp8_e32 v[236:237], v171
	v_cvt_pk_f32_fp8_sdwa v[238:239], v171 src0_sel:WORD_1
	v_pk_fma_f32 v[228:229], v[72:73], v[236:237], v[228:229] op_sel:[1,0,0]
	v_pk_fma_f32 v[230:231], v[72:73], v[238:239], v[230:231] op_sel:[1,0,0]
	s_waitcnt vmcnt(9)
	v_cvt_pk_f32_fp8_e32 v[232:233], v172
	v_cvt_pk_f32_fp8_sdwa v[234:235], v172 src0_sel:WORD_1
	v_pk_fma_f32 v[216:217], v[74:75], v[232:233], v[216:217] op_sel_hi:[0,1,1]
	v_pk_fma_f32 v[218:219], v[74:75], v[234:235], v[218:219] op_sel_hi:[0,1,1]
	v_cvt_pk_f32_fp8_e32 v[236:237], v173
	v_cvt_pk_f32_fp8_sdwa v[238:239], v173 src0_sel:WORD_1
	v_pk_fma_f32 v[220:221], v[74:75], v[236:237], v[220:221] op_sel_hi:[0,1,1]
	v_pk_fma_f32 v[222:223], v[74:75], v[238:239], v[222:223] op_sel_hi:[0,1,1]
	v_cvt_pk_f32_fp8_e32 v[232:233], v174
	v_cvt_pk_f32_fp8_sdwa v[234:235], v174 src0_sel:WORD_1
	v_pk_fma_f32 v[224:225], v[74:75], v[232:233], v[224:225] op_sel_hi:[0,1,1]
	v_pk_fma_f32 v[226:227], v[74:75], v[234:235], v[226:227] op_sel_hi:[0,1,1]
	v_cvt_pk_f32_fp8_e32 v[236:237], v175
	v_cvt_pk_f32_fp8_sdwa v[238:239], v175 src0_sel:WORD_1
	v_pk_fma_f32 v[228:229], v[74:75], v[236:237], v[228:229] op_sel_hi:[0,1,1]
	v_pk_fma_f32 v[230:231], v[74:75], v[238:239], v[230:231] op_sel_hi:[0,1,1]
	s_waitcnt vmcnt(8)
	v_cvt_pk_f32_fp8_e32 v[232:233], v176
	v_cvt_pk_f32_fp8_sdwa v[234:235], v176 src0_sel:WORD_1
	v_pk_fma_f32 v[216:217], v[74:75], v[232:233], v[216:217] op_sel:[1,0,0]
	v_pk_fma_f32 v[218:219], v[74:75], v[234:235], v[218:219] op_sel:[1,0,0]
	v_cvt_pk_f32_fp8_e32 v[236:237], v177
	v_cvt_pk_f32_fp8_sdwa v[238:239], v177 src0_sel:WORD_1
	v_pk_fma_f32 v[220:221], v[74:75], v[236:237], v[220:221] op_sel:[1,0,0]
	v_pk_fma_f32 v[222:223], v[74:75], v[238:239], v[222:223] op_sel:[1,0,0]
	v_cvt_pk_f32_fp8_e32 v[232:233], v178
	v_cvt_pk_f32_fp8_sdwa v[234:235], v178 src0_sel:WORD_1
	v_pk_fma_f32 v[224:225], v[74:75], v[232:233], v[224:225] op_sel:[1,0,0]
	v_pk_fma_f32 v[226:227], v[74:75], v[234:235], v[226:227] op_sel:[1,0,0]
	v_cvt_pk_f32_fp8_e32 v[236:237], v179
	v_cvt_pk_f32_fp8_sdwa v[238:239], v179 src0_sel:WORD_1
	v_pk_fma_f32 v[228:229], v[74:75], v[236:237], v[228:229] op_sel:[1,0,0]
	v_pk_fma_f32 v[230:231], v[74:75], v[238:239], v[230:231] op_sel:[1,0,0]
	s_waitcnt vmcnt(7)
	v_cvt_pk_f32_fp8_e32 v[232:233], v180
	v_cvt_pk_f32_fp8_sdwa v[234:235], v180 src0_sel:WORD_1
	v_pk_fma_f32 v[216:217], v[76:77], v[232:233], v[216:217] op_sel_hi:[0,1,1]
	v_pk_fma_f32 v[218:219], v[76:77], v[234:235], v[218:219] op_sel_hi:[0,1,1]
	v_cvt_pk_f32_fp8_e32 v[236:237], v181
	v_cvt_pk_f32_fp8_sdwa v[238:239], v181 src0_sel:WORD_1
	v_pk_fma_f32 v[220:221], v[76:77], v[236:237], v[220:221] op_sel_hi:[0,1,1]
	v_pk_fma_f32 v[222:223], v[76:77], v[238:239], v[222:223] op_sel_hi:[0,1,1]
	v_cvt_pk_f32_fp8_e32 v[232:233], v182
	v_cvt_pk_f32_fp8_sdwa v[234:235], v182 src0_sel:WORD_1
	v_pk_fma_f32 v[224:225], v[76:77], v[232:233], v[224:225] op_sel_hi:[0,1,1]
	v_pk_fma_f32 v[226:227], v[76:77], v[234:235], v[226:227] op_sel_hi:[0,1,1]
	v_cvt_pk_f32_fp8_e32 v[236:237], v183
	v_cvt_pk_f32_fp8_sdwa v[238:239], v183 src0_sel:WORD_1
	v_pk_fma_f32 v[228:229], v[76:77], v[236:237], v[228:229] op_sel_hi:[0,1,1]
	v_pk_fma_f32 v[230:231], v[76:77], v[238:239], v[230:231] op_sel_hi:[0,1,1]
	s_waitcnt vmcnt(6)
	v_cvt_pk_f32_fp8_e32 v[232:233], v184
	v_cvt_pk_f32_fp8_sdwa v[234:235], v184 src0_sel:WORD_1
	v_pk_fma_f32 v[216:217], v[76:77], v[232:233], v[216:217] op_sel:[1,0,0]
	v_pk_fma_f32 v[218:219], v[76:77], v[234:235], v[218:219] op_sel:[1,0,0]
	v_cvt_pk_f32_fp8_e32 v[236:237], v185
	v_cvt_pk_f32_fp8_sdwa v[238:239], v185 src0_sel:WORD_1
	v_pk_fma_f32 v[220:221], v[76:77], v[236:237], v[220:221] op_sel:[1,0,0]
	v_pk_fma_f32 v[222:223], v[76:77], v[238:239], v[222:223] op_sel:[1,0,0]
	v_cvt_pk_f32_fp8_e32 v[232:233], v186
	v_cvt_pk_f32_fp8_sdwa v[234:235], v186 src0_sel:WORD_1
	v_pk_fma_f32 v[224:225], v[76:77], v[232:233], v[224:225] op_sel:[1,0,0]
	v_pk_fma_f32 v[226:227], v[76:77], v[234:235], v[226:227] op_sel:[1,0,0]
	v_cvt_pk_f32_fp8_e32 v[236:237], v187
	v_cvt_pk_f32_fp8_sdwa v[238:239], v187 src0_sel:WORD_1
	v_pk_fma_f32 v[228:229], v[76:77], v[236:237], v[228:229] op_sel:[1,0,0]
	v_pk_fma_f32 v[230:231], v[76:77], v[238:239], v[230:231] op_sel:[1,0,0]
	s_waitcnt vmcnt(5)
; DI f2_t cvt8lo(unsigned w) { return __builtin_amdgcn_cvt_pk_f32_fp8(w, false); }
; DI f2_t cvt8hi(unsigned w) { return __builtin_amdgcn_cvt_pk_f32_fp8(w, true); }
; DI void phase11(const Params& p, char* smem, int rep) {
;     ...
;         for (int k = 0; k < 16; ++k) {
;           const f2_t a2 = {aa[k], aa[k]};
; #pragma unroll
;           for (int d = 0; d < 4; ++d) { const unsigned ww = rows[k][d]; o[2 * d] += a2 * cvt8lo(ww); o[2 * d + 1] += a2 * cvt8hi(ww); }
;         }
	v_cvt_pk_f32_fp8_e32 v[232:233], v190
	v_cvt_pk_f32_fp8_sdwa v[234:235], v190 src0_sel:WORD_1
	v_pk_fma_f32 v[216:217], v[78:79], v[232:233], v[216:217] op_sel_hi:[0,1,1]
	v_pk_fma_f32 v[218:219], v[78:79], v[234:235], v[218:219] op_sel_hi:[0,1,1]
	v_cvt_pk_f32_fp8_e32 v[236:237], v191
	v_cvt_pk_f32_fp8_sdwa v[238:239], v191 src0_sel:WORD_1
	v_pk_fma_f32 v[220:221], v[78:79], v[236:237], v[220:221] op_sel_hi:[0,1,1]
	v_pk_fma_f32 v[222:223], v[78:79], v[238:239], v[222:223] op_sel_hi:[0,1,1]
	v_cvt_pk_f32_fp8_e32 v[232:233], v192
	v_cvt_pk_f32_fp8_sdwa v[234:235], v192 src0_sel:WORD_1
	v_pk_fma_f32 v[224:225], v[78:79], v[232:233], v[224:225] op_sel_hi:[0,1,1]
	v_pk_fma_f32 v[226:227], v[78:79], v[234:235], v[226:227] op_sel_hi:[0,1,1]
	v_cvt_pk_f32_fp8_e32 v[236:237], v193
	v_cvt_pk_f32_fp8_sdwa v[238:239], v193 src0_sel:WORD_1
	v_pk_fma_f32 v[228:229], v[78:79], v[236:237], v[228:229] op_sel_hi:[0,1,1]
	v_pk_fma_f32 v[230:231], v[78:79], v[238:239], v[230:231] op_sel_hi:[0,1,1]
	s_waitcnt vmcnt(4)
	v_cvt_pk_f32_fp8_e32 v[232:233], v194
	v_cvt_pk_f32_fp8_sdwa v[234:235], v194 src0_sel:WORD_1
	v_pk_fma_f32 v[216:217], v[78:79], v[232:233], v[216:217] op_sel:[1,0,0]
	v_pk_fma_f32 v[218:219], v[78:79], v[234:235], v[218:219] op_sel:[1,0,0]
	v_cvt_pk_f32_fp8_e32 v[236:237], v195
	v_cvt_pk_f32_fp8_sdwa v[238:239], v195 src0_sel:WORD_1
	v_pk_fma_f32 v[220:221], v[78:79], v[236:237], v[220:221] op_sel:[1,0,0]
	v_pk_fma_f32 v[222:223], v[78:79], v[238:239], v[222:223] op_sel:[1,0,0]
	v_cvt_pk_f32_fp8_e32 v[232:233], v196
	v_cvt_pk_f32_fp8_sdwa v[234:235], v196 src0_sel:WORD_1
	v_pk_fma_f32 v[224:225], v[78:79], v[232:233], v[224:225] op_sel:[1,0,0]
	v_pk_fma_f32 v[226:227], v[78:79], v[234:235], v[226:227] op_sel:[1,0,0]
	v_cvt_pk_f32_fp8_e32 v[236:237], v197
	v_cvt_pk_f32_fp8_sdwa v[238:239], v197 src0_sel:WORD_1
	v_pk_fma_f32 v[228:229], v[78:79], v[236:237], v[228:229] op_sel:[1,0,0]
	v_pk_fma_f32 v[230:231], v[78:79], v[238:239], v[230:231] op_sel:[1,0,0]
	s_waitcnt vmcnt(3)
	v_cvt_pk_f32_fp8_e32 v[232:233], v198
	v_cvt_pk_f32_fp8_sdwa v[234:235], v198 src0_sel:WORD_1
	v_pk_fma_f32 v[216:217], v[80:81], v[232:233], v[216:217] op_sel_hi:[0,1,1]
	v_pk_fma_f32 v[218:219], v[80:81], v[234:235], v[218:219] op_sel_hi:[0,1,1]
	v_cvt_pk_f32_fp8_e32 v[236:237], v199
	v_cvt_pk_f32_fp8_sdwa v[238:239], v199 src0_sel:WORD_1
	v_pk_fma_f32 v[220:221], v[80:81], v[236:237], v[220:221] op_sel_hi:[0,1,1]
	v_pk_fma_f32 v[222:223], v[80:81], v[238:239], v[222:223] op_sel_hi:[0,1,1]
	v_cvt_pk_f32_fp8_e32 v[232:233], v200
	v_cvt_pk_f32_fp8_sdwa v[234:235], v200 src0_sel:WORD_1
	v_pk_fma_f32 v[224:225], v[80:81], v[232:233], v[224:225] op_sel_hi:[0,1,1]
	v_pk_fma_f32 v[226:227], v[80:81], v[234:235], v[226:227] op_sel_hi:[0,1,1]
	v_cvt_pk_f32_fp8_e32 v[236:237], v201
	v_cvt_pk_f32_fp8_sdwa v[238:239], v201 src0_sel:WORD_1
	v_pk_fma_f32 v[228:229], v[80:81], v[236:237], v[228:229] op_sel_hi:[0,1,1]
	v_pk_fma_f32 v[230:231], v[80:81], v[238:239], v[230:231] op_sel_hi:[0,1,1]
	s_waitcnt vmcnt(2)
	v_cvt_pk_f32_fp8_e32 v[232:233], v202
	v_cvt_pk_f32_fp8_sdwa v[234:235], v202 src0_sel:WORD_1
	v_pk_fma_f32 v[216:217], v[80:81], v[232:233], v[216:217] op_sel:[1,0,0]
	v_pk_fma_f32 v[218:219], v[80:81], v[234:235], v[218:219] op_sel:[1,0,0]
	v_cvt_pk_f32_fp8_e32 v[236:237], v203
	v_cvt_pk_f32_fp8_sdwa v[238:239], v203 src0_sel:WORD_1
	v_pk_fma_f32 v[220:221], v[80:81], v[236:237], v[220:221] op_sel:[1,0,0]
	v_pk_fma_f32 v[222:223], v[80:81], v[238:239], v[222:223] op_sel:[1,0,0]
	v_cvt_pk_f32_fp8_e32 v[232:233], v204
	v_cvt_pk_f32_fp8_sdwa v[234:235], v204 src0_sel:WORD_1
	v_pk_fma_f32 v[224:225], v[80:81], v[232:233], v[224:225] op_sel:[1,0,0]
	v_pk_fma_f32 v[226:227], v[80:81], v[234:235], v[226:227] op_sel:[1,0,0]
	v_cvt_pk_f32_fp8_e32 v[236:237], v205
	v_cvt_pk_f32_fp8_sdwa v[238:239], v205 src0_sel:WORD_1
	v_pk_fma_f32 v[228:229], v[80:81], v[236:237], v[228:229] op_sel:[1,0,0]
	v_pk_fma_f32 v[230:231], v[80:81], v[238:239], v[230:231] op_sel:[1,0,0]
	s_waitcnt vmcnt(1)
	v_cvt_pk_f32_fp8_e32 v[232:233], v206
	v_cvt_pk_f32_fp8_sdwa v[234:235], v206 src0_sel:WORD_1
	v_pk_fma_f32 v[216:217], v[82:83], v[232:233], v[216:217] op_sel_hi:[0,1,1]
	v_pk_fma_f32 v[218:219], v[82:83], v[234:235], v[218:219] op_sel_hi:[0,1,1]
	v_cvt_pk_f32_fp8_e32 v[236:237], v207
	v_cvt_pk_f32_fp8_sdwa v[238:239], v207 src0_sel:WORD_1
	v_pk_fma_f32 v[220:221], v[82:83], v[236:237], v[220:221] op_sel_hi:[0,1,1]
	v_pk_fma_f32 v[222:223], v[82:83], v[238:239], v[222:223] op_sel_hi:[0,1,1]
	v_cvt_pk_f32_fp8_e32 v[232:233], v208
	v_cvt_pk_f32_fp8_sdwa v[234:235], v208 src0_sel:WORD_1
	v_pk_fma_f32 v[224:225], v[82:83], v[232:233], v[224:225] op_sel_hi:[0,1,1]
	v_pk_fma_f32 v[226:227], v[82:83], v[234:235], v[226:227] op_sel_hi:[0,1,1]
	v_cvt_pk_f32_fp8_e32 v[236:237], v209
	v_cvt_pk_f32_fp8_sdwa v[238:239], v209 src0_sel:WORD_1
	v_pk_fma_f32 v[228:229], v[82:83], v[236:237], v[228:229] op_sel_hi:[0,1,1]
	v_pk_fma_f32 v[230:231], v[82:83], v[238:239], v[230:231] op_sel_hi:[0,1,1]
	s_waitcnt vmcnt(0)
; DI unsigned pk2(float a, float b) { f2_t v = {a, b}; bf2_t r = __builtin_convertvector(v, bf2_t); return __builtin_bit_cast(unsigned, r); }
; DI void phase11(const Params& p, char* smem, int rep) {
;     ...
;       const int tok = __builtin_amdgcn_readfirstlane(c * 16 + w * 4 + t);
;       const int i0 = IDS[(size_t)tok * 128 + lane], i1 = IDS[(size_t)tok * 128 + 64 + lane];
;       const float a0 = ACT[(size_t)tok * 128 + lane], a1 = ACT[(size_t)tok * 128 + 64 + lane];
;       wave_lds_sync();
;       lw[(lane & 3) * 32 + (lane >> 2)] = i0; lw[(lane & 3) * 32 + 16 + (lane >> 2)] = i1;
;       lf[(lane & 3) * 32 + (lane >> 2)] = a0; lf[(lane & 3) * 32 + 16 + (lane >> 2)] = a1;
;       wave_lds_sync();
;       f2_t o[8];
; #pragma unroll
;       for (int i = 0; i < 8; ++i) o[i] = f2_t{0.f, 0.f};
;       const unsigned char* vb = V8 + s * 256 + l15 * 16;
; #pragma unroll
;       for (int batch = 0; batch < 2; ++batch) {
;         int ida[16]; float aa[16];
; #pragma unroll
;         for (int q = 0; q < 4; ++q) {
;           const int4 v = *(const int4*)(lw + g * 32 + batch * 16 + q * 4); ida[q * 4] = v.x; ida[q * 4 + 1] = v.y; ida[q * 4 + 2] = v.z; ida[q * 4 + 3] = v.w;
;           const float4 f = *(const float4*)(lf + g * 32 + batch * 16 + q * 4); aa[q * 4] = f.x; aa[q * 4 + 1] = f.y; aa[q * 4 + 2] = f.z; aa[q * 4 + 3] = f.w;
;         }
;         u32x4 rows[16];
; #pragma unroll
;         for (int k = 0; k < 16; ++k) rows[k] = *(const u32x4*)(vb + (size_t)ida[k] * 2048);
; #pragma unroll
;         for (int k = 0; k < 16; ++k) {
;           const f2_t a2 = {aa[k], aa[k]};
; #pragma unroll
;           for (int d = 0; d < 4; ++d) { const unsigned ww = rows[k][d]; o[2 * d] += a2 * cvt8lo(ww); o[2 * d + 1] += a2 * cvt8hi(ww); }
;         }
;       }
;       float ov[16];
; #pragma unroll
;       for (int d = 0; d < 4; ++d) { ov[4 * d] = o[2 * d].x; ov[4 * d + 1] = o[2 * d].y; ov[4 * d + 2] = o[2 * d + 1].x; ov[4 * d + 3] = o[2 * d + 1].y; }
;       float q8[8], q4[4];
; #pragma unroll
;       for (int k = 0; k < 8; ++k) q8[k] = (b5 ? ov[8 + k] : ov[k]) + __shfl_xor(b5 ? ov[k] : ov[8 + k], 32);
; #pragma unroll
;       for (int k = 0; k < 4; ++k) q4[k] = (b4 ? q8[4 + k] : q8[k]) + __shfl_xor(b4 ? q8[k] : q8[4 + k], 16);
;       *(uint2*)(OUTP + (size_t)tok * D_ + s * 256 + l15 * 16 + 8 * b5 + 4 * b4) = make_uint2(pk2(q4[0], q4[1]), pk2(q4[2], q4[3]));
	v_cvt_pk_f32_fp8_e32 v[232:233], v210
	v_cvt_pk_f32_fp8_sdwa v[234:235], v210 src0_sel:WORD_1
	v_pk_fma_f32 v[216:217], v[82:83], v[232:233], v[216:217] op_sel:[1,0,0]
	v_pk_fma_f32 v[218:219], v[82:83], v[234:235], v[218:219] op_sel:[1,0,0]
	v_cvt_pk_f32_fp8_e32 v[236:237], v211
	v_cvt_pk_f32_fp8_sdwa v[238:239], v211 src0_sel:WORD_1
	v_pk_fma_f32 v[220:221], v[82:83], v[236:237], v[220:221] op_sel:[1,0,0]
	v_pk_fma_f32 v[222:223], v[82:83], v[238:239], v[222:223] op_sel:[1,0,0]
	v_cvt_pk_f32_fp8_e32 v[232:233], v212
	v_cvt_pk_f32_fp8_sdwa v[234:235], v212 src0_sel:WORD_1
	v_pk_fma_f32 v[224:225], v[82:83], v[232:233], v[224:225] op_sel:[1,0,0]
	v_pk_fma_f32 v[226:227], v[82:83], v[234:235], v[226:227] op_sel:[1,0,0]
	v_cvt_pk_f32_fp8_e32 v[236:237], v213
	v_cvt_pk_f32_fp8_sdwa v[238:239], v213 src0_sel:WORD_1
	v_pk_fma_f32 v[228:229], v[82:83], v[236:237], v[228:229] op_sel:[1,0,0]
	v_pk_fma_f32 v[230:231], v[82:83], v[238:239], v[230:231] op_sel:[1,0,0]
	ds_read_b128 v[52:55], v6 offset:528
	ds_read_b128 v[56:59], v6 offset:544
	ds_read_b128 v[60:63], v6 offset:560
	ds_read_b128 v[64:67], v6 offset:576
	ds_read_b128 v[68:71], v6 offset:592
	ds_read_b128 v[72:75], v6 offset:608
	ds_read_b128 v[76:79], v6 offset:624
	ds_read_b128 v[80:83], v6 offset:640
	v_add_u32_e32 v214, s46, v4
	s_nop 0
	v_permlane32_swap_b32_e32 v216, v224
	v_permlane32_swap_b32_e32 v217, v225
	v_permlane32_swap_b32_e32 v218, v226
	v_permlane32_swap_b32_e32 v219, v227
	v_permlane32_swap_b32_e32 v220, v228
	v_permlane32_swap_b32_e32 v221, v229
	v_permlane32_swap_b32_e32 v222, v230
	v_permlane32_swap_b32_e32 v223, v231
	v_add_f32_e32 v216, v216, v224
	v_add_f32_e32 v217, v217, v225
	v_add_f32_e32 v218, v218, v226
	v_add_f32_e32 v219, v219, v227
	v_add_f32_e32 v220, v220, v228
	v_add_f32_e32 v221, v221, v229
	v_add_f32_e32 v222, v222, v230
	v_add_f32_e32 v223, v223, v231
	s_nop 1
	v_permlane16_swap_b32_e32 v216, v220
	v_permlane16_swap_b32_e32 v217, v221
	v_permlane16_swap_b32_e32 v218, v222
	v_permlane16_swap_b32_e32 v219, v223
	v_add_f32_e32 v216, v216, v220
	v_add_f32_e32 v217, v217, v221
	v_add_f32_e32 v218, v218, v222
	v_add_f32_e32 v219, v219, v223
	v_cvt_pk_bf16_f32 v232, v216, v217
	v_cvt_pk_bf16_f32 v233, v218, v219
	global_store_dwordx2 v214, v[232:233], s[14:15] nt
	s_add_i32 s54, s34, 1
	s_lshl_b32 s46, s54, 12
	s_add_i32 s46, s46, s24
	s_add_i32 s55, s34, 2
	s_lshl_b32 s47, s55, 9
	s_add_u32 s42, s6, s47
	s_addc_u32 s43, s7, 0
	s_add_u32 s44, s8, s47
	s_addc_u32 s45, s9, 0
	global_load_dword v10, v3, s[42:43]
	global_load_dword v11, v3, s[42:43] offset:256
	global_load_dword v12, v3, s[44:45]
	global_load_dword v13, v3, s[44:45] offset:256
	s_waitcnt lgkmcnt(0)
	v_lshl_add_u32 v20, v20, 11, v2
	v_lshl_add_u32 v21, v21, 11, v2
	v_lshl_add_u32 v22, v22, 11, v2
	v_lshl_add_u32 v23, v23, 11, v2
	v_lshl_add_u32 v24, v24, 11, v2
	v_lshl_add_u32 v25, v25, 11, v2
	v_lshl_add_u32 v26, v26, 11, v2
	v_lshl_add_u32 v27, v27, 11, v2
	v_lshl_add_u32 v28, v28, 11, v2
	v_lshl_add_u32 v29, v29, 11, v2
	v_lshl_add_u32 v30, v30, 11, v2
	v_lshl_add_u32 v31, v31, 11, v2
	v_lshl_add_u32 v32, v32, 11, v2
	v_lshl_add_u32 v33, v33, 11, v2
	v_lshl_add_u32 v34, v34, 11, v2
	v_lshl_add_u32 v35, v35, 11, v2
	v_lshl_add_u32 v36, v36, 11, v2
	v_lshl_add_u32 v37, v37, 11, v2
	v_lshl_add_u32 v38, v38, 11, v2
	v_lshl_add_u32 v39, v39, 11, v2
	v_lshl_add_u32 v40, v40, 11, v2
	v_lshl_add_u32 v41, v41, 11, v2
	v_lshl_add_u32 v42, v42, 11, v2
	v_lshl_add_u32 v43, v43, 11, v2
	v_lshl_add_u32 v44, v44, 11, v2
	v_lshl_add_u32 v45, v45, 11, v2
	v_lshl_add_u32 v46, v46, 11, v2
	v_lshl_add_u32 v47, v47, 11, v2
	v_lshl_add_u32 v48, v48, 11, v2
	v_lshl_add_u32 v49, v49, 11, v2
	v_lshl_add_u32 v50, v50, 11, v2
	v_lshl_add_u32 v51, v51, 11, v2
	global_load_dwordx4 v[84:87], v20, s[20:21]
	global_load_dwordx4 v[88:91], v21, s[20:21]
	global_load_dwordx4 v[92:95], v22, s[20:21]
	global_load_dwordx4 v[96:99], v23, s[20:21]
	global_load_dwordx4 v[100:103], v24, s[20:21]
	global_load_dwordx4 v[104:107], v25, s[20:21]
	global_load_dwordx4 v[108:111], v26, s[20:21]
	global_load_dwordx4 v[112:115], v27, s[20:21]
	global_load_dwordx4 v[116:119], v28, s[20:21]
	global_load_dwordx4 v[120:123], v29, s[20:21]
	global_load_dwordx4 v[124:127], v30, s[20:21]
	global_load_dwordx4 v[128:131], v31, s[20:21]
	global_load_dwordx4 v[132:135], v32, s[20:21]
	global_load_dwordx4 v[136:139], v33, s[20:21]
	global_load_dwordx4 v[140:143], v34, s[20:21]
	global_load_dwordx4 v[144:147], v35, s[20:21]
	global_load_dwordx4 v[148:151], v36, s[20:21]
	global_load_dwordx4 v[152:155], v37, s[20:21]
	global_load_dwordx4 v[156:159], v38, s[20:21]
	global_load_dwordx4 v[160:163], v39, s[20:21]
	global_load_dwordx4 v[164:167], v40, s[20:21]
	global_load_dwordx4 v[168:171], v41, s[20:21]
	global_load_dwordx4 v[172:175], v42, s[20:21]
	global_load_dwordx4 v[176:179], v43, s[20:21]
	global_load_dwordx4 v[180:183], v44, s[20:21]
	global_load_dwordx4 v[184:187], v45, s[20:21]
	global_load_dwordx4 v[190:193], v46, s[20:21]
	global_load_dwordx4 v[194:197], v47, s[20:21]
	global_load_dwordx4 v[198:201], v48, s[20:21]
	global_load_dwordx4 v[202:205], v49, s[20:21]
	global_load_dwordx4 v[206:209], v50, s[20:21]
	global_load_dwordx4 v[210:213], v51, s[20:21]
	s_waitcnt vmcnt(31)
; DI f2_t cvt8lo(unsigned w) { return __builtin_amdgcn_cvt_pk_f32_fp8(w, false); }
; DI f2_t cvt8hi(unsigned w) { return __builtin_amdgcn_cvt_pk_f32_fp8(w, true); }
; DI void phase11(const Params& p, char* smem, int rep) {
;     ...
;         for (int k = 0; k < 16; ++k) rows[k] = *(const u32x4*)(vb + (size_t)ida[k] * 2048);
; #pragma unroll
;         for (int k = 0; k < 16; ++k) {
;           const f2_t a2 = {aa[k], aa[k]};
; #pragma unroll
;           for (int d = 0; d < 4; ++d) { const unsigned ww = rows[k][d]; o[2 * d] += a2 * cvt8lo(ww); o[2 * d + 1] += a2 * cvt8hi(ww); }
;         }
	v_cvt_pk_f32_fp8_e32 v[232:233], v84
	v_cvt_pk_f32_fp8_sdwa v[234:235], v84 src0_sel:WORD_1
	v_pk_fma_f32 v[216:217], v[52:53], v[232:233], 0 op_sel_hi:[0,1,0]
	v_pk_fma_f32 v[218:219], v[52:53], v[234:235], 0 op_sel_hi:[0,1,0]
	v_cvt_pk_f32_fp8_e32 v[236:237], v85
	v_cvt_pk_f32_fp8_sdwa v[238:239], v85 src0_sel:WORD_1
	v_pk_fma_f32 v[220:221], v[52:53], v[236:237], 0 op_sel_hi:[0,1,0]
	v_pk_fma_f32 v[222:223], v[52:53], v[238:239], 0 op_sel_hi:[0,1,0]
	v_cvt_pk_f32_fp8_e32 v[232:233], v86
	v_cvt_pk_f32_fp8_sdwa v[234:235], v86 src0_sel:WORD_1
	v_pk_fma_f32 v[224:225], v[52:53], v[232:233], 0 op_sel_hi:[0,1,0]
	v_pk_fma_f32 v[226:227], v[52:53], v[234:235], 0 op_sel_hi:[0,1,0]
	v_cvt_pk_f32_fp8_e32 v[236:237], v87
	v_cvt_pk_f32_fp8_sdwa v[238:239], v87 src0_sel:WORD_1
	v_pk_fma_f32 v[228:229], v[52:53], v[236:237], 0 op_sel_hi:[0,1,0]
	v_pk_fma_f32 v[230:231], v[52:53], v[238:239], 0 op_sel_hi:[0,1,0]
	s_waitcnt vmcnt(30)
	v_cvt_pk_f32_fp8_e32 v[232:233], v88
	v_cvt_pk_f32_fp8_sdwa v[234:235], v88 src0_sel:WORD_1
	v_pk_fma_f32 v[216:217], v[52:53], v[232:233], v[216:217] op_sel:[1,0,0]
	v_pk_fma_f32 v[218:219], v[52:53], v[234:235], v[218:219] op_sel:[1,0,0]
	v_cvt_pk_f32_fp8_e32 v[236:237], v89
	v_cvt_pk_f32_fp8_sdwa v[238:239], v89 src0_sel:WORD_1
	v_pk_fma_f32 v[220:221], v[52:53], v[236:237], v[220:221] op_sel:[1,0,0]
	v_pk_fma_f32 v[222:223], v[52:53], v[238:239], v[222:223] op_sel:[1,0,0]
	v_cvt_pk_f32_fp8_e32 v[232:233], v90
	v_cvt_pk_f32_fp8_sdwa v[234:235], v90 src0_sel:WORD_1
	v_pk_fma_f32 v[224:225], v[52:53], v[232:233], v[224:225] op_sel:[1,0,0]
	v_pk_fma_f32 v[226:227], v[52:53], v[234:235], v[226:227] op_sel:[1,0,0]
	v_cvt_pk_f32_fp8_e32 v[236:237], v91
	v_cvt_pk_f32_fp8_sdwa v[238:239], v91 src0_sel:WORD_1
	v_pk_fma_f32 v[228:229], v[52:53], v[236:237], v[228:229] op_sel:[1,0,0]
	v_pk_fma_f32 v[230:231], v[52:53], v[238:239], v[230:231] op_sel:[1,0,0]
	s_waitcnt vmcnt(29)
	v_cvt_pk_f32_fp8_e32 v[232:233], v92
	v_cvt_pk_f32_fp8_sdwa v[234:235], v92 src0_sel:WORD_1
	v_pk_fma_f32 v[216:217], v[54:55], v[232:233], v[216:217] op_sel_hi:[0,1,1]
	v_pk_fma_f32 v[218:219], v[54:55], v[234:235], v[218:219] op_sel_hi:[0,1,1]
	v_cvt_pk_f32_fp8_e32 v[236:237], v93
	v_cvt_pk_f32_fp8_sdwa v[238:239], v93 src0_sel:WORD_1
	v_pk_fma_f32 v[220:221], v[54:55], v[236:237], v[220:221] op_sel_hi:[0,1,1]
	v_pk_fma_f32 v[222:223], v[54:55], v[238:239], v[222:223] op_sel_hi:[0,1,1]
	v_cvt_pk_f32_fp8_e32 v[232:233], v94
	v_cvt_pk_f32_fp8_sdwa v[234:235], v94 src0_sel:WORD_1
	v_pk_fma_f32 v[224:225], v[54:55], v[232:233], v[224:225] op_sel_hi:[0,1,1]
	v_pk_fma_f32 v[226:227], v[54:55], v[234:235], v[226:227] op_sel_hi:[0,1,1]
	v_cvt_pk_f32_fp8_e32 v[236:237], v95
	v_cvt_pk_f32_fp8_sdwa v[238:239], v95 src0_sel:WORD_1
	v_pk_fma_f32 v[228:229], v[54:55], v[236:237], v[228:229] op_sel_hi:[0,1,1]
	v_pk_fma_f32 v[230:231], v[54:55], v[238:239], v[230:231] op_sel_hi:[0,1,1]
	s_waitcnt vmcnt(28)
	v_cvt_pk_f32_fp8_e32 v[232:233], v96
	v_cvt_pk_f32_fp8_sdwa v[234:235], v96 src0_sel:WORD_1
	v_pk_fma_f32 v[216:217], v[54:55], v[232:233], v[216:217] op_sel:[1,0,0]
	v_pk_fma_f32 v[218:219], v[54:55], v[234:235], v[218:219] op_sel:[1,0,0]
	v_cvt_pk_f32_fp8_e32 v[236:237], v97
	v_cvt_pk_f32_fp8_sdwa v[238:239], v97 src0_sel:WORD_1
	v_pk_fma_f32 v[220:221], v[54:55], v[236:237], v[220:221] op_sel:[1,0,0]
	v_pk_fma_f32 v[222:223], v[54:55], v[238:239], v[222:223] op_sel:[1,0,0]
	v_cvt_pk_f32_fp8_e32 v[232:233], v98
	v_cvt_pk_f32_fp8_sdwa v[234:235], v98 src0_sel:WORD_1
	v_pk_fma_f32 v[224:225], v[54:55], v[232:233], v[224:225] op_sel:[1,0,0]
	v_pk_fma_f32 v[226:227], v[54:55], v[234:235], v[226:227] op_sel:[1,0,0]
	v_cvt_pk_f32_fp8_e32 v[236:237], v99
	v_cvt_pk_f32_fp8_sdwa v[238:239], v99 src0_sel:WORD_1
	v_pk_fma_f32 v[228:229], v[54:55], v[236:237], v[228:229] op_sel:[1,0,0]
	v_pk_fma_f32 v[230:231], v[54:55], v[238:239], v[230:231] op_sel:[1,0,0]
	s_waitcnt vmcnt(27)
	v_cvt_pk_f32_fp8_e32 v[232:233], v100
	v_cvt_pk_f32_fp8_sdwa v[234:235], v100 src0_sel:WORD_1
	v_pk_fma_f32 v[216:217], v[56:57], v[232:233], v[216:217] op_sel_hi:[0,1,1]
	v_pk_fma_f32 v[218:219], v[56:57], v[234:235], v[218:219] op_sel_hi:[0,1,1]
	v_cvt_pk_f32_fp8_e32 v[236:237], v101
	v_cvt_pk_f32_fp8_sdwa v[238:239], v101 src0_sel:WORD_1
	v_pk_fma_f32 v[220:221], v[56:57], v[236:237], v[220:221] op_sel_hi:[0,1,1]
	v_pk_fma_f32 v[222:223], v[56:57], v[238:239], v[222:223] op_sel_hi:[0,1,1]
	v_cvt_pk_f32_fp8_e32 v[232:233], v102
	v_cvt_pk_f32_fp8_sdwa v[234:235], v102 src0_sel:WORD_1
	v_pk_fma_f32 v[224:225], v[56:57], v[232:233], v[224:225] op_sel_hi:[0,1,1]
	v_pk_fma_f32 v[226:227], v[56:57], v[234:235], v[226:227] op_sel_hi:[0,1,1]
	v_cvt_pk_f32_fp8_e32 v[236:237], v103
	v_cvt_pk_f32_fp8_sdwa v[238:239], v103 src0_sel:WORD_1
	v_pk_fma_f32 v[228:229], v[56:57], v[236:237], v[228:229] op_sel_hi:[0,1,1]
	v_pk_fma_f32 v[230:231], v[56:57], v[238:239], v[230:231] op_sel_hi:[0,1,1]
	s_waitcnt vmcnt(26)
	v_cvt_pk_f32_fp8_e32 v[232:233], v104
	v_cvt_pk_f32_fp8_sdwa v[234:235], v104 src0_sel:WORD_1
	v_pk_fma_f32 v[216:217], v[56:57], v[232:233], v[216:217] op_sel:[1,0,0]
	v_pk_fma_f32 v[218:219], v[56:57], v[234:235], v[218:219] op_sel:[1,0,0]
	v_cvt_pk_f32_fp8_e32 v[236:237], v105
	v_cvt_pk_f32_fp8_sdwa v[238:239], v105 src0_sel:WORD_1
	v_pk_fma_f32 v[220:221], v[56:57], v[236:237], v[220:221] op_sel:[1,0,0]
	v_pk_fma_f32 v[222:223], v[56:57], v[238:239], v[222:223] op_sel:[1,0,0]
	v_cvt_pk_f32_fp8_e32 v[232:233], v106
	v_cvt_pk_f32_fp8_sdwa v[234:235], v106 src0_sel:WORD_1
	v_pk_fma_f32 v[224:225], v[56:57], v[232:233], v[224:225] op_sel:[1,0,0]
	v_pk_fma_f32 v[226:227], v[56:57], v[234:235], v[226:227] op_sel:[1,0,0]
	v_cvt_pk_f32_fp8_e32 v[236:237], v107
	v_cvt_pk_f32_fp8_sdwa v[238:239], v107 src0_sel:WORD_1
	v_pk_fma_f32 v[228:229], v[56:57], v[236:237], v[228:229] op_sel:[1,0,0]
	v_pk_fma_f32 v[230:231], v[56:57], v[238:239], v[230:231] op_sel:[1,0,0]
	s_waitcnt vmcnt(25)
; DI f2_t cvt8lo(unsigned w) { return __builtin_amdgcn_cvt_pk_f32_fp8(w, false); }
; DI f2_t cvt8hi(unsigned w) { return __builtin_amdgcn_cvt_pk_f32_fp8(w, true); }
; DI void phase11(const Params& p, char* smem, int rep) {
;     ...
;         for (int k = 0; k < 16; ++k) {
;           const f2_t a2 = {aa[k], aa[k]};
; #pragma unroll
;           for (int d = 0; d < 4; ++d) { const unsigned ww = rows[k][d]; o[2 * d] += a2 * cvt8lo(ww); o[2 * d + 1] += a2 * cvt8hi(ww); }
;         }
	v_cvt_pk_f32_fp8_e32 v[232:233], v108
	v_cvt_pk_f32_fp8_sdwa v[234:235], v108 src0_sel:WORD_1
	v_pk_fma_f32 v[216:217], v[58:59], v[232:233], v[216:217] op_sel_hi:[0,1,1]
	v_pk_fma_f32 v[218:219], v[58:59], v[234:235], v[218:219] op_sel_hi:[0,1,1]
	v_cvt_pk_f32_fp8_e32 v[236:237], v109
	v_cvt_pk_f32_fp8_sdwa v[238:239], v109 src0_sel:WORD_1
	v_pk_fma_f32 v[220:221], v[58:59], v[236:237], v[220:221] op_sel_hi:[0,1,1]
	v_pk_fma_f32 v[222:223], v[58:59], v[238:239], v[222:223] op_sel_hi:[0,1,1]
	v_cvt_pk_f32_fp8_e32 v[232:233], v110
	v_cvt_pk_f32_fp8_sdwa v[234:235], v110 src0_sel:WORD_1
	v_pk_fma_f32 v[224:225], v[58:59], v[232:233], v[224:225] op_sel_hi:[0,1,1]
	v_pk_fma_f32 v[226:227], v[58:59], v[234:235], v[226:227] op_sel_hi:[0,1,1]
	v_cvt_pk_f32_fp8_e32 v[236:237], v111
	v_cvt_pk_f32_fp8_sdwa v[238:239], v111 src0_sel:WORD_1
	v_pk_fma_f32 v[228:229], v[58:59], v[236:237], v[228:229] op_sel_hi:[0,1,1]
	v_pk_fma_f32 v[230:231], v[58:59], v[238:239], v[230:231] op_sel_hi:[0,1,1]
	s_waitcnt vmcnt(24)
	v_cvt_pk_f32_fp8_e32 v[232:233], v112
	v_cvt_pk_f32_fp8_sdwa v[234:235], v112 src0_sel:WORD_1
	v_pk_fma_f32 v[216:217], v[58:59], v[232:233], v[216:217] op_sel:[1,0,0]
	v_pk_fma_f32 v[218:219], v[58:59], v[234:235], v[218:219] op_sel:[1,0,0]
	v_cvt_pk_f32_fp8_e32 v[236:237], v113
	v_cvt_pk_f32_fp8_sdwa v[238:239], v113 src0_sel:WORD_1
	v_pk_fma_f32 v[220:221], v[58:59], v[236:237], v[220:221] op_sel:[1,0,0]
	v_pk_fma_f32 v[222:223], v[58:59], v[238:239], v[222:223] op_sel:[1,0,0]
	v_cvt_pk_f32_fp8_e32 v[232:233], v114
	v_cvt_pk_f32_fp8_sdwa v[234:235], v114 src0_sel:WORD_1
	v_pk_fma_f32 v[224:225], v[58:59], v[232:233], v[224:225] op_sel:[1,0,0]
	v_pk_fma_f32 v[226:227], v[58:59], v[234:235], v[226:227] op_sel:[1,0,0]
	v_cvt_pk_f32_fp8_e32 v[236:237], v115
	v_cvt_pk_f32_fp8_sdwa v[238:239], v115 src0_sel:WORD_1
	v_pk_fma_f32 v[228:229], v[58:59], v[236:237], v[228:229] op_sel:[1,0,0]
	v_pk_fma_f32 v[230:231], v[58:59], v[238:239], v[230:231] op_sel:[1,0,0]
	s_waitcnt vmcnt(23)
	v_cvt_pk_f32_fp8_e32 v[232:233], v116
	v_cvt_pk_f32_fp8_sdwa v[234:235], v116 src0_sel:WORD_1
	v_pk_fma_f32 v[216:217], v[60:61], v[232:233], v[216:217] op_sel_hi:[0,1,1]
	v_pk_fma_f32 v[218:219], v[60:61], v[234:235], v[218:219] op_sel_hi:[0,1,1]
	v_cvt_pk_f32_fp8_e32 v[236:237], v117
	v_cvt_pk_f32_fp8_sdwa v[238:239], v117 src0_sel:WORD_1
	v_pk_fma_f32 v[220:221], v[60:61], v[236:237], v[220:221] op_sel_hi:[0,1,1]
	v_pk_fma_f32 v[222:223], v[60:61], v[238:239], v[222:223] op_sel_hi:[0,1,1]
	v_cvt_pk_f32_fp8_e32 v[232:233], v118
	v_cvt_pk_f32_fp8_sdwa v[234:235], v118 src0_sel:WORD_1
	v_pk_fma_f32 v[224:225], v[60:61], v[232:233], v[224:225] op_sel_hi:[0,1,1]
	v_pk_fma_f32 v[226:227], v[60:61], v[234:235], v[226:227] op_sel_hi:[0,1,1]
	v_cvt_pk_f32_fp8_e32 v[236:237], v119
	v_cvt_pk_f32_fp8_sdwa v[238:239], v119 src0_sel:WORD_1
	v_pk_fma_f32 v[228:229], v[60:61], v[236:237], v[228:229] op_sel_hi:[0,1,1]
	v_pk_fma_f32 v[230:231], v[60:61], v[238:239], v[230:231] op_sel_hi:[0,1,1]
	s_waitcnt vmcnt(22)
	v_cvt_pk_f32_fp8_e32 v[232:233], v120
	v_cvt_pk_f32_fp8_sdwa v[234:235], v120 src0_sel:WORD_1
	v_pk_fma_f32 v[216:217], v[60:61], v[232:233], v[216:217] op_sel:[1,0,0]
	v_pk_fma_f32 v[218:219], v[60:61], v[234:235], v[218:219] op_sel:[1,0,0]
	v_cvt_pk_f32_fp8_e32 v[236:237], v121
	v_cvt_pk_f32_fp8_sdwa v[238:239], v121 src0_sel:WORD_1
	v_pk_fma_f32 v[220:221], v[60:61], v[236:237], v[220:221] op_sel:[1,0,0]
	v_pk_fma_f32 v[222:223], v[60:61], v[238:239], v[222:223] op_sel:[1,0,0]
	v_cvt_pk_f32_fp8_e32 v[232:233], v122
	v_cvt_pk_f32_fp8_sdwa v[234:235], v122 src0_sel:WORD_1
	v_pk_fma_f32 v[224:225], v[60:61], v[232:233], v[224:225] op_sel:[1,0,0]
	v_pk_fma_f32 v[226:227], v[60:61], v[234:235], v[226:227] op_sel:[1,0,0]
	v_cvt_pk_f32_fp8_e32 v[236:237], v123
	v_cvt_pk_f32_fp8_sdwa v[238:239], v123 src0_sel:WORD_1
	v_pk_fma_f32 v[228:229], v[60:61], v[236:237], v[228:229] op_sel:[1,0,0]
	v_pk_fma_f32 v[230:231], v[60:61], v[238:239], v[230:231] op_sel:[1,0,0]
	s_waitcnt vmcnt(21)
	v_cvt_pk_f32_fp8_e32 v[232:233], v124
	v_cvt_pk_f32_fp8_sdwa v[234:235], v124 src0_sel:WORD_1
	v_pk_fma_f32 v[216:217], v[62:63], v[232:233], v[216:217] op_sel_hi:[0,1,1]
	v_pk_fma_f32 v[218:219], v[62:63], v[234:235], v[218:219] op_sel_hi:[0,1,1]
	v_cvt_pk_f32_fp8_e32 v[236:237], v125
	v_cvt_pk_f32_fp8_sdwa v[238:239], v125 src0_sel:WORD_1
	v_pk_fma_f32 v[220:221], v[62:63], v[236:237], v[220:221] op_sel_hi:[0,1,1]
	v_pk_fma_f32 v[222:223], v[62:63], v[238:239], v[222:223] op_sel_hi:[0,1,1]
	v_cvt_pk_f32_fp8_e32 v[232:233], v126
	v_cvt_pk_f32_fp8_sdwa v[234:235], v126 src0_sel:WORD_1
	v_pk_fma_f32 v[224:225], v[62:63], v[232:233], v[224:225] op_sel_hi:[0,1,1]
	v_pk_fma_f32 v[226:227], v[62:63], v[234:235], v[226:227] op_sel_hi:[0,1,1]
	v_cvt_pk_f32_fp8_e32 v[236:237], v127
	v_cvt_pk_f32_fp8_sdwa v[238:239], v127 src0_sel:WORD_1
	v_pk_fma_f32 v[228:229], v[62:63], v[236:237], v[228:229] op_sel_hi:[0,1,1]
	v_pk_fma_f32 v[230:231], v[62:63], v[238:239], v[230:231] op_sel_hi:[0,1,1]
	s_waitcnt vmcnt(20)
	v_cvt_pk_f32_fp8_e32 v[232:233], v128
	v_cvt_pk_f32_fp8_sdwa v[234:235], v128 src0_sel:WORD_1
	v_pk_fma_f32 v[216:217], v[62:63], v[232:233], v[216:217] op_sel:[1,0,0]
	v_pk_fma_f32 v[218:219], v[62:63], v[234:235], v[218:219] op_sel:[1,0,0]
	v_cvt_pk_f32_fp8_e32 v[236:237], v129
	v_cvt_pk_f32_fp8_sdwa v[238:239], v129 src0_sel:WORD_1
	v_pk_fma_f32 v[220:221], v[62:63], v[236:237], v[220:221] op_sel:[1,0,0]
	v_pk_fma_f32 v[222:223], v[62:63], v[238:239], v[222:223] op_sel:[1,0,0]
	v_cvt_pk_f32_fp8_e32 v[232:233], v130
	v_cvt_pk_f32_fp8_sdwa v[234:235], v130 src0_sel:WORD_1
	v_pk_fma_f32 v[224:225], v[62:63], v[232:233], v[224:225] op_sel:[1,0,0]
	v_pk_fma_f32 v[226:227], v[62:63], v[234:235], v[226:227] op_sel:[1,0,0]
	v_cvt_pk_f32_fp8_e32 v[236:237], v131
	v_cvt_pk_f32_fp8_sdwa v[238:239], v131 src0_sel:WORD_1
	v_pk_fma_f32 v[228:229], v[62:63], v[236:237], v[228:229] op_sel:[1,0,0]
	v_pk_fma_f32 v[230:231], v[62:63], v[238:239], v[230:231] op_sel:[1,0,0]
	s_waitcnt vmcnt(19)
; DI f2_t cvt8lo(unsigned w) { return __builtin_amdgcn_cvt_pk_f32_fp8(w, false); }
; DI f2_t cvt8hi(unsigned w) { return __builtin_amdgcn_cvt_pk_f32_fp8(w, true); }
; DI void wave_lds_sync() { asm volatile("s_waitcnt lgkmcnt(0)" ::: "memory"); __builtin_amdgcn_wave_barrier(); }
; DI void phase11(const Params& p, char* smem, int rep) {
;     ...
;       lw[(lane & 3) * 32 + (lane >> 2)] = i0; lw[(lane & 3) * 32 + 16 + (lane >> 2)] = i1;
;       lf[(lane & 3) * 32 + (lane >> 2)] = a0; lf[(lane & 3) * 32 + 16 + (lane >> 2)] = a1;
;       wave_lds_sync();
;       f2_t o[8];
; #pragma unroll
;       for (int i = 0; i < 8; ++i) o[i] = f2_t{0.f, 0.f};
;       const unsigned char* vb = V8 + s * 256 + l15 * 16;
; #pragma unroll
;       for (int batch = 0; batch < 2; ++batch) {
;         int ida[16]; float aa[16];
; #pragma unroll
;         for (int q = 0; q < 4; ++q) {
;           const int4 v = *(const int4*)(lw + g * 32 + batch * 16 + q * 4); ida[q * 4] = v.x; ida[q * 4 + 1] = v.y; ida[q * 4 + 2] = v.z; ida[q * 4 + 3] = v.w;
;           const float4 f = *(const float4*)(lf + g * 32 + batch * 16 + q * 4); aa[q * 4] = f.x; aa[q * 4 + 1] = f.y; aa[q * 4 + 2] = f.z; aa[q * 4 + 3] = f.w;
;         }
;         u32x4 rows[16];
; #pragma unroll
;         for (int k = 0; k < 16; ++k) rows[k] = *(const u32x4*)(vb + (size_t)ida[k] * 2048);
; #pragma unroll
;         for (int k = 0; k < 16; ++k) {
;           const f2_t a2 = {aa[k], aa[k]};
; #pragma unroll
;           for (int d = 0; d < 4; ++d) { const unsigned ww = rows[k][d]; o[2 * d] += a2 * cvt8lo(ww); o[2 * d + 1] += a2 * cvt8hi(ww); }
	v_cvt_pk_f32_fp8_e32 v[232:233], v132
	v_cvt_pk_f32_fp8_sdwa v[234:235], v132 src0_sel:WORD_1
	v_pk_fma_f32 v[216:217], v[64:65], v[232:233], v[216:217] op_sel_hi:[0,1,1]
	v_pk_fma_f32 v[218:219], v[64:65], v[234:235], v[218:219] op_sel_hi:[0,1,1]
	v_cvt_pk_f32_fp8_e32 v[236:237], v133
	v_cvt_pk_f32_fp8_sdwa v[238:239], v133 src0_sel:WORD_1
	v_pk_fma_f32 v[220:221], v[64:65], v[236:237], v[220:221] op_sel_hi:[0,1,1]
	v_pk_fma_f32 v[222:223], v[64:65], v[238:239], v[222:223] op_sel_hi:[0,1,1]
	v_cvt_pk_f32_fp8_e32 v[232:233], v134
	v_cvt_pk_f32_fp8_sdwa v[234:235], v134 src0_sel:WORD_1
	v_pk_fma_f32 v[224:225], v[64:65], v[232:233], v[224:225] op_sel_hi:[0,1,1]
	v_pk_fma_f32 v[226:227], v[64:65], v[234:235], v[226:227] op_sel_hi:[0,1,1]
	v_cvt_pk_f32_fp8_e32 v[236:237], v135
	v_cvt_pk_f32_fp8_sdwa v[238:239], v135 src0_sel:WORD_1
	v_pk_fma_f32 v[228:229], v[64:65], v[236:237], v[228:229] op_sel_hi:[0,1,1]
	v_pk_fma_f32 v[230:231], v[64:65], v[238:239], v[230:231] op_sel_hi:[0,1,1]
	s_waitcnt vmcnt(18)
	v_cvt_pk_f32_fp8_e32 v[232:233], v136
	v_cvt_pk_f32_fp8_sdwa v[234:235], v136 src0_sel:WORD_1
	v_pk_fma_f32 v[216:217], v[64:65], v[232:233], v[216:217] op_sel:[1,0,0]
	v_pk_fma_f32 v[218:219], v[64:65], v[234:235], v[218:219] op_sel:[1,0,0]
	v_cvt_pk_f32_fp8_e32 v[236:237], v137
	v_cvt_pk_f32_fp8_sdwa v[238:239], v137 src0_sel:WORD_1
	v_pk_fma_f32 v[220:221], v[64:65], v[236:237], v[220:221] op_sel:[1,0,0]
	v_pk_fma_f32 v[222:223], v[64:65], v[238:239], v[222:223] op_sel:[1,0,0]
	v_cvt_pk_f32_fp8_e32 v[232:233], v138
	v_cvt_pk_f32_fp8_sdwa v[234:235], v138 src0_sel:WORD_1
	v_pk_fma_f32 v[224:225], v[64:65], v[232:233], v[224:225] op_sel:[1,0,0]
	v_pk_fma_f32 v[226:227], v[64:65], v[234:235], v[226:227] op_sel:[1,0,0]
	v_cvt_pk_f32_fp8_e32 v[236:237], v139
	v_cvt_pk_f32_fp8_sdwa v[238:239], v139 src0_sel:WORD_1
	v_pk_fma_f32 v[228:229], v[64:65], v[236:237], v[228:229] op_sel:[1,0,0]
	v_pk_fma_f32 v[230:231], v[64:65], v[238:239], v[230:231] op_sel:[1,0,0]
	s_waitcnt vmcnt(17)
	v_cvt_pk_f32_fp8_e32 v[232:233], v140
	v_cvt_pk_f32_fp8_sdwa v[234:235], v140 src0_sel:WORD_1
	v_pk_fma_f32 v[216:217], v[66:67], v[232:233], v[216:217] op_sel_hi:[0,1,1]
	v_pk_fma_f32 v[218:219], v[66:67], v[234:235], v[218:219] op_sel_hi:[0,1,1]
	v_cvt_pk_f32_fp8_e32 v[236:237], v141
	v_cvt_pk_f32_fp8_sdwa v[238:239], v141 src0_sel:WORD_1
	v_pk_fma_f32 v[220:221], v[66:67], v[236:237], v[220:221] op_sel_hi:[0,1,1]
	v_pk_fma_f32 v[222:223], v[66:67], v[238:239], v[222:223] op_sel_hi:[0,1,1]
	v_cvt_pk_f32_fp8_e32 v[232:233], v142
	v_cvt_pk_f32_fp8_sdwa v[234:235], v142 src0_sel:WORD_1
	v_pk_fma_f32 v[224:225], v[66:67], v[232:233], v[224:225] op_sel_hi:[0,1,1]
	v_pk_fma_f32 v[226:227], v[66:67], v[234:235], v[226:227] op_sel_hi:[0,1,1]
	v_cvt_pk_f32_fp8_e32 v[236:237], v143
	v_cvt_pk_f32_fp8_sdwa v[238:239], v143 src0_sel:WORD_1
	v_pk_fma_f32 v[228:229], v[66:67], v[236:237], v[228:229] op_sel_hi:[0,1,1]
	v_pk_fma_f32 v[230:231], v[66:67], v[238:239], v[230:231] op_sel_hi:[0,1,1]
	s_waitcnt vmcnt(16)
	v_cvt_pk_f32_fp8_e32 v[232:233], v144
	v_cvt_pk_f32_fp8_sdwa v[234:235], v144 src0_sel:WORD_1
	v_pk_fma_f32 v[216:217], v[66:67], v[232:233], v[216:217] op_sel:[1,0,0]
	v_pk_fma_f32 v[218:219], v[66:67], v[234:235], v[218:219] op_sel:[1,0,0]
	v_cvt_pk_f32_fp8_e32 v[236:237], v145
	v_cvt_pk_f32_fp8_sdwa v[238:239], v145 src0_sel:WORD_1
	v_pk_fma_f32 v[220:221], v[66:67], v[236:237], v[220:221] op_sel:[1,0,0]
	v_pk_fma_f32 v[222:223], v[66:67], v[238:239], v[222:223] op_sel:[1,0,0]
	v_cvt_pk_f32_fp8_e32 v[232:233], v146
	v_cvt_pk_f32_fp8_sdwa v[234:235], v146 src0_sel:WORD_1
	v_pk_fma_f32 v[224:225], v[66:67], v[232:233], v[224:225] op_sel:[1,0,0]
	v_pk_fma_f32 v[226:227], v[66:67], v[234:235], v[226:227] op_sel:[1,0,0]
	v_cvt_pk_f32_fp8_e32 v[236:237], v147
	v_cvt_pk_f32_fp8_sdwa v[238:239], v147 src0_sel:WORD_1
	v_pk_fma_f32 v[228:229], v[66:67], v[236:237], v[228:229] op_sel:[1,0,0]
	v_pk_fma_f32 v[230:231], v[66:67], v[238:239], v[230:231] op_sel:[1,0,0]
	ds_write2_b32 v5, v10, v11 offset0:4 offset1:20
	ds_write2_b32 v5, v12, v13 offset0:132 offset1:148
	s_waitcnt lgkmcnt(0)
	ds_read_b128 v[20:23], v6 offset:16
	ds_read_b128 v[24:27], v6 offset:32
	ds_read_b128 v[28:31], v6 offset:48
	ds_read_b128 v[32:35], v6 offset:64
	ds_read_b128 v[36:39], v6 offset:80
	ds_read_b128 v[40:43], v6 offset:96
	ds_read_b128 v[44:47], v6 offset:112
	ds_read_b128 v[48:51], v6 offset:128
	s_waitcnt vmcnt(15)
	v_cvt_pk_f32_fp8_e32 v[232:233], v148
	v_cvt_pk_f32_fp8_sdwa v[234:235], v148 src0_sel:WORD_1
	v_pk_fma_f32 v[216:217], v[68:69], v[232:233], v[216:217] op_sel_hi:[0,1,1]
	v_pk_fma_f32 v[218:219], v[68:69], v[234:235], v[218:219] op_sel_hi:[0,1,1]
	v_cvt_pk_f32_fp8_e32 v[236:237], v149
	v_cvt_pk_f32_fp8_sdwa v[238:239], v149 src0_sel:WORD_1
	v_pk_fma_f32 v[220:221], v[68:69], v[236:237], v[220:221] op_sel_hi:[0,1,1]
	v_pk_fma_f32 v[222:223], v[68:69], v[238:239], v[222:223] op_sel_hi:[0,1,1]
	v_cvt_pk_f32_fp8_e32 v[232:233], v150
	v_cvt_pk_f32_fp8_sdwa v[234:235], v150 src0_sel:WORD_1
	v_pk_fma_f32 v[224:225], v[68:69], v[232:233], v[224:225] op_sel_hi:[0,1,1]
	v_pk_fma_f32 v[226:227], v[68:69], v[234:235], v[226:227] op_sel_hi:[0,1,1]
	v_cvt_pk_f32_fp8_e32 v[236:237], v151
	v_cvt_pk_f32_fp8_sdwa v[238:239], v151 src0_sel:WORD_1
	v_pk_fma_f32 v[228:229], v[68:69], v[236:237], v[228:229] op_sel_hi:[0,1,1]
	v_pk_fma_f32 v[230:231], v[68:69], v[238:239], v[230:231] op_sel_hi:[0,1,1]
	s_waitcnt vmcnt(14)
; DI f2_t cvt8lo(unsigned w) { return __builtin_amdgcn_cvt_pk_f32_fp8(w, false); }
; DI f2_t cvt8hi(unsigned w) { return __builtin_amdgcn_cvt_pk_f32_fp8(w, true); }
; DI void phase11(const Params& p, char* smem, int rep) {
;     ...
;         for (int k = 0; k < 16; ++k) {
;           const f2_t a2 = {aa[k], aa[k]};
; #pragma unroll
;           for (int d = 0; d < 4; ++d) { const unsigned ww = rows[k][d]; o[2 * d] += a2 * cvt8lo(ww); o[2 * d + 1] += a2 * cvt8hi(ww); }
;         }
	v_cvt_pk_f32_fp8_e32 v[232:233], v152
	v_cvt_pk_f32_fp8_sdwa v[234:235], v152 src0_sel:WORD_1
	v_pk_fma_f32 v[216:217], v[68:69], v[232:233], v[216:217] op_sel:[1,0,0]
	v_pk_fma_f32 v[218:219], v[68:69], v[234:235], v[218:219] op_sel:[1,0,0]
	v_cvt_pk_f32_fp8_e32 v[236:237], v153
	v_cvt_pk_f32_fp8_sdwa v[238:239], v153 src0_sel:WORD_1
	v_pk_fma_f32 v[220:221], v[68:69], v[236:237], v[220:221] op_sel:[1,0,0]
	v_pk_fma_f32 v[222:223], v[68:69], v[238:239], v[222:223] op_sel:[1,0,0]
	v_cvt_pk_f32_fp8_e32 v[232:233], v154
	v_cvt_pk_f32_fp8_sdwa v[234:235], v154 src0_sel:WORD_1
	v_pk_fma_f32 v[224:225], v[68:69], v[232:233], v[224:225] op_sel:[1,0,0]
	v_pk_fma_f32 v[226:227], v[68:69], v[234:235], v[226:227] op_sel:[1,0,0]
	v_cvt_pk_f32_fp8_e32 v[236:237], v155
	v_cvt_pk_f32_fp8_sdwa v[238:239], v155 src0_sel:WORD_1
	v_pk_fma_f32 v[228:229], v[68:69], v[236:237], v[228:229] op_sel:[1,0,0]
	v_pk_fma_f32 v[230:231], v[68:69], v[238:239], v[230:231] op_sel:[1,0,0]
	s_waitcnt vmcnt(13)
	v_cvt_pk_f32_fp8_e32 v[232:233], v156
	v_cvt_pk_f32_fp8_sdwa v[234:235], v156 src0_sel:WORD_1
	v_pk_fma_f32 v[216:217], v[70:71], v[232:233], v[216:217] op_sel_hi:[0,1,1]
	v_pk_fma_f32 v[218:219], v[70:71], v[234:235], v[218:219] op_sel_hi:[0,1,1]
	v_cvt_pk_f32_fp8_e32 v[236:237], v157
	v_cvt_pk_f32_fp8_sdwa v[238:239], v157 src0_sel:WORD_1
	v_pk_fma_f32 v[220:221], v[70:71], v[236:237], v[220:221] op_sel_hi:[0,1,1]
	v_pk_fma_f32 v[222:223], v[70:71], v[238:239], v[222:223] op_sel_hi:[0,1,1]
	v_cvt_pk_f32_fp8_e32 v[232:233], v158
	v_cvt_pk_f32_fp8_sdwa v[234:235], v158 src0_sel:WORD_1
	v_pk_fma_f32 v[224:225], v[70:71], v[232:233], v[224:225] op_sel_hi:[0,1,1]
	v_pk_fma_f32 v[226:227], v[70:71], v[234:235], v[226:227] op_sel_hi:[0,1,1]
	v_cvt_pk_f32_fp8_e32 v[236:237], v159
	v_cvt_pk_f32_fp8_sdwa v[238:239], v159 src0_sel:WORD_1
	v_pk_fma_f32 v[228:229], v[70:71], v[236:237], v[228:229] op_sel_hi:[0,1,1]
	v_pk_fma_f32 v[230:231], v[70:71], v[238:239], v[230:231] op_sel_hi:[0,1,1]
	s_waitcnt vmcnt(12)
	v_cvt_pk_f32_fp8_e32 v[232:233], v160
	v_cvt_pk_f32_fp8_sdwa v[234:235], v160 src0_sel:WORD_1
	v_pk_fma_f32 v[216:217], v[70:71], v[232:233], v[216:217] op_sel:[1,0,0]
	v_pk_fma_f32 v[218:219], v[70:71], v[234:235], v[218:219] op_sel:[1,0,0]
	v_cvt_pk_f32_fp8_e32 v[236:237], v161
	v_cvt_pk_f32_fp8_sdwa v[238:239], v161 src0_sel:WORD_1
	v_pk_fma_f32 v[220:221], v[70:71], v[236:237], v[220:221] op_sel:[1,0,0]
	v_pk_fma_f32 v[222:223], v[70:71], v[238:239], v[222:223] op_sel:[1,0,0]
	v_cvt_pk_f32_fp8_e32 v[232:233], v162
	v_cvt_pk_f32_fp8_sdwa v[234:235], v162 src0_sel:WORD_1
	v_pk_fma_f32 v[224:225], v[70:71], v[232:233], v[224:225] op_sel:[1,0,0]
	v_pk_fma_f32 v[226:227], v[70:71], v[234:235], v[226:227] op_sel:[1,0,0]
	v_cvt_pk_f32_fp8_e32 v[236:237], v163
	v_cvt_pk_f32_fp8_sdwa v[238:239], v163 src0_sel:WORD_1
	v_pk_fma_f32 v[228:229], v[70:71], v[236:237], v[228:229] op_sel:[1,0,0]
	v_pk_fma_f32 v[230:231], v[70:71], v[238:239], v[230:231] op_sel:[1,0,0]
	s_waitcnt vmcnt(11)
	v_cvt_pk_f32_fp8_e32 v[232:233], v164
	v_cvt_pk_f32_fp8_sdwa v[234:235], v164 src0_sel:WORD_1
	v_pk_fma_f32 v[216:217], v[72:73], v[232:233], v[216:217] op_sel_hi:[0,1,1]
	v_pk_fma_f32 v[218:219], v[72:73], v[234:235], v[218:219] op_sel_hi:[0,1,1]
	v_cvt_pk_f32_fp8_e32 v[236:237], v165
	v_cvt_pk_f32_fp8_sdwa v[238:239], v165 src0_sel:WORD_1
	v_pk_fma_f32 v[220:221], v[72:73], v[236:237], v[220:221] op_sel_hi:[0,1,1]
	v_pk_fma_f32 v[222:223], v[72:73], v[238:239], v[222:223] op_sel_hi:[0,1,1]
	v_cvt_pk_f32_fp8_e32 v[232:233], v166
	v_cvt_pk_f32_fp8_sdwa v[234:235], v166 src0_sel:WORD_1
	v_pk_fma_f32 v[224:225], v[72:73], v[232:233], v[224:225] op_sel_hi:[0,1,1]
	v_pk_fma_f32 v[226:227], v[72:73], v[234:235], v[226:227] op_sel_hi:[0,1,1]
	v_cvt_pk_f32_fp8_e32 v[236:237], v167
	v_cvt_pk_f32_fp8_sdwa v[238:239], v167 src0_sel:WORD_1
	v_pk_fma_f32 v[228:229], v[72:73], v[236:237], v[228:229] op_sel_hi:[0,1,1]
	v_pk_fma_f32 v[230:231], v[72:73], v[238:239], v[230:231] op_sel_hi:[0,1,1]
	s_waitcnt vmcnt(10)
	v_cvt_pk_f32_fp8_e32 v[232:233], v168
	v_cvt_pk_f32_fp8_sdwa v[234:235], v168 src0_sel:WORD_1
	v_pk_fma_f32 v[216:217], v[72:73], v[232:233], v[216:217] op_sel:[1,0,0]
	v_pk_fma_f32 v[218:219], v[72:73], v[234:235], v[218:219] op_sel:[1,0,0]
	v_cvt_pk_f32_fp8_e32 v[236:237], v169
	v_cvt_pk_f32_fp8_sdwa v[238:239], v169 src0_sel:WORD_1
	v_pk_fma_f32 v[220:221], v[72:73], v[236:237], v[220:221] op_sel:[1,0,0]
	v_pk_fma_f32 v[222:223], v[72:73], v[238:239], v[222:223] op_sel:[1,0,0]
	v_cvt_pk_f32_fp8_e32 v[232:233], v170
	v_cvt_pk_f32_fp8_sdwa v[234:235], v170 src0_sel:WORD_1
	v_pk_fma_f32 v[224:225], v[72:73], v[232:233], v[224:225] op_sel:[1,0,0]
	v_pk_fma_f32 v[226:227], v[72:73], v[234:235], v[226:227] op_sel:[1,0,0]
	v_cvt_pk_f32_fp8_e32 v[236:237], v171
	v_cvt_pk_f32_fp8_sdwa v[238:239], v171 src0_sel:WORD_1
	v_pk_fma_f32 v[228:229], v[72:73], v[236:237], v[228:229] op_sel:[1,0,0]
	v_pk_fma_f32 v[230:231], v[72:73], v[238:239], v[230:231] op_sel:[1,0,0]
	s_waitcnt vmcnt(9)
	v_cvt_pk_f32_fp8_e32 v[232:233], v172
	v_cvt_pk_f32_fp8_sdwa v[234:235], v172 src0_sel:WORD_1
	v_pk_fma_f32 v[216:217], v[74:75], v[232:233], v[216:217] op_sel_hi:[0,1,1]
	v_pk_fma_f32 v[218:219], v[74:75], v[234:235], v[218:219] op_sel_hi:[0,1,1]
	v_cvt_pk_f32_fp8_e32 v[236:237], v173
	v_cvt_pk_f32_fp8_sdwa v[238:239], v173 src0_sel:WORD_1
	v_pk_fma_f32 v[220:221], v[74:75], v[236:237], v[220:221] op_sel_hi:[0,1,1]
	v_pk_fma_f32 v[222:223], v[74:75], v[238:239], v[222:223] op_sel_hi:[0,1,1]
	v_cvt_pk_f32_fp8_e32 v[232:233], v174
	v_cvt_pk_f32_fp8_sdwa v[234:235], v174 src0_sel:WORD_1
	v_pk_fma_f32 v[224:225], v[74:75], v[232:233], v[224:225] op_sel_hi:[0,1,1]
	v_pk_fma_f32 v[226:227], v[74:75], v[234:235], v[226:227] op_sel_hi:[0,1,1]
	v_cvt_pk_f32_fp8_e32 v[236:237], v175
	v_cvt_pk_f32_fp8_sdwa v[238:239], v175 src0_sel:WORD_1
	v_pk_fma_f32 v[228:229], v[74:75], v[236:237], v[228:229] op_sel_hi:[0,1,1]
	v_pk_fma_f32 v[230:231], v[74:75], v[238:239], v[230:231] op_sel_hi:[0,1,1]
	s_waitcnt vmcnt(8)
; DI f2_t cvt8lo(unsigned w) { return __builtin_amdgcn_cvt_pk_f32_fp8(w, false); }
; DI f2_t cvt8hi(unsigned w) { return __builtin_amdgcn_cvt_pk_f32_fp8(w, true); }
; DI void phase11(const Params& p, char* smem, int rep) {
;     ...
;         for (int k = 0; k < 16; ++k) {
;           const f2_t a2 = {aa[k], aa[k]};
; #pragma unroll
;           for (int d = 0; d < 4; ++d) { const unsigned ww = rows[k][d]; o[2 * d] += a2 * cvt8lo(ww); o[2 * d + 1] += a2 * cvt8hi(ww); }
;         }
	v_cvt_pk_f32_fp8_e32 v[232:233], v176
	v_cvt_pk_f32_fp8_sdwa v[234:235], v176 src0_sel:WORD_1
	v_pk_fma_f32 v[216:217], v[74:75], v[232:233], v[216:217] op_sel:[1,0,0]
	v_pk_fma_f32 v[218:219], v[74:75], v[234:235], v[218:219] op_sel:[1,0,0]
	v_cvt_pk_f32_fp8_e32 v[236:237], v177
	v_cvt_pk_f32_fp8_sdwa v[238:239], v177 src0_sel:WORD_1
	v_pk_fma_f32 v[220:221], v[74:75], v[236:237], v[220:221] op_sel:[1,0,0]
	v_pk_fma_f32 v[222:223], v[74:75], v[238:239], v[222:223] op_sel:[1,0,0]
	v_cvt_pk_f32_fp8_e32 v[232:233], v178
	v_cvt_pk_f32_fp8_sdwa v[234:235], v178 src0_sel:WORD_1
	v_pk_fma_f32 v[224:225], v[74:75], v[232:233], v[224:225] op_sel:[1,0,0]
	v_pk_fma_f32 v[226:227], v[74:75], v[234:235], v[226:227] op_sel:[1,0,0]
	v_cvt_pk_f32_fp8_e32 v[236:237], v179
	v_cvt_pk_f32_fp8_sdwa v[238:239], v179 src0_sel:WORD_1
	v_pk_fma_f32 v[228:229], v[74:75], v[236:237], v[228:229] op_sel:[1,0,0]
	v_pk_fma_f32 v[230:231], v[74:75], v[238:239], v[230:231] op_sel:[1,0,0]
	s_waitcnt vmcnt(7)
	v_cvt_pk_f32_fp8_e32 v[232:233], v180
	v_cvt_pk_f32_fp8_sdwa v[234:235], v180 src0_sel:WORD_1
	v_pk_fma_f32 v[216:217], v[76:77], v[232:233], v[216:217] op_sel_hi:[0,1,1]
	v_pk_fma_f32 v[218:219], v[76:77], v[234:235], v[218:219] op_sel_hi:[0,1,1]
	v_cvt_pk_f32_fp8_e32 v[236:237], v181
	v_cvt_pk_f32_fp8_sdwa v[238:239], v181 src0_sel:WORD_1
	v_pk_fma_f32 v[220:221], v[76:77], v[236:237], v[220:221] op_sel_hi:[0,1,1]
	v_pk_fma_f32 v[222:223], v[76:77], v[238:239], v[222:223] op_sel_hi:[0,1,1]
	v_cvt_pk_f32_fp8_e32 v[232:233], v182
	v_cvt_pk_f32_fp8_sdwa v[234:235], v182 src0_sel:WORD_1
	v_pk_fma_f32 v[224:225], v[76:77], v[232:233], v[224:225] op_sel_hi:[0,1,1]
	v_pk_fma_f32 v[226:227], v[76:77], v[234:235], v[226:227] op_sel_hi:[0,1,1]
	v_cvt_pk_f32_fp8_e32 v[236:237], v183
	v_cvt_pk_f32_fp8_sdwa v[238:239], v183 src0_sel:WORD_1
	v_pk_fma_f32 v[228:229], v[76:77], v[236:237], v[228:229] op_sel_hi:[0,1,1]
	v_pk_fma_f32 v[230:231], v[76:77], v[238:239], v[230:231] op_sel_hi:[0,1,1]
	s_waitcnt vmcnt(6)
	v_cvt_pk_f32_fp8_e32 v[232:233], v184
	v_cvt_pk_f32_fp8_sdwa v[234:235], v184 src0_sel:WORD_1
	v_pk_fma_f32 v[216:217], v[76:77], v[232:233], v[216:217] op_sel:[1,0,0]
	v_pk_fma_f32 v[218:219], v[76:77], v[234:235], v[218:219] op_sel:[1,0,0]
	v_cvt_pk_f32_fp8_e32 v[236:237], v185
	v_cvt_pk_f32_fp8_sdwa v[238:239], v185 src0_sel:WORD_1
	v_pk_fma_f32 v[220:221], v[76:77], v[236:237], v[220:221] op_sel:[1,0,0]
	v_pk_fma_f32 v[222:223], v[76:77], v[238:239], v[222:223] op_sel:[1,0,0]
	v_cvt_pk_f32_fp8_e32 v[232:233], v186
	v_cvt_pk_f32_fp8_sdwa v[234:235], v186 src0_sel:WORD_1
	v_pk_fma_f32 v[224:225], v[76:77], v[232:233], v[224:225] op_sel:[1,0,0]
	v_pk_fma_f32 v[226:227], v[76:77], v[234:235], v[226:227] op_sel:[1,0,0]
	v_cvt_pk_f32_fp8_e32 v[236:237], v187
	v_cvt_pk_f32_fp8_sdwa v[238:239], v187 src0_sel:WORD_1
	v_pk_fma_f32 v[228:229], v[76:77], v[236:237], v[228:229] op_sel:[1,0,0]
	v_pk_fma_f32 v[230:231], v[76:77], v[238:239], v[230:231] op_sel:[1,0,0]
	s_waitcnt vmcnt(5)
	v_cvt_pk_f32_fp8_e32 v[232:233], v190
	v_cvt_pk_f32_fp8_sdwa v[234:235], v190 src0_sel:WORD_1
	v_pk_fma_f32 v[216:217], v[78:79], v[232:233], v[216:217] op_sel_hi:[0,1,1]
	v_pk_fma_f32 v[218:219], v[78:79], v[234:235], v[218:219] op_sel_hi:[0,1,1]
	v_cvt_pk_f32_fp8_e32 v[236:237], v191
	v_cvt_pk_f32_fp8_sdwa v[238:239], v191 src0_sel:WORD_1
	v_pk_fma_f32 v[220:221], v[78:79], v[236:237], v[220:221] op_sel_hi:[0,1,1]
	v_pk_fma_f32 v[222:223], v[78:79], v[238:239], v[222:223] op_sel_hi:[0,1,1]
	v_cvt_pk_f32_fp8_e32 v[232:233], v192
	v_cvt_pk_f32_fp8_sdwa v[234:235], v192 src0_sel:WORD_1
	v_pk_fma_f32 v[224:225], v[78:79], v[232:233], v[224:225] op_sel_hi:[0,1,1]
	v_pk_fma_f32 v[226:227], v[78:79], v[234:235], v[226:227] op_sel_hi:[0,1,1]
	v_cvt_pk_f32_fp8_e32 v[236:237], v193
	v_cvt_pk_f32_fp8_sdwa v[238:239], v193 src0_sel:WORD_1
	v_pk_fma_f32 v[228:229], v[78:79], v[236:237], v[228:229] op_sel_hi:[0,1,1]
	v_pk_fma_f32 v[230:231], v[78:79], v[238:239], v[230:231] op_sel_hi:[0,1,1]
	s_waitcnt vmcnt(4)
	v_cvt_pk_f32_fp8_e32 v[232:233], v194
	v_cvt_pk_f32_fp8_sdwa v[234:235], v194 src0_sel:WORD_1
	v_pk_fma_f32 v[216:217], v[78:79], v[232:233], v[216:217] op_sel:[1,0,0]
	v_pk_fma_f32 v[218:219], v[78:79], v[234:235], v[218:219] op_sel:[1,0,0]
	v_cvt_pk_f32_fp8_e32 v[236:237], v195
	v_cvt_pk_f32_fp8_sdwa v[238:239], v195 src0_sel:WORD_1
	v_pk_fma_f32 v[220:221], v[78:79], v[236:237], v[220:221] op_sel:[1,0,0]
	v_pk_fma_f32 v[222:223], v[78:79], v[238:239], v[222:223] op_sel:[1,0,0]
	v_cvt_pk_f32_fp8_e32 v[232:233], v196
	v_cvt_pk_f32_fp8_sdwa v[234:235], v196 src0_sel:WORD_1
	v_pk_fma_f32 v[224:225], v[78:79], v[232:233], v[224:225] op_sel:[1,0,0]
	v_pk_fma_f32 v[226:227], v[78:79], v[234:235], v[226:227] op_sel:[1,0,0]
	v_cvt_pk_f32_fp8_e32 v[236:237], v197
	v_cvt_pk_f32_fp8_sdwa v[238:239], v197 src0_sel:WORD_1
	v_pk_fma_f32 v[228:229], v[78:79], v[236:237], v[228:229] op_sel:[1,0,0]
	v_pk_fma_f32 v[230:231], v[78:79], v[238:239], v[230:231] op_sel:[1,0,0]
	s_waitcnt vmcnt(3)
	v_cvt_pk_f32_fp8_e32 v[232:233], v198
	v_cvt_pk_f32_fp8_sdwa v[234:235], v198 src0_sel:WORD_1
	v_pk_fma_f32 v[216:217], v[80:81], v[232:233], v[216:217] op_sel_hi:[0,1,1]
	v_pk_fma_f32 v[218:219], v[80:81], v[234:235], v[218:219] op_sel_hi:[0,1,1]
	v_cvt_pk_f32_fp8_e32 v[236:237], v199
	v_cvt_pk_f32_fp8_sdwa v[238:239], v199 src0_sel:WORD_1
	v_pk_fma_f32 v[220:221], v[80:81], v[236:237], v[220:221] op_sel_hi:[0,1,1]
	v_pk_fma_f32 v[222:223], v[80:81], v[238:239], v[222:223] op_sel_hi:[0,1,1]
	v_cvt_pk_f32_fp8_e32 v[232:233], v200
	v_cvt_pk_f32_fp8_sdwa v[234:235], v200 src0_sel:WORD_1
	v_pk_fma_f32 v[224:225], v[80:81], v[232:233], v[224:225] op_sel_hi:[0,1,1]
	v_pk_fma_f32 v[226:227], v[80:81], v[234:235], v[226:227] op_sel_hi:[0,1,1]
	v_cvt_pk_f32_fp8_e32 v[236:237], v201
	v_cvt_pk_f32_fp8_sdwa v[238:239], v201 src0_sel:WORD_1
	v_pk_fma_f32 v[228:229], v[80:81], v[236:237], v[228:229] op_sel_hi:[0,1,1]
	v_pk_fma_f32 v[230:231], v[80:81], v[238:239], v[230:231] op_sel_hi:[0,1,1]
	s_waitcnt vmcnt(2)
; DI unsigned pk2(float a, float b) { f2_t v = {a, b}; bf2_t r = __builtin_convertvector(v, bf2_t); return __builtin_bit_cast(unsigned, r); }
; DI void phase11(const Params& p, char* smem, int rep) {
;     ...
;       const int tok = __builtin_amdgcn_readfirstlane(c * 16 + w * 4 + t);
;       const int i0 = IDS[(size_t)tok * 128 + lane], i1 = IDS[(size_t)tok * 128 + 64 + lane];
;       const float a0 = ACT[(size_t)tok * 128 + lane], a1 = ACT[(size_t)tok * 128 + 64 + lane];
;       wave_lds_sync();
;       lw[(lane & 3) * 32 + (lane >> 2)] = i0; lw[(lane & 3) * 32 + 16 + (lane >> 2)] = i1;
;       lf[(lane & 3) * 32 + (lane >> 2)] = a0; lf[(lane & 3) * 32 + 16 + (lane >> 2)] = a1;
;       wave_lds_sync();
;       f2_t o[8];
; #pragma unroll
;       for (int i = 0; i < 8; ++i) o[i] = f2_t{0.f, 0.f};
;       const unsigned char* vb = V8 + s * 256 + l15 * 16;
; #pragma unroll
;       for (int batch = 0; batch < 2; ++batch) {
;         int ida[16]; float aa[16];
; #pragma unroll
;         for (int q = 0; q < 4; ++q) {
;           const int4 v = *(const int4*)(lw + g * 32 + batch * 16 + q * 4); ida[q * 4] = v.x; ida[q * 4 + 1] = v.y; ida[q * 4 + 2] = v.z; ida[q * 4 + 3] = v.w;
;           const float4 f = *(const float4*)(lf + g * 32 + batch * 16 + q * 4); aa[q * 4] = f.x; aa[q * 4 + 1] = f.y; aa[q * 4 + 2] = f.z; aa[q * 4 + 3] = f.w;
;         }
;         u32x4 rows[16];
; #pragma unroll
;         for (int k = 0; k < 16; ++k) rows[k] = *(const u32x4*)(vb + (size_t)ida[k] * 2048);
; #pragma unroll
;         for (int k = 0; k < 16; ++k) {
;           const f2_t a2 = {aa[k], aa[k]};
; #pragma unroll
;           for (int d = 0; d < 4; ++d) { const unsigned ww = rows[k][d]; o[2 * d] += a2 * cvt8lo(ww); o[2 * d + 1] += a2 * cvt8hi(ww); }
;         }
;       }
;       float ov[16];
; #pragma unroll
;       for (int d = 0; d < 4; ++d) { ov[4 * d] = o[2 * d].x; ov[4 * d + 1] = o[2 * d].y; ov[4 * d + 2] = o[2 * d + 1].x; ov[4 * d + 3] = o[2 * d + 1].y; }
;       float q8[8], q4[4];
; #pragma unroll
;       for (int k = 0; k < 8; ++k) q8[k] = (b5 ? ov[8 + k] : ov[k]) + __shfl_xor(b5 ? ov[k] : ov[8 + k], 32);
; #pragma unroll
;       for (int k = 0; k < 4; ++k) q4[k] = (b4 ? q8[4 + k] : q8[k]) + __shfl_xor(b4 ? q8[k] : q8[4 + k], 16);
;       *(uint2*)(OUTP + (size_t)tok * D_ + s * 256 + l15 * 16 + 8 * b5 + 4 * b4) = make_uint2(pk2(q4[0], q4[1]), pk2(q4[2], q4[3]));
	v_cvt_pk_f32_fp8_e32 v[232:233], v202
	v_cvt_pk_f32_fp8_sdwa v[234:235], v202 src0_sel:WORD_1
	v_pk_fma_f32 v[216:217], v[80:81], v[232:233], v[216:217] op_sel:[1,0,0]
	v_pk_fma_f32 v[218:219], v[80:81], v[234:235], v[218:219] op_sel:[1,0,0]
	v_cvt_pk_f32_fp8_e32 v[236:237], v203
	v_cvt_pk_f32_fp8_sdwa v[238:239], v203 src0_sel:WORD_1
	v_pk_fma_f32 v[220:221], v[80:81], v[236:237], v[220:221] op_sel:[1,0,0]
	v_pk_fma_f32 v[222:223], v[80:81], v[238:239], v[222:223] op_sel:[1,0,0]
	v_cvt_pk_f32_fp8_e32 v[232:233], v204
	v_cvt_pk_f32_fp8_sdwa v[234:235], v204 src0_sel:WORD_1
	v_pk_fma_f32 v[224:225], v[80:81], v[232:233], v[224:225] op_sel:[1,0,0]
	v_pk_fma_f32 v[226:227], v[80:81], v[234:235], v[226:227] op_sel:[1,0,0]
	v_cvt_pk_f32_fp8_e32 v[236:237], v205
	v_cvt_pk_f32_fp8_sdwa v[238:239], v205 src0_sel:WORD_1
	v_pk_fma_f32 v[228:229], v[80:81], v[236:237], v[228:229] op_sel:[1,0,0]
	v_pk_fma_f32 v[230:231], v[80:81], v[238:239], v[230:231] op_sel:[1,0,0]
	s_waitcnt vmcnt(1)
	v_cvt_pk_f32_fp8_e32 v[232:233], v206
	v_cvt_pk_f32_fp8_sdwa v[234:235], v206 src0_sel:WORD_1
	v_pk_fma_f32 v[216:217], v[82:83], v[232:233], v[216:217] op_sel_hi:[0,1,1]
	v_pk_fma_f32 v[218:219], v[82:83], v[234:235], v[218:219] op_sel_hi:[0,1,1]
	v_cvt_pk_f32_fp8_e32 v[236:237], v207
	v_cvt_pk_f32_fp8_sdwa v[238:239], v207 src0_sel:WORD_1
	v_pk_fma_f32 v[220:221], v[82:83], v[236:237], v[220:221] op_sel_hi:[0,1,1]
	v_pk_fma_f32 v[222:223], v[82:83], v[238:239], v[222:223] op_sel_hi:[0,1,1]
	v_cvt_pk_f32_fp8_e32 v[232:233], v208
	v_cvt_pk_f32_fp8_sdwa v[234:235], v208 src0_sel:WORD_1
	v_pk_fma_f32 v[224:225], v[82:83], v[232:233], v[224:225] op_sel_hi:[0,1,1]
	v_pk_fma_f32 v[226:227], v[82:83], v[234:235], v[226:227] op_sel_hi:[0,1,1]
	v_cvt_pk_f32_fp8_e32 v[236:237], v209
	v_cvt_pk_f32_fp8_sdwa v[238:239], v209 src0_sel:WORD_1
	v_pk_fma_f32 v[228:229], v[82:83], v[236:237], v[228:229] op_sel_hi:[0,1,1]
	v_pk_fma_f32 v[230:231], v[82:83], v[238:239], v[230:231] op_sel_hi:[0,1,1]
	s_waitcnt vmcnt(0)
	v_cvt_pk_f32_fp8_e32 v[232:233], v210
	v_cvt_pk_f32_fp8_sdwa v[234:235], v210 src0_sel:WORD_1
	v_pk_fma_f32 v[216:217], v[82:83], v[232:233], v[216:217] op_sel:[1,0,0]
	v_pk_fma_f32 v[218:219], v[82:83], v[234:235], v[218:219] op_sel:[1,0,0]
	v_cvt_pk_f32_fp8_e32 v[236:237], v211
	v_cvt_pk_f32_fp8_sdwa v[238:239], v211 src0_sel:WORD_1
	v_pk_fma_f32 v[220:221], v[82:83], v[236:237], v[220:221] op_sel:[1,0,0]
	v_pk_fma_f32 v[222:223], v[82:83], v[238:239], v[222:223] op_sel:[1,0,0]
	v_cvt_pk_f32_fp8_e32 v[232:233], v212
	v_cvt_pk_f32_fp8_sdwa v[234:235], v212 src0_sel:WORD_1
	v_pk_fma_f32 v[224:225], v[82:83], v[232:233], v[224:225] op_sel:[1,0,0]
	v_pk_fma_f32 v[226:227], v[82:83], v[234:235], v[226:227] op_sel:[1,0,0]
	v_cvt_pk_f32_fp8_e32 v[236:237], v213
	v_cvt_pk_f32_fp8_sdwa v[238:239], v213 src0_sel:WORD_1
	v_pk_fma_f32 v[228:229], v[82:83], v[236:237], v[228:229] op_sel:[1,0,0]
	v_pk_fma_f32 v[230:231], v[82:83], v[238:239], v[230:231] op_sel:[1,0,0]
	ds_read_b128 v[52:55], v6 offset:528
	ds_read_b128 v[56:59], v6 offset:544
	ds_read_b128 v[60:63], v6 offset:560
	ds_read_b128 v[64:67], v6 offset:576
	ds_read_b128 v[68:71], v6 offset:592
	ds_read_b128 v[72:75], v6 offset:608
	ds_read_b128 v[76:79], v6 offset:624
	ds_read_b128 v[80:83], v6 offset:640
	v_add_u32_e32 v214, s46, v4
	s_nop 0
	v_permlane32_swap_b32_e32 v216, v224
	v_permlane32_swap_b32_e32 v217, v225
	v_permlane32_swap_b32_e32 v218, v226
	v_permlane32_swap_b32_e32 v219, v227
	v_permlane32_swap_b32_e32 v220, v228
	v_permlane32_swap_b32_e32 v221, v229
	v_permlane32_swap_b32_e32 v222, v230
	v_permlane32_swap_b32_e32 v223, v231
	v_add_f32_e32 v216, v216, v224
	v_add_f32_e32 v217, v217, v225
	v_add_f32_e32 v218, v218, v226
	v_add_f32_e32 v219, v219, v227
	v_add_f32_e32 v220, v220, v228
	v_add_f32_e32 v221, v221, v229
	v_add_f32_e32 v222, v222, v230
	v_add_f32_e32 v223, v223, v231
	s_nop 1
	v_permlane16_swap_b32_e32 v216, v220
	v_permlane16_swap_b32_e32 v217, v221
	v_permlane16_swap_b32_e32 v218, v222
	v_permlane16_swap_b32_e32 v219, v223
	v_add_f32_e32 v216, v216, v220
	v_add_f32_e32 v217, v217, v221
	v_add_f32_e32 v218, v218, v222
	v_add_f32_e32 v219, v219, v223
	v_cvt_pk_bf16_f32 v232, v216, v217
	v_cvt_pk_bf16_f32 v233, v218, v219
	global_store_dwordx2 v214, v[232:233], s[14:15] nt
	s_add_i32 s54, s34, 2
	s_lshl_b32 s46, s54, 12
	s_add_i32 s46, s46, s24
	s_add_i32 s55, s34, 3
	s_lshl_b32 s47, s55, 9
	s_add_u32 s42, s6, s47
	s_addc_u32 s43, s7, 0
	s_add_u32 s44, s8, s47
	s_addc_u32 s45, s9, 0
	global_load_dword v10, v3, s[42:43]
	global_load_dword v11, v3, s[42:43] offset:256
	global_load_dword v12, v3, s[44:45]
	global_load_dword v13, v3, s[44:45] offset:256
	s_waitcnt lgkmcnt(0)
; DI f2_t cvt8lo(unsigned w) { return __builtin_amdgcn_cvt_pk_f32_fp8(w, false); }
; DI f2_t cvt8hi(unsigned w) { return __builtin_amdgcn_cvt_pk_f32_fp8(w, true); }
; DI void phase11(const Params& p, char* smem, int rep) {
;     ...
;           const int4 v = *(const int4*)(lw + g * 32 + batch * 16 + q * 4); ida[q * 4] = v.x; ida[q * 4 + 1] = v.y; ida[q * 4 + 2] = v.z; ida[q * 4 + 3] = v.w;
;           const float4 f = *(const float4*)(lf + g * 32 + batch * 16 + q * 4); aa[q * 4] = f.x; aa[q * 4 + 1] = f.y; aa[q * 4 + 2] = f.z; aa[q * 4 + 3] = f.w;
;         }
;         u32x4 rows[16];
; #pragma unroll
;         for (int k = 0; k < 16; ++k) rows[k] = *(const u32x4*)(vb + (size_t)ida[k] * 2048);
; #pragma unroll
;         for (int k = 0; k < 16; ++k) {
;           const f2_t a2 = {aa[k], aa[k]};
; #pragma unroll
;           for (int d = 0; d < 4; ++d) { const unsigned ww = rows[k][d]; o[2 * d] += a2 * cvt8lo(ww); o[2 * d + 1] += a2 * cvt8hi(ww); }
	v_lshl_add_u32 v20, v20, 11, v2
	v_lshl_add_u32 v21, v21, 11, v2
	v_lshl_add_u32 v22, v22, 11, v2
	v_lshl_add_u32 v23, v23, 11, v2
	v_lshl_add_u32 v24, v24, 11, v2
	v_lshl_add_u32 v25, v25, 11, v2
	v_lshl_add_u32 v26, v26, 11, v2
	v_lshl_add_u32 v27, v27, 11, v2
	v_lshl_add_u32 v28, v28, 11, v2
	v_lshl_add_u32 v29, v29, 11, v2
	v_lshl_add_u32 v30, v30, 11, v2
	v_lshl_add_u32 v31, v31, 11, v2
	v_lshl_add_u32 v32, v32, 11, v2
	v_lshl_add_u32 v33, v33, 11, v2
	v_lshl_add_u32 v34, v34, 11, v2
	v_lshl_add_u32 v35, v35, 11, v2
	v_lshl_add_u32 v36, v36, 11, v2
	v_lshl_add_u32 v37, v37, 11, v2
	v_lshl_add_u32 v38, v38, 11, v2
	v_lshl_add_u32 v39, v39, 11, v2
	v_lshl_add_u32 v40, v40, 11, v2
	v_lshl_add_u32 v41, v41, 11, v2
	v_lshl_add_u32 v42, v42, 11, v2
	v_lshl_add_u32 v43, v43, 11, v2
	v_lshl_add_u32 v44, v44, 11, v2
	v_lshl_add_u32 v45, v45, 11, v2
	v_lshl_add_u32 v46, v46, 11, v2
	v_lshl_add_u32 v47, v47, 11, v2
	v_lshl_add_u32 v48, v48, 11, v2
	v_lshl_add_u32 v49, v49, 11, v2
	v_lshl_add_u32 v50, v50, 11, v2
	v_lshl_add_u32 v51, v51, 11, v2
	global_load_dwordx4 v[84:87], v20, s[20:21]
	global_load_dwordx4 v[88:91], v21, s[20:21]
	global_load_dwordx4 v[92:95], v22, s[20:21]
	global_load_dwordx4 v[96:99], v23, s[20:21]
	global_load_dwordx4 v[100:103], v24, s[20:21]
	global_load_dwordx4 v[104:107], v25, s[20:21]
	global_load_dwordx4 v[108:111], v26, s[20:21]
	global_load_dwordx4 v[112:115], v27, s[20:21]
	global_load_dwordx4 v[116:119], v28, s[20:21]
	global_load_dwordx4 v[120:123], v29, s[20:21]
	global_load_dwordx4 v[124:127], v30, s[20:21]
	global_load_dwordx4 v[128:131], v31, s[20:21]
	global_load_dwordx4 v[132:135], v32, s[20:21]
	global_load_dwordx4 v[136:139], v33, s[20:21]
	global_load_dwordx4 v[140:143], v34, s[20:21]
	global_load_dwordx4 v[144:147], v35, s[20:21]
	global_load_dwordx4 v[148:151], v36, s[20:21]
	global_load_dwordx4 v[152:155], v37, s[20:21]
	global_load_dwordx4 v[156:159], v38, s[20:21]
	global_load_dwordx4 v[160:163], v39, s[20:21]
	global_load_dwordx4 v[164:167], v40, s[20:21]
	global_load_dwordx4 v[168:171], v41, s[20:21]
	global_load_dwordx4 v[172:175], v42, s[20:21]
	global_load_dwordx4 v[176:179], v43, s[20:21]
	global_load_dwordx4 v[180:183], v44, s[20:21]
	global_load_dwordx4 v[184:187], v45, s[20:21]
	global_load_dwordx4 v[190:193], v46, s[20:21]
	global_load_dwordx4 v[194:197], v47, s[20:21]
	global_load_dwordx4 v[198:201], v48, s[20:21]
	global_load_dwordx4 v[202:205], v49, s[20:21]
	global_load_dwordx4 v[206:209], v50, s[20:21]
	global_load_dwordx4 v[210:213], v51, s[20:21]
	s_waitcnt vmcnt(31)
	v_cvt_pk_f32_fp8_e32 v[232:233], v84
	v_cvt_pk_f32_fp8_sdwa v[234:235], v84 src0_sel:WORD_1
	v_pk_fma_f32 v[216:217], v[52:53], v[232:233], 0 op_sel_hi:[0,1,0]
	v_pk_fma_f32 v[218:219], v[52:53], v[234:235], 0 op_sel_hi:[0,1,0]
	v_cvt_pk_f32_fp8_e32 v[236:237], v85
	v_cvt_pk_f32_fp8_sdwa v[238:239], v85 src0_sel:WORD_1
	v_pk_fma_f32 v[220:221], v[52:53], v[236:237], 0 op_sel_hi:[0,1,0]
	v_pk_fma_f32 v[222:223], v[52:53], v[238:239], 0 op_sel_hi:[0,1,0]
	v_cvt_pk_f32_fp8_e32 v[232:233], v86
	v_cvt_pk_f32_fp8_sdwa v[234:235], v86 src0_sel:WORD_1
	v_pk_fma_f32 v[224:225], v[52:53], v[232:233], 0 op_sel_hi:[0,1,0]
	v_pk_fma_f32 v[226:227], v[52:53], v[234:235], 0 op_sel_hi:[0,1,0]
	v_cvt_pk_f32_fp8_e32 v[236:237], v87
	v_cvt_pk_f32_fp8_sdwa v[238:239], v87 src0_sel:WORD_1
	v_pk_fma_f32 v[228:229], v[52:53], v[236:237], 0 op_sel_hi:[0,1,0]
	v_pk_fma_f32 v[230:231], v[52:53], v[238:239], 0 op_sel_hi:[0,1,0]
	s_waitcnt vmcnt(30)
	v_cvt_pk_f32_fp8_e32 v[232:233], v88
	v_cvt_pk_f32_fp8_sdwa v[234:235], v88 src0_sel:WORD_1
	v_pk_fma_f32 v[216:217], v[52:53], v[232:233], v[216:217] op_sel:[1,0,0]
	v_pk_fma_f32 v[218:219], v[52:53], v[234:235], v[218:219] op_sel:[1,0,0]
	v_cvt_pk_f32_fp8_e32 v[236:237], v89
	v_cvt_pk_f32_fp8_sdwa v[238:239], v89 src0_sel:WORD_1
	v_pk_fma_f32 v[220:221], v[52:53], v[236:237], v[220:221] op_sel:[1,0,0]
	v_pk_fma_f32 v[222:223], v[52:53], v[238:239], v[222:223] op_sel:[1,0,0]
	v_cvt_pk_f32_fp8_e32 v[232:233], v90
	v_cvt_pk_f32_fp8_sdwa v[234:235], v90 src0_sel:WORD_1
	v_pk_fma_f32 v[224:225], v[52:53], v[232:233], v[224:225] op_sel:[1,0,0]
	v_pk_fma_f32 v[226:227], v[52:53], v[234:235], v[226:227] op_sel:[1,0,0]
	v_cvt_pk_f32_fp8_e32 v[236:237], v91
	v_cvt_pk_f32_fp8_sdwa v[238:239], v91 src0_sel:WORD_1
	v_pk_fma_f32 v[228:229], v[52:53], v[236:237], v[228:229] op_sel:[1,0,0]
	v_pk_fma_f32 v[230:231], v[52:53], v[238:239], v[230:231] op_sel:[1,0,0]
	s_waitcnt vmcnt(29)
	v_cvt_pk_f32_fp8_e32 v[232:233], v92
	v_cvt_pk_f32_fp8_sdwa v[234:235], v92 src0_sel:WORD_1
	v_pk_fma_f32 v[216:217], v[54:55], v[232:233], v[216:217] op_sel_hi:[0,1,1]
	v_pk_fma_f32 v[218:219], v[54:55], v[234:235], v[218:219] op_sel_hi:[0,1,1]
	v_cvt_pk_f32_fp8_e32 v[236:237], v93
	v_cvt_pk_f32_fp8_sdwa v[238:239], v93 src0_sel:WORD_1
	v_pk_fma_f32 v[220:221], v[54:55], v[236:237], v[220:221] op_sel_hi:[0,1,1]
	v_pk_fma_f32 v[222:223], v[54:55], v[238:239], v[222:223] op_sel_hi:[0,1,1]
	v_cvt_pk_f32_fp8_e32 v[232:233], v94
	v_cvt_pk_f32_fp8_sdwa v[234:235], v94 src0_sel:WORD_1
	v_pk_fma_f32 v[224:225], v[54:55], v[232:233], v[224:225] op_sel_hi:[0,1,1]
	v_pk_fma_f32 v[226:227], v[54:55], v[234:235], v[226:227] op_sel_hi:[0,1,1]
	v_cvt_pk_f32_fp8_e32 v[236:237], v95
	v_cvt_pk_f32_fp8_sdwa v[238:239], v95 src0_sel:WORD_1
	v_pk_fma_f32 v[228:229], v[54:55], v[236:237], v[228:229] op_sel_hi:[0,1,1]
	v_pk_fma_f32 v[230:231], v[54:55], v[238:239], v[230:231] op_sel_hi:[0,1,1]
	s_waitcnt vmcnt(28)
; DI f2_t cvt8lo(unsigned w) { return __builtin_amdgcn_cvt_pk_f32_fp8(w, false); }
; DI f2_t cvt8hi(unsigned w) { return __builtin_amdgcn_cvt_pk_f32_fp8(w, true); }
; DI void phase11(const Params& p, char* smem, int rep) {
;     ...
;         for (int k = 0; k < 16; ++k) rows[k] = *(const u32x4*)(vb + (size_t)ida[k] * 2048);
; #pragma unroll
;         for (int k = 0; k < 16; ++k) {
;           const f2_t a2 = {aa[k], aa[k]};
; #pragma unroll
;           for (int d = 0; d < 4; ++d) { const unsigned ww = rows[k][d]; o[2 * d] += a2 * cvt8lo(ww); o[2 * d + 1] += a2 * cvt8hi(ww); }
;         }
	v_cvt_pk_f32_fp8_e32 v[232:233], v96
	v_cvt_pk_f32_fp8_sdwa v[234:235], v96 src0_sel:WORD_1
	v_pk_fma_f32 v[216:217], v[54:55], v[232:233], v[216:217] op_sel:[1,0,0]
	v_pk_fma_f32 v[218:219], v[54:55], v[234:235], v[218:219] op_sel:[1,0,0]
	v_cvt_pk_f32_fp8_e32 v[236:237], v97
	v_cvt_pk_f32_fp8_sdwa v[238:239], v97 src0_sel:WORD_1
	v_pk_fma_f32 v[220:221], v[54:55], v[236:237], v[220:221] op_sel:[1,0,0]
	v_pk_fma_f32 v[222:223], v[54:55], v[238:239], v[222:223] op_sel:[1,0,0]
	v_cvt_pk_f32_fp8_e32 v[232:233], v98
	v_cvt_pk_f32_fp8_sdwa v[234:235], v98 src0_sel:WORD_1
	v_pk_fma_f32 v[224:225], v[54:55], v[232:233], v[224:225] op_sel:[1,0,0]
	v_pk_fma_f32 v[226:227], v[54:55], v[234:235], v[226:227] op_sel:[1,0,0]
	v_cvt_pk_f32_fp8_e32 v[236:237], v99
	v_cvt_pk_f32_fp8_sdwa v[238:239], v99 src0_sel:WORD_1
	v_pk_fma_f32 v[228:229], v[54:55], v[236:237], v[228:229] op_sel:[1,0,0]
	v_pk_fma_f32 v[230:231], v[54:55], v[238:239], v[230:231] op_sel:[1,0,0]
	s_waitcnt vmcnt(27)
	v_cvt_pk_f32_fp8_e32 v[232:233], v100
	v_cvt_pk_f32_fp8_sdwa v[234:235], v100 src0_sel:WORD_1
	v_pk_fma_f32 v[216:217], v[56:57], v[232:233], v[216:217] op_sel_hi:[0,1,1]
	v_pk_fma_f32 v[218:219], v[56:57], v[234:235], v[218:219] op_sel_hi:[0,1,1]
	v_cvt_pk_f32_fp8_e32 v[236:237], v101
	v_cvt_pk_f32_fp8_sdwa v[238:239], v101 src0_sel:WORD_1
	v_pk_fma_f32 v[220:221], v[56:57], v[236:237], v[220:221] op_sel_hi:[0,1,1]
	v_pk_fma_f32 v[222:223], v[56:57], v[238:239], v[222:223] op_sel_hi:[0,1,1]
	v_cvt_pk_f32_fp8_e32 v[232:233], v102
	v_cvt_pk_f32_fp8_sdwa v[234:235], v102 src0_sel:WORD_1
	v_pk_fma_f32 v[224:225], v[56:57], v[232:233], v[224:225] op_sel_hi:[0,1,1]
	v_pk_fma_f32 v[226:227], v[56:57], v[234:235], v[226:227] op_sel_hi:[0,1,1]
	v_cvt_pk_f32_fp8_e32 v[236:237], v103
	v_cvt_pk_f32_fp8_sdwa v[238:239], v103 src0_sel:WORD_1
	v_pk_fma_f32 v[228:229], v[56:57], v[236:237], v[228:229] op_sel_hi:[0,1,1]
	v_pk_fma_f32 v[230:231], v[56:57], v[238:239], v[230:231] op_sel_hi:[0,1,1]
	s_waitcnt vmcnt(26)
	v_cvt_pk_f32_fp8_e32 v[232:233], v104
	v_cvt_pk_f32_fp8_sdwa v[234:235], v104 src0_sel:WORD_1
	v_pk_fma_f32 v[216:217], v[56:57], v[232:233], v[216:217] op_sel:[1,0,0]
	v_pk_fma_f32 v[218:219], v[56:57], v[234:235], v[218:219] op_sel:[1,0,0]
	v_cvt_pk_f32_fp8_e32 v[236:237], v105
	v_cvt_pk_f32_fp8_sdwa v[238:239], v105 src0_sel:WORD_1
	v_pk_fma_f32 v[220:221], v[56:57], v[236:237], v[220:221] op_sel:[1,0,0]
	v_pk_fma_f32 v[222:223], v[56:57], v[238:239], v[222:223] op_sel:[1,0,0]
	v_cvt_pk_f32_fp8_e32 v[232:233], v106
	v_cvt_pk_f32_fp8_sdwa v[234:235], v106 src0_sel:WORD_1
	v_pk_fma_f32 v[224:225], v[56:57], v[232:233], v[224:225] op_sel:[1,0,0]
	v_pk_fma_f32 v[226:227], v[56:57], v[234:235], v[226:227] op_sel:[1,0,0]
	v_cvt_pk_f32_fp8_e32 v[236:237], v107
	v_cvt_pk_f32_fp8_sdwa v[238:239], v107 src0_sel:WORD_1
	v_pk_fma_f32 v[228:229], v[56:57], v[236:237], v[228:229] op_sel:[1,0,0]
	v_pk_fma_f32 v[230:231], v[56:57], v[238:239], v[230:231] op_sel:[1,0,0]
	s_waitcnt vmcnt(25)
	v_cvt_pk_f32_fp8_e32 v[232:233], v108
	v_cvt_pk_f32_fp8_sdwa v[234:235], v108 src0_sel:WORD_1
	v_pk_fma_f32 v[216:217], v[58:59], v[232:233], v[216:217] op_sel_hi:[0,1,1]
	v_pk_fma_f32 v[218:219], v[58:59], v[234:235], v[218:219] op_sel_hi:[0,1,1]
	v_cvt_pk_f32_fp8_e32 v[236:237], v109
	v_cvt_pk_f32_fp8_sdwa v[238:239], v109 src0_sel:WORD_1
	v_pk_fma_f32 v[220:221], v[58:59], v[236:237], v[220:221] op_sel_hi:[0,1,1]
	v_pk_fma_f32 v[222:223], v[58:59], v[238:239], v[222:223] op_sel_hi:[0,1,1]
	v_cvt_pk_f32_fp8_e32 v[232:233], v110
	v_cvt_pk_f32_fp8_sdwa v[234:235], v110 src0_sel:WORD_1
	v_pk_fma_f32 v[224:225], v[58:59], v[232:233], v[224:225] op_sel_hi:[0,1,1]
	v_pk_fma_f32 v[226:227], v[58:59], v[234:235], v[226:227] op_sel_hi:[0,1,1]
	v_cvt_pk_f32_fp8_e32 v[236:237], v111
	v_cvt_pk_f32_fp8_sdwa v[238:239], v111 src0_sel:WORD_1
	v_pk_fma_f32 v[228:229], v[58:59], v[236:237], v[228:229] op_sel_hi:[0,1,1]
	v_pk_fma_f32 v[230:231], v[58:59], v[238:239], v[230:231] op_sel_hi:[0,1,1]
	s_waitcnt vmcnt(24)
	v_cvt_pk_f32_fp8_e32 v[232:233], v112
	v_cvt_pk_f32_fp8_sdwa v[234:235], v112 src0_sel:WORD_1
	v_pk_fma_f32 v[216:217], v[58:59], v[232:233], v[216:217] op_sel:[1,0,0]
	v_pk_fma_f32 v[218:219], v[58:59], v[234:235], v[218:219] op_sel:[1,0,0]
	v_cvt_pk_f32_fp8_e32 v[236:237], v113
	v_cvt_pk_f32_fp8_sdwa v[238:239], v113 src0_sel:WORD_1
	v_pk_fma_f32 v[220:221], v[58:59], v[236:237], v[220:221] op_sel:[1,0,0]
	v_pk_fma_f32 v[222:223], v[58:59], v[238:239], v[222:223] op_sel:[1,0,0]
	v_cvt_pk_f32_fp8_e32 v[232:233], v114
	v_cvt_pk_f32_fp8_sdwa v[234:235], v114 src0_sel:WORD_1
	v_pk_fma_f32 v[224:225], v[58:59], v[232:233], v[224:225] op_sel:[1,0,0]
	v_pk_fma_f32 v[226:227], v[58:59], v[234:235], v[226:227] op_sel:[1,0,0]
	v_cvt_pk_f32_fp8_e32 v[236:237], v115
	v_cvt_pk_f32_fp8_sdwa v[238:239], v115 src0_sel:WORD_1
	v_pk_fma_f32 v[228:229], v[58:59], v[236:237], v[228:229] op_sel:[1,0,0]
	v_pk_fma_f32 v[230:231], v[58:59], v[238:239], v[230:231] op_sel:[1,0,0]
	s_waitcnt vmcnt(23)
	v_cvt_pk_f32_fp8_e32 v[232:233], v116
	v_cvt_pk_f32_fp8_sdwa v[234:235], v116 src0_sel:WORD_1
	v_pk_fma_f32 v[216:217], v[60:61], v[232:233], v[216:217] op_sel_hi:[0,1,1]
	v_pk_fma_f32 v[218:219], v[60:61], v[234:235], v[218:219] op_sel_hi:[0,1,1]
	v_cvt_pk_f32_fp8_e32 v[236:237], v117
	v_cvt_pk_f32_fp8_sdwa v[238:239], v117 src0_sel:WORD_1
	v_pk_fma_f32 v[220:221], v[60:61], v[236:237], v[220:221] op_sel_hi:[0,1,1]
	v_pk_fma_f32 v[222:223], v[60:61], v[238:239], v[222:223] op_sel_hi:[0,1,1]
	v_cvt_pk_f32_fp8_e32 v[232:233], v118
	v_cvt_pk_f32_fp8_sdwa v[234:235], v118 src0_sel:WORD_1
	v_pk_fma_f32 v[224:225], v[60:61], v[232:233], v[224:225] op_sel_hi:[0,1,1]
	v_pk_fma_f32 v[226:227], v[60:61], v[234:235], v[226:227] op_sel_hi:[0,1,1]
	v_cvt_pk_f32_fp8_e32 v[236:237], v119
	v_cvt_pk_f32_fp8_sdwa v[238:239], v119 src0_sel:WORD_1
	v_pk_fma_f32 v[228:229], v[60:61], v[236:237], v[228:229] op_sel_hi:[0,1,1]
	v_pk_fma_f32 v[230:231], v[60:61], v[238:239], v[230:231] op_sel_hi:[0,1,1]
	s_waitcnt vmcnt(22)
; DI f2_t cvt8lo(unsigned w) { return __builtin_amdgcn_cvt_pk_f32_fp8(w, false); }
; DI f2_t cvt8hi(unsigned w) { return __builtin_amdgcn_cvt_pk_f32_fp8(w, true); }
; DI void phase11(const Params& p, char* smem, int rep) {
;     ...
;         for (int k = 0; k < 16; ++k) rows[k] = *(const u32x4*)(vb + (size_t)ida[k] * 2048);
; #pragma unroll
;         for (int k = 0; k < 16; ++k) {
;           const f2_t a2 = {aa[k], aa[k]};
; #pragma unroll
;           for (int d = 0; d < 4; ++d) { const unsigned ww = rows[k][d]; o[2 * d] += a2 * cvt8lo(ww); o[2 * d + 1] += a2 * cvt8hi(ww); }
;         }
	v_cvt_pk_f32_fp8_e32 v[232:233], v120
	v_cvt_pk_f32_fp8_sdwa v[234:235], v120 src0_sel:WORD_1
	v_pk_fma_f32 v[216:217], v[60:61], v[232:233], v[216:217] op_sel:[1,0,0]
	v_pk_fma_f32 v[218:219], v[60:61], v[234:235], v[218:219] op_sel:[1,0,0]
	v_cvt_pk_f32_fp8_e32 v[236:237], v121
	v_cvt_pk_f32_fp8_sdwa v[238:239], v121 src0_sel:WORD_1
	v_pk_fma_f32 v[220:221], v[60:61], v[236:237], v[220:221] op_sel:[1,0,0]
	v_pk_fma_f32 v[222:223], v[60:61], v[238:239], v[222:223] op_sel:[1,0,0]
	v_cvt_pk_f32_fp8_e32 v[232:233], v122
	v_cvt_pk_f32_fp8_sdwa v[234:235], v122 src0_sel:WORD_1
	v_pk_fma_f32 v[224:225], v[60:61], v[232:233], v[224:225] op_sel:[1,0,0]
	v_pk_fma_f32 v[226:227], v[60:61], v[234:235], v[226:227] op_sel:[1,0,0]
	v_cvt_pk_f32_fp8_e32 v[236:237], v123
	v_cvt_pk_f32_fp8_sdwa v[238:239], v123 src0_sel:WORD_1
	v_pk_fma_f32 v[228:229], v[60:61], v[236:237], v[228:229] op_sel:[1,0,0]
	v_pk_fma_f32 v[230:231], v[60:61], v[238:239], v[230:231] op_sel:[1,0,0]
	s_waitcnt vmcnt(21)
	v_cvt_pk_f32_fp8_e32 v[232:233], v124
	v_cvt_pk_f32_fp8_sdwa v[234:235], v124 src0_sel:WORD_1
	v_pk_fma_f32 v[216:217], v[62:63], v[232:233], v[216:217] op_sel_hi:[0,1,1]
	v_pk_fma_f32 v[218:219], v[62:63], v[234:235], v[218:219] op_sel_hi:[0,1,1]
	v_cvt_pk_f32_fp8_e32 v[236:237], v125
	v_cvt_pk_f32_fp8_sdwa v[238:239], v125 src0_sel:WORD_1
	v_pk_fma_f32 v[220:221], v[62:63], v[236:237], v[220:221] op_sel_hi:[0,1,1]
	v_pk_fma_f32 v[222:223], v[62:63], v[238:239], v[222:223] op_sel_hi:[0,1,1]
	v_cvt_pk_f32_fp8_e32 v[232:233], v126
	v_cvt_pk_f32_fp8_sdwa v[234:235], v126 src0_sel:WORD_1
	v_pk_fma_f32 v[224:225], v[62:63], v[232:233], v[224:225] op_sel_hi:[0,1,1]
	v_pk_fma_f32 v[226:227], v[62:63], v[234:235], v[226:227] op_sel_hi:[0,1,1]
	v_cvt_pk_f32_fp8_e32 v[236:237], v127
	v_cvt_pk_f32_fp8_sdwa v[238:239], v127 src0_sel:WORD_1
	v_pk_fma_f32 v[228:229], v[62:63], v[236:237], v[228:229] op_sel_hi:[0,1,1]
	v_pk_fma_f32 v[230:231], v[62:63], v[238:239], v[230:231] op_sel_hi:[0,1,1]
	s_waitcnt vmcnt(20)
	v_cvt_pk_f32_fp8_e32 v[232:233], v128
	v_cvt_pk_f32_fp8_sdwa v[234:235], v128 src0_sel:WORD_1
	v_pk_fma_f32 v[216:217], v[62:63], v[232:233], v[216:217] op_sel:[1,0,0]
	v_pk_fma_f32 v[218:219], v[62:63], v[234:235], v[218:219] op_sel:[1,0,0]
	v_cvt_pk_f32_fp8_e32 v[236:237], v129
	v_cvt_pk_f32_fp8_sdwa v[238:239], v129 src0_sel:WORD_1
	v_pk_fma_f32 v[220:221], v[62:63], v[236:237], v[220:221] op_sel:[1,0,0]
	v_pk_fma_f32 v[222:223], v[62:63], v[238:239], v[222:223] op_sel:[1,0,0]
	v_cvt_pk_f32_fp8_e32 v[232:233], v130
	v_cvt_pk_f32_fp8_sdwa v[234:235], v130 src0_sel:WORD_1
	v_pk_fma_f32 v[224:225], v[62:63], v[232:233], v[224:225] op_sel:[1,0,0]
	v_pk_fma_f32 v[226:227], v[62:63], v[234:235], v[226:227] op_sel:[1,0,0]
	v_cvt_pk_f32_fp8_e32 v[236:237], v131
	v_cvt_pk_f32_fp8_sdwa v[238:239], v131 src0_sel:WORD_1
	v_pk_fma_f32 v[228:229], v[62:63], v[236:237], v[228:229] op_sel:[1,0,0]
	v_pk_fma_f32 v[230:231], v[62:63], v[238:239], v[230:231] op_sel:[1,0,0]
	s_waitcnt vmcnt(19)
	v_cvt_pk_f32_fp8_e32 v[232:233], v132
	v_cvt_pk_f32_fp8_sdwa v[234:235], v132 src0_sel:WORD_1
	v_pk_fma_f32 v[216:217], v[64:65], v[232:233], v[216:217] op_sel_hi:[0,1,1]
	v_pk_fma_f32 v[218:219], v[64:65], v[234:235], v[218:219] op_sel_hi:[0,1,1]
	v_cvt_pk_f32_fp8_e32 v[236:237], v133
	v_cvt_pk_f32_fp8_sdwa v[238:239], v133 src0_sel:WORD_1
	v_pk_fma_f32 v[220:221], v[64:65], v[236:237], v[220:221] op_sel_hi:[0,1,1]
	v_pk_fma_f32 v[222:223], v[64:65], v[238:239], v[222:223] op_sel_hi:[0,1,1]
	v_cvt_pk_f32_fp8_e32 v[232:233], v134
	v_cvt_pk_f32_fp8_sdwa v[234:235], v134 src0_sel:WORD_1
	v_pk_fma_f32 v[224:225], v[64:65], v[232:233], v[224:225] op_sel_hi:[0,1,1]
	v_pk_fma_f32 v[226:227], v[64:65], v[234:235], v[226:227] op_sel_hi:[0,1,1]
	v_cvt_pk_f32_fp8_e32 v[236:237], v135
	v_cvt_pk_f32_fp8_sdwa v[238:239], v135 src0_sel:WORD_1
	v_pk_fma_f32 v[228:229], v[64:65], v[236:237], v[228:229] op_sel_hi:[0,1,1]
	v_pk_fma_f32 v[230:231], v[64:65], v[238:239], v[230:231] op_sel_hi:[0,1,1]
	s_waitcnt vmcnt(18)
	v_cvt_pk_f32_fp8_e32 v[232:233], v136
	v_cvt_pk_f32_fp8_sdwa v[234:235], v136 src0_sel:WORD_1
	v_pk_fma_f32 v[216:217], v[64:65], v[232:233], v[216:217] op_sel:[1,0,0]
	v_pk_fma_f32 v[218:219], v[64:65], v[234:235], v[218:219] op_sel:[1,0,0]
	v_cvt_pk_f32_fp8_e32 v[236:237], v137
	v_cvt_pk_f32_fp8_sdwa v[238:239], v137 src0_sel:WORD_1
	v_pk_fma_f32 v[220:221], v[64:65], v[236:237], v[220:221] op_sel:[1,0,0]
	v_pk_fma_f32 v[222:223], v[64:65], v[238:239], v[222:223] op_sel:[1,0,0]
	v_cvt_pk_f32_fp8_e32 v[232:233], v138
	v_cvt_pk_f32_fp8_sdwa v[234:235], v138 src0_sel:WORD_1
	v_pk_fma_f32 v[224:225], v[64:65], v[232:233], v[224:225] op_sel:[1,0,0]
	v_pk_fma_f32 v[226:227], v[64:65], v[234:235], v[226:227] op_sel:[1,0,0]
	v_cvt_pk_f32_fp8_e32 v[236:237], v139
	v_cvt_pk_f32_fp8_sdwa v[238:239], v139 src0_sel:WORD_1
	v_pk_fma_f32 v[228:229], v[64:65], v[236:237], v[228:229] op_sel:[1,0,0]
	v_pk_fma_f32 v[230:231], v[64:65], v[238:239], v[230:231] op_sel:[1,0,0]
	s_waitcnt vmcnt(17)
	v_cvt_pk_f32_fp8_e32 v[232:233], v140
	v_cvt_pk_f32_fp8_sdwa v[234:235], v140 src0_sel:WORD_1
	v_pk_fma_f32 v[216:217], v[66:67], v[232:233], v[216:217] op_sel_hi:[0,1,1]
	v_pk_fma_f32 v[218:219], v[66:67], v[234:235], v[218:219] op_sel_hi:[0,1,1]
	v_cvt_pk_f32_fp8_e32 v[236:237], v141
	v_cvt_pk_f32_fp8_sdwa v[238:239], v141 src0_sel:WORD_1
	v_pk_fma_f32 v[220:221], v[66:67], v[236:237], v[220:221] op_sel_hi:[0,1,1]
	v_pk_fma_f32 v[222:223], v[66:67], v[238:239], v[222:223] op_sel_hi:[0,1,1]
	v_cvt_pk_f32_fp8_e32 v[232:233], v142
	v_cvt_pk_f32_fp8_sdwa v[234:235], v142 src0_sel:WORD_1
	v_pk_fma_f32 v[224:225], v[66:67], v[232:233], v[224:225] op_sel_hi:[0,1,1]
	v_pk_fma_f32 v[226:227], v[66:67], v[234:235], v[226:227] op_sel_hi:[0,1,1]
	v_cvt_pk_f32_fp8_e32 v[236:237], v143
	v_cvt_pk_f32_fp8_sdwa v[238:239], v143 src0_sel:WORD_1
	v_pk_fma_f32 v[228:229], v[66:67], v[236:237], v[228:229] op_sel_hi:[0,1,1]
	v_pk_fma_f32 v[230:231], v[66:67], v[238:239], v[230:231] op_sel_hi:[0,1,1]
	s_waitcnt vmcnt(16)
; DI f2_t cvt8lo(unsigned w) { return __builtin_amdgcn_cvt_pk_f32_fp8(w, false); }
; DI f2_t cvt8hi(unsigned w) { return __builtin_amdgcn_cvt_pk_f32_fp8(w, true); }
; DI void wave_lds_sync() { asm volatile("s_waitcnt lgkmcnt(0)" ::: "memory"); __builtin_amdgcn_wave_barrier(); }
; DI void phase11(const Params& p, char* smem, int rep) {
;     ...
;       lw[(lane & 3) * 32 + (lane >> 2)] = i0; lw[(lane & 3) * 32 + 16 + (lane >> 2)] = i1;
;       lf[(lane & 3) * 32 + (lane >> 2)] = a0; lf[(lane & 3) * 32 + 16 + (lane >> 2)] = a1;
;       wave_lds_sync();
;       f2_t o[8];
; #pragma unroll
;       for (int i = 0; i < 8; ++i) o[i] = f2_t{0.f, 0.f};
;       const unsigned char* vb = V8 + s * 256 + l15 * 16;
; #pragma unroll
;       for (int batch = 0; batch < 2; ++batch) {
;         int ida[16]; float aa[16];
; #pragma unroll
;         for (int q = 0; q < 4; ++q) {
;           const int4 v = *(const int4*)(lw + g * 32 + batch * 16 + q * 4); ida[q * 4] = v.x; ida[q * 4 + 1] = v.y; ida[q * 4 + 2] = v.z; ida[q * 4 + 3] = v.w;
;           const float4 f = *(const float4*)(lf + g * 32 + batch * 16 + q * 4); aa[q * 4] = f.x; aa[q * 4 + 1] = f.y; aa[q * 4 + 2] = f.z; aa[q * 4 + 3] = f.w;
;         }
;         u32x4 rows[16];
; #pragma unroll
;         for (int k = 0; k < 16; ++k) rows[k] = *(const u32x4*)(vb + (size_t)ida[k] * 2048);
; #pragma unroll
;         for (int k = 0; k < 16; ++k) {
;           const f2_t a2 = {aa[k], aa[k]};
; #pragma unroll
;           for (int d = 0; d < 4; ++d) { const unsigned ww = rows[k][d]; o[2 * d] += a2 * cvt8lo(ww); o[2 * d + 1] += a2 * cvt8hi(ww); }
;         }
	v_cvt_pk_f32_fp8_e32 v[232:233], v144
	v_cvt_pk_f32_fp8_sdwa v[234:235], v144 src0_sel:WORD_1
	v_pk_fma_f32 v[216:217], v[66:67], v[232:233], v[216:217] op_sel:[1,0,0]
	v_pk_fma_f32 v[218:219], v[66:67], v[234:235], v[218:219] op_sel:[1,0,0]
	v_cvt_pk_f32_fp8_e32 v[236:237], v145
	v_cvt_pk_f32_fp8_sdwa v[238:239], v145 src0_sel:WORD_1
	v_pk_fma_f32 v[220:221], v[66:67], v[236:237], v[220:221] op_sel:[1,0,0]
	v_pk_fma_f32 v[222:223], v[66:67], v[238:239], v[222:223] op_sel:[1,0,0]
	v_cvt_pk_f32_fp8_e32 v[232:233], v146
	v_cvt_pk_f32_fp8_sdwa v[234:235], v146 src0_sel:WORD_1
	v_pk_fma_f32 v[224:225], v[66:67], v[232:233], v[224:225] op_sel:[1,0,0]
	v_pk_fma_f32 v[226:227], v[66:67], v[234:235], v[226:227] op_sel:[1,0,0]
	v_cvt_pk_f32_fp8_e32 v[236:237], v147
	v_cvt_pk_f32_fp8_sdwa v[238:239], v147 src0_sel:WORD_1
	v_pk_fma_f32 v[228:229], v[66:67], v[236:237], v[228:229] op_sel:[1,0,0]
	v_pk_fma_f32 v[230:231], v[66:67], v[238:239], v[230:231] op_sel:[1,0,0]
	ds_write2_b32 v5, v10, v11 offset0:4 offset1:20
	ds_write2_b32 v5, v12, v13 offset0:132 offset1:148
	s_waitcnt lgkmcnt(0)
	ds_read_b128 v[20:23], v6 offset:16
	ds_read_b128 v[24:27], v6 offset:32
	ds_read_b128 v[28:31], v6 offset:48
	ds_read_b128 v[32:35], v6 offset:64
	ds_read_b128 v[36:39], v6 offset:80
	ds_read_b128 v[40:43], v6 offset:96
	ds_read_b128 v[44:47], v6 offset:112
	ds_read_b128 v[48:51], v6 offset:128
	s_waitcnt vmcnt(15)
	v_cvt_pk_f32_fp8_e32 v[232:233], v148
	v_cvt_pk_f32_fp8_sdwa v[234:235], v148 src0_sel:WORD_1
	v_pk_fma_f32 v[216:217], v[68:69], v[232:233], v[216:217] op_sel_hi:[0,1,1]
	v_pk_fma_f32 v[218:219], v[68:69], v[234:235], v[218:219] op_sel_hi:[0,1,1]
	v_cvt_pk_f32_fp8_e32 v[236:237], v149
	v_cvt_pk_f32_fp8_sdwa v[238:239], v149 src0_sel:WORD_1
	v_pk_fma_f32 v[220:221], v[68:69], v[236:237], v[220:221] op_sel_hi:[0,1,1]
	v_pk_fma_f32 v[222:223], v[68:69], v[238:239], v[222:223] op_sel_hi:[0,1,1]
	v_cvt_pk_f32_fp8_e32 v[232:233], v150
	v_cvt_pk_f32_fp8_sdwa v[234:235], v150 src0_sel:WORD_1
	v_pk_fma_f32 v[224:225], v[68:69], v[232:233], v[224:225] op_sel_hi:[0,1,1]
	v_pk_fma_f32 v[226:227], v[68:69], v[234:235], v[226:227] op_sel_hi:[0,1,1]
	v_cvt_pk_f32_fp8_e32 v[236:237], v151
	v_cvt_pk_f32_fp8_sdwa v[238:239], v151 src0_sel:WORD_1
	v_pk_fma_f32 v[228:229], v[68:69], v[236:237], v[228:229] op_sel_hi:[0,1,1]
	v_pk_fma_f32 v[230:231], v[68:69], v[238:239], v[230:231] op_sel_hi:[0,1,1]
	s_waitcnt vmcnt(14)
	v_cvt_pk_f32_fp8_e32 v[232:233], v152
	v_cvt_pk_f32_fp8_sdwa v[234:235], v152 src0_sel:WORD_1
	v_pk_fma_f32 v[216:217], v[68:69], v[232:233], v[216:217] op_sel:[1,0,0]
	v_pk_fma_f32 v[218:219], v[68:69], v[234:235], v[218:219] op_sel:[1,0,0]
	v_cvt_pk_f32_fp8_e32 v[236:237], v153
	v_cvt_pk_f32_fp8_sdwa v[238:239], v153 src0_sel:WORD_1
	v_pk_fma_f32 v[220:221], v[68:69], v[236:237], v[220:221] op_sel:[1,0,0]
	v_pk_fma_f32 v[222:223], v[68:69], v[238:239], v[222:223] op_sel:[1,0,0]
	v_cvt_pk_f32_fp8_e32 v[232:233], v154
	v_cvt_pk_f32_fp8_sdwa v[234:235], v154 src0_sel:WORD_1
	v_pk_fma_f32 v[224:225], v[68:69], v[232:233], v[224:225] op_sel:[1,0,0]
	v_pk_fma_f32 v[226:227], v[68:69], v[234:235], v[226:227] op_sel:[1,0,0]
	v_cvt_pk_f32_fp8_e32 v[236:237], v155
	v_cvt_pk_f32_fp8_sdwa v[238:239], v155 src0_sel:WORD_1
	v_pk_fma_f32 v[228:229], v[68:69], v[236:237], v[228:229] op_sel:[1,0,0]
	v_pk_fma_f32 v[230:231], v[68:69], v[238:239], v[230:231] op_sel:[1,0,0]
	s_waitcnt vmcnt(13)
	v_cvt_pk_f32_fp8_e32 v[232:233], v156
	v_cvt_pk_f32_fp8_sdwa v[234:235], v156 src0_sel:WORD_1
	v_pk_fma_f32 v[216:217], v[70:71], v[232:233], v[216:217] op_sel_hi:[0,1,1]
	v_pk_fma_f32 v[218:219], v[70:71], v[234:235], v[218:219] op_sel_hi:[0,1,1]
	v_cvt_pk_f32_fp8_e32 v[236:237], v157
	v_cvt_pk_f32_fp8_sdwa v[238:239], v157 src0_sel:WORD_1
	v_pk_fma_f32 v[220:221], v[70:71], v[236:237], v[220:221] op_sel_hi:[0,1,1]
	v_pk_fma_f32 v[222:223], v[70:71], v[238:239], v[222:223] op_sel_hi:[0,1,1]
	v_cvt_pk_f32_fp8_e32 v[232:233], v158
	v_cvt_pk_f32_fp8_sdwa v[234:235], v158 src0_sel:WORD_1
	v_pk_fma_f32 v[224:225], v[70:71], v[232:233], v[224:225] op_sel_hi:[0,1,1]
	v_pk_fma_f32 v[226:227], v[70:71], v[234:235], v[226:227] op_sel_hi:[0,1,1]
	v_cvt_pk_f32_fp8_e32 v[236:237], v159
	v_cvt_pk_f32_fp8_sdwa v[238:239], v159 src0_sel:WORD_1
	v_pk_fma_f32 v[228:229], v[70:71], v[236:237], v[228:229] op_sel_hi:[0,1,1]
	v_pk_fma_f32 v[230:231], v[70:71], v[238:239], v[230:231] op_sel_hi:[0,1,1]
	s_waitcnt vmcnt(12)
	v_cvt_pk_f32_fp8_e32 v[232:233], v160
	v_cvt_pk_f32_fp8_sdwa v[234:235], v160 src0_sel:WORD_1
	v_pk_fma_f32 v[216:217], v[70:71], v[232:233], v[216:217] op_sel:[1,0,0]
	v_pk_fma_f32 v[218:219], v[70:71], v[234:235], v[218:219] op_sel:[1,0,0]
	v_cvt_pk_f32_fp8_e32 v[236:237], v161
	v_cvt_pk_f32_fp8_sdwa v[238:239], v161 src0_sel:WORD_1
	v_pk_fma_f32 v[220:221], v[70:71], v[236:237], v[220:221] op_sel:[1,0,0]
	v_pk_fma_f32 v[222:223], v[70:71], v[238:239], v[222:223] op_sel:[1,0,0]
	v_cvt_pk_f32_fp8_e32 v[232:233], v162
	v_cvt_pk_f32_fp8_sdwa v[234:235], v162 src0_sel:WORD_1
	v_pk_fma_f32 v[224:225], v[70:71], v[232:233], v[224:225] op_sel:[1,0,0]
	v_pk_fma_f32 v[226:227], v[70:71], v[234:235], v[226:227] op_sel:[1,0,0]
	v_cvt_pk_f32_fp8_e32 v[236:237], v163
	v_cvt_pk_f32_fp8_sdwa v[238:239], v163 src0_sel:WORD_1
	v_pk_fma_f32 v[228:229], v[70:71], v[236:237], v[228:229] op_sel:[1,0,0]
	v_pk_fma_f32 v[230:231], v[70:71], v[238:239], v[230:231] op_sel:[1,0,0]
	s_waitcnt vmcnt(11)
; DI f2_t cvt8lo(unsigned w) { return __builtin_amdgcn_cvt_pk_f32_fp8(w, false); }
; DI f2_t cvt8hi(unsigned w) { return __builtin_amdgcn_cvt_pk_f32_fp8(w, true); }
; DI void phase11(const Params& p, char* smem, int rep) {
;     ...
;         for (int k = 0; k < 16; ++k) rows[k] = *(const u32x4*)(vb + (size_t)ida[k] * 2048);
; #pragma unroll
;         for (int k = 0; k < 16; ++k) {
;           const f2_t a2 = {aa[k], aa[k]};
; #pragma unroll
;           for (int d = 0; d < 4; ++d) { const unsigned ww = rows[k][d]; o[2 * d] += a2 * cvt8lo(ww); o[2 * d + 1] += a2 * cvt8hi(ww); }
;         }
	v_cvt_pk_f32_fp8_e32 v[232:233], v164
	v_cvt_pk_f32_fp8_sdwa v[234:235], v164 src0_sel:WORD_1
	v_pk_fma_f32 v[216:217], v[72:73], v[232:233], v[216:217] op_sel_hi:[0,1,1]
	v_pk_fma_f32 v[218:219], v[72:73], v[234:235], v[218:219] op_sel_hi:[0,1,1]
	v_cvt_pk_f32_fp8_e32 v[236:237], v165
	v_cvt_pk_f32_fp8_sdwa v[238:239], v165 src0_sel:WORD_1
	v_pk_fma_f32 v[220:221], v[72:73], v[236:237], v[220:221] op_sel_hi:[0,1,1]
	v_pk_fma_f32 v[222:223], v[72:73], v[238:239], v[222:223] op_sel_hi:[0,1,1]
	v_cvt_pk_f32_fp8_e32 v[232:233], v166
	v_cvt_pk_f32_fp8_sdwa v[234:235], v166 src0_sel:WORD_1
	v_pk_fma_f32 v[224:225], v[72:73], v[232:233], v[224:225] op_sel_hi:[0,1,1]
	v_pk_fma_f32 v[226:227], v[72:73], v[234:235], v[226:227] op_sel_hi:[0,1,1]
	v_cvt_pk_f32_fp8_e32 v[236:237], v167
	v_cvt_pk_f32_fp8_sdwa v[238:239], v167 src0_sel:WORD_1
	v_pk_fma_f32 v[228:229], v[72:73], v[236:237], v[228:229] op_sel_hi:[0,1,1]
	v_pk_fma_f32 v[230:231], v[72:73], v[238:239], v[230:231] op_sel_hi:[0,1,1]
	s_waitcnt vmcnt(10)
	v_cvt_pk_f32_fp8_e32 v[232:233], v168
	v_cvt_pk_f32_fp8_sdwa v[234:235], v168 src0_sel:WORD_1
	v_pk_fma_f32 v[216:217], v[72:73], v[232:233], v[216:217] op_sel:[1,0,0]
	v_pk_fma_f32 v[218:219], v[72:73], v[234:235], v[218:219] op_sel:[1,0,0]
	v_cvt_pk_f32_fp8_e32 v[236:237], v169
	v_cvt_pk_f32_fp8_sdwa v[238:239], v169 src0_sel:WORD_1
	v_pk_fma_f32 v[220:221], v[72:73], v[236:237], v[220:221] op_sel:[1,0,0]
	v_pk_fma_f32 v[222:223], v[72:73], v[238:239], v[222:223] op_sel:[1,0,0]
	v_cvt_pk_f32_fp8_e32 v[232:233], v170
	v_cvt_pk_f32_fp8_sdwa v[234:235], v170 src0_sel:WORD_1
	v_pk_fma_f32 v[224:225], v[72:73], v[232:233], v[224:225] op_sel:[1,0,0]
	v_pk_fma_f32 v[226:227], v[72:73], v[234:235], v[226:227] op_sel:[1,0,0]
	v_cvt_pk_f32_fp8_e32 v[236:237], v171
	v_cvt_pk_f32_fp8_sdwa v[238:239], v171 src0_sel:WORD_1
	v_pk_fma_f32 v[228:229], v[72:73], v[236:237], v[228:229] op_sel:[1,0,0]
	v_pk_fma_f32 v[230:231], v[72:73], v[238:239], v[230:231] op_sel:[1,0,0]
	s_waitcnt vmcnt(9)
	v_cvt_pk_f32_fp8_e32 v[232:233], v172
	v_cvt_pk_f32_fp8_sdwa v[234:235], v172 src0_sel:WORD_1
	v_pk_fma_f32 v[216:217], v[74:75], v[232:233], v[216:217] op_sel_hi:[0,1,1]
	v_pk_fma_f32 v[218:219], v[74:75], v[234:235], v[218:219] op_sel_hi:[0,1,1]
	v_cvt_pk_f32_fp8_e32 v[236:237], v173
	v_cvt_pk_f32_fp8_sdwa v[238:239], v173 src0_sel:WORD_1
	v_pk_fma_f32 v[220:221], v[74:75], v[236:237], v[220:221] op_sel_hi:[0,1,1]
	v_pk_fma_f32 v[222:223], v[74:75], v[238:239], v[222:223] op_sel_hi:[0,1,1]
	v_cvt_pk_f32_fp8_e32 v[232:233], v174
	v_cvt_pk_f32_fp8_sdwa v[234:235], v174 src0_sel:WORD_1
	v_pk_fma_f32 v[224:225], v[74:75], v[232:233], v[224:225] op_sel_hi:[0,1,1]
	v_pk_fma_f32 v[226:227], v[74:75], v[234:235], v[226:227] op_sel_hi:[0,1,1]
	v_cvt_pk_f32_fp8_e32 v[236:237], v175
	v_cvt_pk_f32_fp8_sdwa v[238:239], v175 src0_sel:WORD_1
	v_pk_fma_f32 v[228:229], v[74:75], v[236:237], v[228:229] op_sel_hi:[0,1,1]
	v_pk_fma_f32 v[230:231], v[74:75], v[238:239], v[230:231] op_sel_hi:[0,1,1]
	s_waitcnt vmcnt(8)
	v_cvt_pk_f32_fp8_e32 v[232:233], v176
	v_cvt_pk_f32_fp8_sdwa v[234:235], v176 src0_sel:WORD_1
	v_pk_fma_f32 v[216:217], v[74:75], v[232:233], v[216:217] op_sel:[1,0,0]
	v_pk_fma_f32 v[218:219], v[74:75], v[234:235], v[218:219] op_sel:[1,0,0]
	v_cvt_pk_f32_fp8_e32 v[236:237], v177
	v_cvt_pk_f32_fp8_sdwa v[238:239], v177 src0_sel:WORD_1
	v_pk_fma_f32 v[220:221], v[74:75], v[236:237], v[220:221] op_sel:[1,0,0]
	v_pk_fma_f32 v[222:223], v[74:75], v[238:239], v[222:223] op_sel:[1,0,0]
	v_cvt_pk_f32_fp8_e32 v[232:233], v178
	v_cvt_pk_f32_fp8_sdwa v[234:235], v178 src0_sel:WORD_1
	v_pk_fma_f32 v[224:225], v[74:75], v[232:233], v[224:225] op_sel:[1,0,0]
	v_pk_fma_f32 v[226:227], v[74:75], v[234:235], v[226:227] op_sel:[1,0,0]
	v_cvt_pk_f32_fp8_e32 v[236:237], v179
	v_cvt_pk_f32_fp8_sdwa v[238:239], v179 src0_sel:WORD_1
	v_pk_fma_f32 v[228:229], v[74:75], v[236:237], v[228:229] op_sel:[1,0,0]
	v_pk_fma_f32 v[230:231], v[74:75], v[238:239], v[230:231] op_sel:[1,0,0]
	s_waitcnt vmcnt(7)
	v_cvt_pk_f32_fp8_e32 v[232:233], v180
	v_cvt_pk_f32_fp8_sdwa v[234:235], v180 src0_sel:WORD_1
	v_pk_fma_f32 v[216:217], v[76:77], v[232:233], v[216:217] op_sel_hi:[0,1,1]
	v_pk_fma_f32 v[218:219], v[76:77], v[234:235], v[218:219] op_sel_hi:[0,1,1]
	v_cvt_pk_f32_fp8_e32 v[236:237], v181
	v_cvt_pk_f32_fp8_sdwa v[238:239], v181 src0_sel:WORD_1
	v_pk_fma_f32 v[220:221], v[76:77], v[236:237], v[220:221] op_sel_hi:[0,1,1]
	v_pk_fma_f32 v[222:223], v[76:77], v[238:239], v[222:223] op_sel_hi:[0,1,1]
	v_cvt_pk_f32_fp8_e32 v[232:233], v182
	v_cvt_pk_f32_fp8_sdwa v[234:235], v182 src0_sel:WORD_1
	v_pk_fma_f32 v[224:225], v[76:77], v[232:233], v[224:225] op_sel_hi:[0,1,1]
	v_pk_fma_f32 v[226:227], v[76:77], v[234:235], v[226:227] op_sel_hi:[0,1,1]
	v_cvt_pk_f32_fp8_e32 v[236:237], v183
	v_cvt_pk_f32_fp8_sdwa v[238:239], v183 src0_sel:WORD_1
	v_pk_fma_f32 v[228:229], v[76:77], v[236:237], v[228:229] op_sel_hi:[0,1,1]
	v_pk_fma_f32 v[230:231], v[76:77], v[238:239], v[230:231] op_sel_hi:[0,1,1]
	s_waitcnt vmcnt(6)
	v_cvt_pk_f32_fp8_e32 v[232:233], v184
	v_cvt_pk_f32_fp8_sdwa v[234:235], v184 src0_sel:WORD_1
	v_pk_fma_f32 v[216:217], v[76:77], v[232:233], v[216:217] op_sel:[1,0,0]
	v_pk_fma_f32 v[218:219], v[76:77], v[234:235], v[218:219] op_sel:[1,0,0]
	v_cvt_pk_f32_fp8_e32 v[236:237], v185
	v_cvt_pk_f32_fp8_sdwa v[238:239], v185 src0_sel:WORD_1
	v_pk_fma_f32 v[220:221], v[76:77], v[236:237], v[220:221] op_sel:[1,0,0]
	v_pk_fma_f32 v[222:223], v[76:77], v[238:239], v[222:223] op_sel:[1,0,0]
	v_cvt_pk_f32_fp8_e32 v[232:233], v186
	v_cvt_pk_f32_fp8_sdwa v[234:235], v186 src0_sel:WORD_1
	v_pk_fma_f32 v[224:225], v[76:77], v[232:233], v[224:225] op_sel:[1,0,0]
	v_pk_fma_f32 v[226:227], v[76:77], v[234:235], v[226:227] op_sel:[1,0,0]
	v_cvt_pk_f32_fp8_e32 v[236:237], v187
	v_cvt_pk_f32_fp8_sdwa v[238:239], v187 src0_sel:WORD_1
	v_pk_fma_f32 v[228:229], v[76:77], v[236:237], v[228:229] op_sel:[1,0,0]
	v_pk_fma_f32 v[230:231], v[76:77], v[238:239], v[230:231] op_sel:[1,0,0]
	s_waitcnt vmcnt(5)
; DI f2_t cvt8lo(unsigned w) { return __builtin_amdgcn_cvt_pk_f32_fp8(w, false); }
; DI f2_t cvt8hi(unsigned w) { return __builtin_amdgcn_cvt_pk_f32_fp8(w, true); }
; DI void phase11(const Params& p, char* smem, int rep) {
;     ...
;         for (int k = 0; k < 16; ++k) rows[k] = *(const u32x4*)(vb + (size_t)ida[k] * 2048);
; #pragma unroll
;         for (int k = 0; k < 16; ++k) {
;           const f2_t a2 = {aa[k], aa[k]};
; #pragma unroll
;           for (int d = 0; d < 4; ++d) { const unsigned ww = rows[k][d]; o[2 * d] += a2 * cvt8lo(ww); o[2 * d + 1] += a2 * cvt8hi(ww); }
;         }
	v_cvt_pk_f32_fp8_e32 v[232:233], v190
	v_cvt_pk_f32_fp8_sdwa v[234:235], v190 src0_sel:WORD_1
	v_pk_fma_f32 v[216:217], v[78:79], v[232:233], v[216:217] op_sel_hi:[0,1,1]
	v_pk_fma_f32 v[218:219], v[78:79], v[234:235], v[218:219] op_sel_hi:[0,1,1]
	v_cvt_pk_f32_fp8_e32 v[236:237], v191
	v_cvt_pk_f32_fp8_sdwa v[238:239], v191 src0_sel:WORD_1
	v_pk_fma_f32 v[220:221], v[78:79], v[236:237], v[220:221] op_sel_hi:[0,1,1]
	v_pk_fma_f32 v[222:223], v[78:79], v[238:239], v[222:223] op_sel_hi:[0,1,1]
	v_cvt_pk_f32_fp8_e32 v[232:233], v192
	v_cvt_pk_f32_fp8_sdwa v[234:235], v192 src0_sel:WORD_1
	v_pk_fma_f32 v[224:225], v[78:79], v[232:233], v[224:225] op_sel_hi:[0,1,1]
	v_pk_fma_f32 v[226:227], v[78:79], v[234:235], v[226:227] op_sel_hi:[0,1,1]
	v_cvt_pk_f32_fp8_e32 v[236:237], v193
	v_cvt_pk_f32_fp8_sdwa v[238:239], v193 src0_sel:WORD_1
	v_pk_fma_f32 v[228:229], v[78:79], v[236:237], v[228:229] op_sel_hi:[0,1,1]
	v_pk_fma_f32 v[230:231], v[78:79], v[238:239], v[230:231] op_sel_hi:[0,1,1]
	s_waitcnt vmcnt(4)
	v_cvt_pk_f32_fp8_e32 v[232:233], v194
	v_cvt_pk_f32_fp8_sdwa v[234:235], v194 src0_sel:WORD_1
	v_pk_fma_f32 v[216:217], v[78:79], v[232:233], v[216:217] op_sel:[1,0,0]
	v_pk_fma_f32 v[218:219], v[78:79], v[234:235], v[218:219] op_sel:[1,0,0]
	v_cvt_pk_f32_fp8_e32 v[236:237], v195
	v_cvt_pk_f32_fp8_sdwa v[238:239], v195 src0_sel:WORD_1
	v_pk_fma_f32 v[220:221], v[78:79], v[236:237], v[220:221] op_sel:[1,0,0]
	v_pk_fma_f32 v[222:223], v[78:79], v[238:239], v[222:223] op_sel:[1,0,0]
	v_cvt_pk_f32_fp8_e32 v[232:233], v196
	v_cvt_pk_f32_fp8_sdwa v[234:235], v196 src0_sel:WORD_1
	v_pk_fma_f32 v[224:225], v[78:79], v[232:233], v[224:225] op_sel:[1,0,0]
	v_pk_fma_f32 v[226:227], v[78:79], v[234:235], v[226:227] op_sel:[1,0,0]
	v_cvt_pk_f32_fp8_e32 v[236:237], v197
	v_cvt_pk_f32_fp8_sdwa v[238:239], v197 src0_sel:WORD_1
	v_pk_fma_f32 v[228:229], v[78:79], v[236:237], v[228:229] op_sel:[1,0,0]
	v_pk_fma_f32 v[230:231], v[78:79], v[238:239], v[230:231] op_sel:[1,0,0]
	s_waitcnt vmcnt(3)
	v_cvt_pk_f32_fp8_e32 v[232:233], v198
	v_cvt_pk_f32_fp8_sdwa v[234:235], v198 src0_sel:WORD_1
	v_pk_fma_f32 v[216:217], v[80:81], v[232:233], v[216:217] op_sel_hi:[0,1,1]
	v_pk_fma_f32 v[218:219], v[80:81], v[234:235], v[218:219] op_sel_hi:[0,1,1]
	v_cvt_pk_f32_fp8_e32 v[236:237], v199
	v_cvt_pk_f32_fp8_sdwa v[238:239], v199 src0_sel:WORD_1
	v_pk_fma_f32 v[220:221], v[80:81], v[236:237], v[220:221] op_sel_hi:[0,1,1]
	v_pk_fma_f32 v[222:223], v[80:81], v[238:239], v[222:223] op_sel_hi:[0,1,1]
	v_cvt_pk_f32_fp8_e32 v[232:233], v200
	v_cvt_pk_f32_fp8_sdwa v[234:235], v200 src0_sel:WORD_1
	v_pk_fma_f32 v[224:225], v[80:81], v[232:233], v[224:225] op_sel_hi:[0,1,1]
	v_pk_fma_f32 v[226:227], v[80:81], v[234:235], v[226:227] op_sel_hi:[0,1,1]
	v_cvt_pk_f32_fp8_e32 v[236:237], v201
	v_cvt_pk_f32_fp8_sdwa v[238:239], v201 src0_sel:WORD_1
	v_pk_fma_f32 v[228:229], v[80:81], v[236:237], v[228:229] op_sel_hi:[0,1,1]
	v_pk_fma_f32 v[230:231], v[80:81], v[238:239], v[230:231] op_sel_hi:[0,1,1]
	s_waitcnt vmcnt(2)
	v_cvt_pk_f32_fp8_e32 v[232:233], v202
	v_cvt_pk_f32_fp8_sdwa v[234:235], v202 src0_sel:WORD_1
	v_pk_fma_f32 v[216:217], v[80:81], v[232:233], v[216:217] op_sel:[1,0,0]
	v_pk_fma_f32 v[218:219], v[80:81], v[234:235], v[218:219] op_sel:[1,0,0]
	v_cvt_pk_f32_fp8_e32 v[236:237], v203
	v_cvt_pk_f32_fp8_sdwa v[238:239], v203 src0_sel:WORD_1
	v_pk_fma_f32 v[220:221], v[80:81], v[236:237], v[220:221] op_sel:[1,0,0]
	v_pk_fma_f32 v[222:223], v[80:81], v[238:239], v[222:223] op_sel:[1,0,0]
	v_cvt_pk_f32_fp8_e32 v[232:233], v204
	v_cvt_pk_f32_fp8_sdwa v[234:235], v204 src0_sel:WORD_1
	v_pk_fma_f32 v[224:225], v[80:81], v[232:233], v[224:225] op_sel:[1,0,0]
	v_pk_fma_f32 v[226:227], v[80:81], v[234:235], v[226:227] op_sel:[1,0,0]
	v_cvt_pk_f32_fp8_e32 v[236:237], v205
	v_cvt_pk_f32_fp8_sdwa v[238:239], v205 src0_sel:WORD_1
	v_pk_fma_f32 v[228:229], v[80:81], v[236:237], v[228:229] op_sel:[1,0,0]
	v_pk_fma_f32 v[230:231], v[80:81], v[238:239], v[230:231] op_sel:[1,0,0]
	s_waitcnt vmcnt(1)
	v_cvt_pk_f32_fp8_e32 v[232:233], v206
	v_cvt_pk_f32_fp8_sdwa v[234:235], v206 src0_sel:WORD_1
	v_pk_fma_f32 v[216:217], v[82:83], v[232:233], v[216:217] op_sel_hi:[0,1,1]
	v_pk_fma_f32 v[218:219], v[82:83], v[234:235], v[218:219] op_sel_hi:[0,1,1]
	v_cvt_pk_f32_fp8_e32 v[236:237], v207
	v_cvt_pk_f32_fp8_sdwa v[238:239], v207 src0_sel:WORD_1
	v_pk_fma_f32 v[220:221], v[82:83], v[236:237], v[220:221] op_sel_hi:[0,1,1]
	v_pk_fma_f32 v[222:223], v[82:83], v[238:239], v[222:223] op_sel_hi:[0,1,1]
	v_cvt_pk_f32_fp8_e32 v[232:233], v208
	v_cvt_pk_f32_fp8_sdwa v[234:235], v208 src0_sel:WORD_1
	v_pk_fma_f32 v[224:225], v[82:83], v[232:233], v[224:225] op_sel_hi:[0,1,1]
	v_pk_fma_f32 v[226:227], v[82:83], v[234:235], v[226:227] op_sel_hi:[0,1,1]
	v_cvt_pk_f32_fp8_e32 v[236:237], v209
	v_cvt_pk_f32_fp8_sdwa v[238:239], v209 src0_sel:WORD_1
	v_pk_fma_f32 v[228:229], v[82:83], v[236:237], v[228:229] op_sel_hi:[0,1,1]
	v_pk_fma_f32 v[230:231], v[82:83], v[238:239], v[230:231] op_sel_hi:[0,1,1]
	s_waitcnt vmcnt(0)
; DI unsigned pk2(float a, float b) { f2_t v = {a, b}; bf2_t r = __builtin_convertvector(v, bf2_t); return __builtin_bit_cast(unsigned, r); }
; DI f2_t cvt8lo(unsigned w) { return __builtin_amdgcn_cvt_pk_f32_fp8(w, false); }
; DI f2_t cvt8hi(unsigned w) { return __builtin_amdgcn_cvt_pk_f32_fp8(w, true); }
; DI void phase11(const Params& p, char* smem, int rep) {
;     ...
;     for (int t = 0; t < 4; ++t) {
;       const int tok = __builtin_amdgcn_readfirstlane(c * 16 + w * 4 + t);
;       const int i0 = IDS[(size_t)tok * 128 + lane], i1 = IDS[(size_t)tok * 128 + 64 + lane];
;       const float a0 = ACT[(size_t)tok * 128 + lane], a1 = ACT[(size_t)tok * 128 + 64 + lane];
;       wave_lds_sync();
;       lw[(lane & 3) * 32 + (lane >> 2)] = i0; lw[(lane & 3) * 32 + 16 + (lane >> 2)] = i1;
;       lf[(lane & 3) * 32 + (lane >> 2)] = a0; lf[(lane & 3) * 32 + 16 + (lane >> 2)] = a1;
;       wave_lds_sync();
;     ...
; #pragma unroll
;         for (int q = 0; q < 4; ++q) {
;           const int4 v = *(const int4*)(lw + g * 32 + batch * 16 + q * 4); ida[q * 4] = v.x; ida[q * 4 + 1] = v.y; ida[q * 4 + 2] = v.z; ida[q * 4 + 3] = v.w;
;           const float4 f = *(const float4*)(lf + g * 32 + batch * 16 + q * 4); aa[q * 4] = f.x; aa[q * 4 + 1] = f.y; aa[q * 4 + 2] = f.z; aa[q * 4 + 3] = f.w;
;         }
;         u32x4 rows[16];
; #pragma unroll
;         for (int k = 0; k < 16; ++k) rows[k] = *(const u32x4*)(vb + (size_t)ida[k] * 2048);
; #pragma unroll
;         for (int k = 0; k < 16; ++k) {
;           const f2_t a2 = {aa[k], aa[k]};
; #pragma unroll
;           for (int d = 0; d < 4; ++d) { const unsigned ww = rows[k][d]; o[2 * d] += a2 * cvt8lo(ww); o[2 * d + 1] += a2 * cvt8hi(ww); }
;         }
;       }
;       float ov[16];
; #pragma unroll
;       for (int d = 0; d < 4; ++d) { ov[4 * d] = o[2 * d].x; ov[4 * d + 1] = o[2 * d].y; ov[4 * d + 2] = o[2 * d + 1].x; ov[4 * d + 3] = o[2 * d + 1].y; }
;       float q8[8], q4[4];
; #pragma unroll
;       for (int k = 0; k < 8; ++k) q8[k] = (b5 ? ov[8 + k] : ov[k]) + __shfl_xor(b5 ? ov[k] : ov[8 + k], 32);
; #pragma unroll
;       for (int k = 0; k < 4; ++k) q4[k] = (b4 ? q8[4 + k] : q8[k]) + __shfl_xor(b4 ? q8[k] : q8[4 + k], 16);
;       *(uint2*)(OUTP + (size_t)tok * D_ + s * 256 + l15 * 16 + 8 * b5 + 4 * b4) = make_uint2(pk2(q4[0], q4[1]), pk2(q4[2], q4[3]));
	v_cvt_pk_f32_fp8_e32 v[232:233], v210
	v_cvt_pk_f32_fp8_sdwa v[234:235], v210 src0_sel:WORD_1
	v_pk_fma_f32 v[216:217], v[82:83], v[232:233], v[216:217] op_sel:[1,0,0]
	v_pk_fma_f32 v[218:219], v[82:83], v[234:235], v[218:219] op_sel:[1,0,0]
	v_cvt_pk_f32_fp8_e32 v[236:237], v211
	v_cvt_pk_f32_fp8_sdwa v[238:239], v211 src0_sel:WORD_1
	v_pk_fma_f32 v[220:221], v[82:83], v[236:237], v[220:221] op_sel:[1,0,0]
	v_pk_fma_f32 v[222:223], v[82:83], v[238:239], v[222:223] op_sel:[1,0,0]
	v_cvt_pk_f32_fp8_e32 v[232:233], v212
	v_cvt_pk_f32_fp8_sdwa v[234:235], v212 src0_sel:WORD_1
	v_pk_fma_f32 v[224:225], v[82:83], v[232:233], v[224:225] op_sel:[1,0,0]
	v_pk_fma_f32 v[226:227], v[82:83], v[234:235], v[226:227] op_sel:[1,0,0]
	v_cvt_pk_f32_fp8_e32 v[236:237], v213
	v_cvt_pk_f32_fp8_sdwa v[238:239], v213 src0_sel:WORD_1
	v_pk_fma_f32 v[228:229], v[82:83], v[236:237], v[228:229] op_sel:[1,0,0]
	v_pk_fma_f32 v[230:231], v[82:83], v[238:239], v[230:231] op_sel:[1,0,0]
	ds_read_b128 v[52:55], v6 offset:528
	ds_read_b128 v[56:59], v6 offset:544
	ds_read_b128 v[60:63], v6 offset:560
	ds_read_b128 v[64:67], v6 offset:576
	ds_read_b128 v[68:71], v6 offset:592
	ds_read_b128 v[72:75], v6 offset:608
	ds_read_b128 v[76:79], v6 offset:624
	ds_read_b128 v[80:83], v6 offset:640
	v_add_u32_e32 v214, s46, v4
	s_nop 0
	v_permlane32_swap_b32_e32 v216, v224
	v_permlane32_swap_b32_e32 v217, v225
	v_permlane32_swap_b32_e32 v218, v226
	v_permlane32_swap_b32_e32 v219, v227
	v_permlane32_swap_b32_e32 v220, v228
	v_permlane32_swap_b32_e32 v221, v229
	v_permlane32_swap_b32_e32 v222, v230
	v_permlane32_swap_b32_e32 v223, v231
	v_add_f32_e32 v216, v216, v224
	v_add_f32_e32 v217, v217, v225
	v_add_f32_e32 v218, v218, v226
	v_add_f32_e32 v219, v219, v227
	v_add_f32_e32 v220, v220, v228
	v_add_f32_e32 v221, v221, v229
	v_add_f32_e32 v222, v222, v230
	v_add_f32_e32 v223, v223, v231
	s_nop 1
	v_permlane16_swap_b32_e32 v216, v220
	v_permlane16_swap_b32_e32 v217, v221
	v_permlane16_swap_b32_e32 v218, v222
	v_permlane16_swap_b32_e32 v219, v223
	v_add_f32_e32 v216, v216, v220
	v_add_f32_e32 v217, v217, v221
	v_add_f32_e32 v218, v218, v222
	v_add_f32_e32 v219, v219, v223
	v_cvt_pk_bf16_f32 v232, v216, v217
	v_cvt_pk_bf16_f32 v233, v218, v219
	global_store_dwordx2 v214, v[232:233], s[14:15] nt
	s_add_i32 s54, s34, 3
	s_lshl_b32 s46, s54, 12
	s_add_i32 s46, s46, s24
	s_add_i32 s55, s34, 4
	s_add_i32 s51, s48, 1
	s_cmp_lt_u32 s51, s49
	s_cselect_b32 s55, s55, 8192
	s_cmp_lt_u32 s55, 8192
	s_cselect_b32 s55, s55, 0
	s_lshl_b32 s47, s55, 9
	s_add_u32 s42, s6, s47
	s_addc_u32 s43, s7, 0
	s_add_u32 s44, s8, s47
	s_addc_u32 s45, s9, 0
	global_load_dword v10, v3, s[42:43]
	global_load_dword v11, v3, s[42:43] offset:256
	global_load_dword v12, v3, s[44:45]
	global_load_dword v13, v3, s[44:45] offset:256
	s_waitcnt lgkmcnt(0)
	v_lshl_add_u32 v20, v20, 11, v2
	v_lshl_add_u32 v21, v21, 11, v2
	v_lshl_add_u32 v22, v22, 11, v2
	v_lshl_add_u32 v23, v23, 11, v2
	v_lshl_add_u32 v24, v24, 11, v2
	v_lshl_add_u32 v25, v25, 11, v2
	v_lshl_add_u32 v26, v26, 11, v2
	v_lshl_add_u32 v27, v27, 11, v2
	v_lshl_add_u32 v28, v28, 11, v2
	v_lshl_add_u32 v29, v29, 11, v2
	v_lshl_add_u32 v30, v30, 11, v2
	v_lshl_add_u32 v31, v31, 11, v2
	v_lshl_add_u32 v32, v32, 11, v2
	v_lshl_add_u32 v33, v33, 11, v2
	v_lshl_add_u32 v34, v34, 11, v2
	v_lshl_add_u32 v35, v35, 11, v2
	v_lshl_add_u32 v36, v36, 11, v2
	v_lshl_add_u32 v37, v37, 11, v2
	v_lshl_add_u32 v38, v38, 11, v2
	v_lshl_add_u32 v39, v39, 11, v2
	v_lshl_add_u32 v40, v40, 11, v2
	v_lshl_add_u32 v41, v41, 11, v2
	v_lshl_add_u32 v42, v42, 11, v2
	v_lshl_add_u32 v43, v43, 11, v2
	v_lshl_add_u32 v44, v44, 11, v2
	v_lshl_add_u32 v45, v45, 11, v2
	v_lshl_add_u32 v46, v46, 11, v2
	v_lshl_add_u32 v47, v47, 11, v2
	v_lshl_add_u32 v48, v48, 11, v2
	v_lshl_add_u32 v49, v49, 11, v2
	v_lshl_add_u32 v50, v50, 11, v2
	v_lshl_add_u32 v51, v51, 11, v2
	global_load_dwordx4 v[84:87], v20, s[20:21]
	global_load_dwordx4 v[88:91], v21, s[20:21]
	global_load_dwordx4 v[92:95], v22, s[20:21]
	global_load_dwordx4 v[96:99], v23, s[20:21]
	global_load_dwordx4 v[100:103], v24, s[20:21]
	global_load_dwordx4 v[104:107], v25, s[20:21]
	global_load_dwordx4 v[108:111], v26, s[20:21]
	global_load_dwordx4 v[112:115], v27, s[20:21]
	global_load_dwordx4 v[116:119], v28, s[20:21]
	global_load_dwordx4 v[120:123], v29, s[20:21]
	global_load_dwordx4 v[124:127], v30, s[20:21]
	global_load_dwordx4 v[128:131], v31, s[20:21]
	global_load_dwordx4 v[132:135], v32, s[20:21]
	global_load_dwordx4 v[136:139], v33, s[20:21]
	global_load_dwordx4 v[140:143], v34, s[20:21]
	global_load_dwordx4 v[144:147], v35, s[20:21]
	global_load_dwordx4 v[148:151], v36, s[20:21]
	global_load_dwordx4 v[152:155], v37, s[20:21]
	global_load_dwordx4 v[156:159], v38, s[20:21]
	global_load_dwordx4 v[160:163], v39, s[20:21]
	global_load_dwordx4 v[164:167], v40, s[20:21]
	global_load_dwordx4 v[168:171], v41, s[20:21]
	global_load_dwordx4 v[172:175], v42, s[20:21]
	global_load_dwordx4 v[176:179], v43, s[20:21]
	global_load_dwordx4 v[180:183], v44, s[20:21]
	global_load_dwordx4 v[184:187], v45, s[20:21]
	global_load_dwordx4 v[190:193], v46, s[20:21]
	global_load_dwordx4 v[194:197], v47, s[20:21]
	global_load_dwordx4 v[198:201], v48, s[20:21]
	global_load_dwordx4 v[202:205], v49, s[20:21]
	global_load_dwordx4 v[206:209], v50, s[20:21]
	global_load_dwordx4 v[210:213], v51, s[20:21]
	s_waitcnt vmcnt(31)
; DI f2_t cvt8lo(unsigned w) { return __builtin_amdgcn_cvt_pk_f32_fp8(w, false); }
; DI f2_t cvt8hi(unsigned w) { return __builtin_amdgcn_cvt_pk_f32_fp8(w, true); }
; DI void phase11(const Params& p, char* smem, int rep) {
;     ...
;         for (int k = 0; k < 16; ++k) rows[k] = *(const u32x4*)(vb + (size_t)ida[k] * 2048);
; #pragma unroll
;         for (int k = 0; k < 16; ++k) {
;           const f2_t a2 = {aa[k], aa[k]};
; #pragma unroll
;           for (int d = 0; d < 4; ++d) { const unsigned ww = rows[k][d]; o[2 * d] += a2 * cvt8lo(ww); o[2 * d + 1] += a2 * cvt8hi(ww); }
;         }
	v_cvt_pk_f32_fp8_e32 v[232:233], v84
	v_cvt_pk_f32_fp8_sdwa v[234:235], v84 src0_sel:WORD_1
	v_pk_fma_f32 v[216:217], v[52:53], v[232:233], 0 op_sel_hi:[0,1,0]
	v_pk_fma_f32 v[218:219], v[52:53], v[234:235], 0 op_sel_hi:[0,1,0]
	v_cvt_pk_f32_fp8_e32 v[236:237], v85
	v_cvt_pk_f32_fp8_sdwa v[238:239], v85 src0_sel:WORD_1
	v_pk_fma_f32 v[220:221], v[52:53], v[236:237], 0 op_sel_hi:[0,1,0]
	v_pk_fma_f32 v[222:223], v[52:53], v[238:239], 0 op_sel_hi:[0,1,0]
	v_cvt_pk_f32_fp8_e32 v[232:233], v86
	v_cvt_pk_f32_fp8_sdwa v[234:235], v86 src0_sel:WORD_1
	v_pk_fma_f32 v[224:225], v[52:53], v[232:233], 0 op_sel_hi:[0,1,0]
	v_pk_fma_f32 v[226:227], v[52:53], v[234:235], 0 op_sel_hi:[0,1,0]
	v_cvt_pk_f32_fp8_e32 v[236:237], v87
	v_cvt_pk_f32_fp8_sdwa v[238:239], v87 src0_sel:WORD_1
	v_pk_fma_f32 v[228:229], v[52:53], v[236:237], 0 op_sel_hi:[0,1,0]
	v_pk_fma_f32 v[230:231], v[52:53], v[238:239], 0 op_sel_hi:[0,1,0]
	s_waitcnt vmcnt(30)
	v_cvt_pk_f32_fp8_e32 v[232:233], v88
	v_cvt_pk_f32_fp8_sdwa v[234:235], v88 src0_sel:WORD_1
	v_pk_fma_f32 v[216:217], v[52:53], v[232:233], v[216:217] op_sel:[1,0,0]
	v_pk_fma_f32 v[218:219], v[52:53], v[234:235], v[218:219] op_sel:[1,0,0]
	v_cvt_pk_f32_fp8_e32 v[236:237], v89
	v_cvt_pk_f32_fp8_sdwa v[238:239], v89 src0_sel:WORD_1
	v_pk_fma_f32 v[220:221], v[52:53], v[236:237], v[220:221] op_sel:[1,0,0]
	v_pk_fma_f32 v[222:223], v[52:53], v[238:239], v[222:223] op_sel:[1,0,0]
	v_cvt_pk_f32_fp8_e32 v[232:233], v90
	v_cvt_pk_f32_fp8_sdwa v[234:235], v90 src0_sel:WORD_1
	v_pk_fma_f32 v[224:225], v[52:53], v[232:233], v[224:225] op_sel:[1,0,0]
	v_pk_fma_f32 v[226:227], v[52:53], v[234:235], v[226:227] op_sel:[1,0,0]
	v_cvt_pk_f32_fp8_e32 v[236:237], v91
	v_cvt_pk_f32_fp8_sdwa v[238:239], v91 src0_sel:WORD_1
	v_pk_fma_f32 v[228:229], v[52:53], v[236:237], v[228:229] op_sel:[1,0,0]
	v_pk_fma_f32 v[230:231], v[52:53], v[238:239], v[230:231] op_sel:[1,0,0]
	s_waitcnt vmcnt(29)
	v_cvt_pk_f32_fp8_e32 v[232:233], v92
	v_cvt_pk_f32_fp8_sdwa v[234:235], v92 src0_sel:WORD_1
	v_pk_fma_f32 v[216:217], v[54:55], v[232:233], v[216:217] op_sel_hi:[0,1,1]
	v_pk_fma_f32 v[218:219], v[54:55], v[234:235], v[218:219] op_sel_hi:[0,1,1]
	v_cvt_pk_f32_fp8_e32 v[236:237], v93
	v_cvt_pk_f32_fp8_sdwa v[238:239], v93 src0_sel:WORD_1
	v_pk_fma_f32 v[220:221], v[54:55], v[236:237], v[220:221] op_sel_hi:[0,1,1]
	v_pk_fma_f32 v[222:223], v[54:55], v[238:239], v[222:223] op_sel_hi:[0,1,1]
	v_cvt_pk_f32_fp8_e32 v[232:233], v94
	v_cvt_pk_f32_fp8_sdwa v[234:235], v94 src0_sel:WORD_1
	v_pk_fma_f32 v[224:225], v[54:55], v[232:233], v[224:225] op_sel_hi:[0,1,1]
	v_pk_fma_f32 v[226:227], v[54:55], v[234:235], v[226:227] op_sel_hi:[0,1,1]
	v_cvt_pk_f32_fp8_e32 v[236:237], v95
	v_cvt_pk_f32_fp8_sdwa v[238:239], v95 src0_sel:WORD_1
	v_pk_fma_f32 v[228:229], v[54:55], v[236:237], v[228:229] op_sel_hi:[0,1,1]
	v_pk_fma_f32 v[230:231], v[54:55], v[238:239], v[230:231] op_sel_hi:[0,1,1]
	s_waitcnt vmcnt(28)
	v_cvt_pk_f32_fp8_e32 v[232:233], v96
	v_cvt_pk_f32_fp8_sdwa v[234:235], v96 src0_sel:WORD_1
	v_pk_fma_f32 v[216:217], v[54:55], v[232:233], v[216:217] op_sel:[1,0,0]
	v_pk_fma_f32 v[218:219], v[54:55], v[234:235], v[218:219] op_sel:[1,0,0]
	v_cvt_pk_f32_fp8_e32 v[236:237], v97
	v_cvt_pk_f32_fp8_sdwa v[238:239], v97 src0_sel:WORD_1
	v_pk_fma_f32 v[220:221], v[54:55], v[236:237], v[220:221] op_sel:[1,0,0]
	v_pk_fma_f32 v[222:223], v[54:55], v[238:239], v[222:223] op_sel:[1,0,0]
	v_cvt_pk_f32_fp8_e32 v[232:233], v98
	v_cvt_pk_f32_fp8_sdwa v[234:235], v98 src0_sel:WORD_1
	v_pk_fma_f32 v[224:225], v[54:55], v[232:233], v[224:225] op_sel:[1,0,0]
	v_pk_fma_f32 v[226:227], v[54:55], v[234:235], v[226:227] op_sel:[1,0,0]
	v_cvt_pk_f32_fp8_e32 v[236:237], v99
	v_cvt_pk_f32_fp8_sdwa v[238:239], v99 src0_sel:WORD_1
	v_pk_fma_f32 v[228:229], v[54:55], v[236:237], v[228:229] op_sel:[1,0,0]
	v_pk_fma_f32 v[230:231], v[54:55], v[238:239], v[230:231] op_sel:[1,0,0]
	s_waitcnt vmcnt(27)
	v_cvt_pk_f32_fp8_e32 v[232:233], v100
	v_cvt_pk_f32_fp8_sdwa v[234:235], v100 src0_sel:WORD_1
	v_pk_fma_f32 v[216:217], v[56:57], v[232:233], v[216:217] op_sel_hi:[0,1,1]
	v_pk_fma_f32 v[218:219], v[56:57], v[234:235], v[218:219] op_sel_hi:[0,1,1]
	v_cvt_pk_f32_fp8_e32 v[236:237], v101
	v_cvt_pk_f32_fp8_sdwa v[238:239], v101 src0_sel:WORD_1
	v_pk_fma_f32 v[220:221], v[56:57], v[236:237], v[220:221] op_sel_hi:[0,1,1]
	v_pk_fma_f32 v[222:223], v[56:57], v[238:239], v[222:223] op_sel_hi:[0,1,1]
	v_cvt_pk_f32_fp8_e32 v[232:233], v102
	v_cvt_pk_f32_fp8_sdwa v[234:235], v102 src0_sel:WORD_1
	v_pk_fma_f32 v[224:225], v[56:57], v[232:233], v[224:225] op_sel_hi:[0,1,1]
	v_pk_fma_f32 v[226:227], v[56:57], v[234:235], v[226:227] op_sel_hi:[0,1,1]
	v_cvt_pk_f32_fp8_e32 v[236:237], v103
	v_cvt_pk_f32_fp8_sdwa v[238:239], v103 src0_sel:WORD_1
	v_pk_fma_f32 v[228:229], v[56:57], v[236:237], v[228:229] op_sel_hi:[0,1,1]
	v_pk_fma_f32 v[230:231], v[56:57], v[238:239], v[230:231] op_sel_hi:[0,1,1]
	s_waitcnt vmcnt(26)
	v_cvt_pk_f32_fp8_e32 v[232:233], v104
	v_cvt_pk_f32_fp8_sdwa v[234:235], v104 src0_sel:WORD_1
	v_pk_fma_f32 v[216:217], v[56:57], v[232:233], v[216:217] op_sel:[1,0,0]
	v_pk_fma_f32 v[218:219], v[56:57], v[234:235], v[218:219] op_sel:[1,0,0]
	v_cvt_pk_f32_fp8_e32 v[236:237], v105
	v_cvt_pk_f32_fp8_sdwa v[238:239], v105 src0_sel:WORD_1
	v_pk_fma_f32 v[220:221], v[56:57], v[236:237], v[220:221] op_sel:[1,0,0]
	v_pk_fma_f32 v[222:223], v[56:57], v[238:239], v[222:223] op_sel:[1,0,0]
	v_cvt_pk_f32_fp8_e32 v[232:233], v106
	v_cvt_pk_f32_fp8_sdwa v[234:235], v106 src0_sel:WORD_1
	v_pk_fma_f32 v[224:225], v[56:57], v[232:233], v[224:225] op_sel:[1,0,0]
	v_pk_fma_f32 v[226:227], v[56:57], v[234:235], v[226:227] op_sel:[1,0,0]
	v_cvt_pk_f32_fp8_e32 v[236:237], v107
	v_cvt_pk_f32_fp8_sdwa v[238:239], v107 src0_sel:WORD_1
	v_pk_fma_f32 v[228:229], v[56:57], v[236:237], v[228:229] op_sel:[1,0,0]
	v_pk_fma_f32 v[230:231], v[56:57], v[238:239], v[230:231] op_sel:[1,0,0]
	s_waitcnt vmcnt(25)
; DI f2_t cvt8lo(unsigned w) { return __builtin_amdgcn_cvt_pk_f32_fp8(w, false); }
; DI f2_t cvt8hi(unsigned w) { return __builtin_amdgcn_cvt_pk_f32_fp8(w, true); }
; DI void phase11(const Params& p, char* smem, int rep) {
;     ...
;         for (int k = 0; k < 16; ++k) rows[k] = *(const u32x4*)(vb + (size_t)ida[k] * 2048);
; #pragma unroll
;         for (int k = 0; k < 16; ++k) {
;           const f2_t a2 = {aa[k], aa[k]};
; #pragma unroll
;           for (int d = 0; d < 4; ++d) { const unsigned ww = rows[k][d]; o[2 * d] += a2 * cvt8lo(ww); o[2 * d + 1] += a2 * cvt8hi(ww); }
;         }
	v_cvt_pk_f32_fp8_e32 v[232:233], v108
	v_cvt_pk_f32_fp8_sdwa v[234:235], v108 src0_sel:WORD_1
	v_pk_fma_f32 v[216:217], v[58:59], v[232:233], v[216:217] op_sel_hi:[0,1,1]
	v_pk_fma_f32 v[218:219], v[58:59], v[234:235], v[218:219] op_sel_hi:[0,1,1]
	v_cvt_pk_f32_fp8_e32 v[236:237], v109
	v_cvt_pk_f32_fp8_sdwa v[238:239], v109 src0_sel:WORD_1
	v_pk_fma_f32 v[220:221], v[58:59], v[236:237], v[220:221] op_sel_hi:[0,1,1]
	v_pk_fma_f32 v[222:223], v[58:59], v[238:239], v[222:223] op_sel_hi:[0,1,1]
	v_cvt_pk_f32_fp8_e32 v[232:233], v110
	v_cvt_pk_f32_fp8_sdwa v[234:235], v110 src0_sel:WORD_1
	v_pk_fma_f32 v[224:225], v[58:59], v[232:233], v[224:225] op_sel_hi:[0,1,1]
	v_pk_fma_f32 v[226:227], v[58:59], v[234:235], v[226:227] op_sel_hi:[0,1,1]
	v_cvt_pk_f32_fp8_e32 v[236:237], v111
	v_cvt_pk_f32_fp8_sdwa v[238:239], v111 src0_sel:WORD_1
	v_pk_fma_f32 v[228:229], v[58:59], v[236:237], v[228:229] op_sel_hi:[0,1,1]
	v_pk_fma_f32 v[230:231], v[58:59], v[238:239], v[230:231] op_sel_hi:[0,1,1]
	s_waitcnt vmcnt(24)
	v_cvt_pk_f32_fp8_e32 v[232:233], v112
	v_cvt_pk_f32_fp8_sdwa v[234:235], v112 src0_sel:WORD_1
	v_pk_fma_f32 v[216:217], v[58:59], v[232:233], v[216:217] op_sel:[1,0,0]
	v_pk_fma_f32 v[218:219], v[58:59], v[234:235], v[218:219] op_sel:[1,0,0]
	v_cvt_pk_f32_fp8_e32 v[236:237], v113
	v_cvt_pk_f32_fp8_sdwa v[238:239], v113 src0_sel:WORD_1
	v_pk_fma_f32 v[220:221], v[58:59], v[236:237], v[220:221] op_sel:[1,0,0]
	v_pk_fma_f32 v[222:223], v[58:59], v[238:239], v[222:223] op_sel:[1,0,0]
	v_cvt_pk_f32_fp8_e32 v[232:233], v114
	v_cvt_pk_f32_fp8_sdwa v[234:235], v114 src0_sel:WORD_1
	v_pk_fma_f32 v[224:225], v[58:59], v[232:233], v[224:225] op_sel:[1,0,0]
	v_pk_fma_f32 v[226:227], v[58:59], v[234:235], v[226:227] op_sel:[1,0,0]
	v_cvt_pk_f32_fp8_e32 v[236:237], v115
	v_cvt_pk_f32_fp8_sdwa v[238:239], v115 src0_sel:WORD_1
	v_pk_fma_f32 v[228:229], v[58:59], v[236:237], v[228:229] op_sel:[1,0,0]
	v_pk_fma_f32 v[230:231], v[58:59], v[238:239], v[230:231] op_sel:[1,0,0]
	s_waitcnt vmcnt(23)
	v_cvt_pk_f32_fp8_e32 v[232:233], v116
	v_cvt_pk_f32_fp8_sdwa v[234:235], v116 src0_sel:WORD_1
	v_pk_fma_f32 v[216:217], v[60:61], v[232:233], v[216:217] op_sel_hi:[0,1,1]
	v_pk_fma_f32 v[218:219], v[60:61], v[234:235], v[218:219] op_sel_hi:[0,1,1]
	v_cvt_pk_f32_fp8_e32 v[236:237], v117
	v_cvt_pk_f32_fp8_sdwa v[238:239], v117 src0_sel:WORD_1
	v_pk_fma_f32 v[220:221], v[60:61], v[236:237], v[220:221] op_sel_hi:[0,1,1]
	v_pk_fma_f32 v[222:223], v[60:61], v[238:239], v[222:223] op_sel_hi:[0,1,1]
	v_cvt_pk_f32_fp8_e32 v[232:233], v118
	v_cvt_pk_f32_fp8_sdwa v[234:235], v118 src0_sel:WORD_1
	v_pk_fma_f32 v[224:225], v[60:61], v[232:233], v[224:225] op_sel_hi:[0,1,1]
	v_pk_fma_f32 v[226:227], v[60:61], v[234:235], v[226:227] op_sel_hi:[0,1,1]
	v_cvt_pk_f32_fp8_e32 v[236:237], v119
	v_cvt_pk_f32_fp8_sdwa v[238:239], v119 src0_sel:WORD_1
	v_pk_fma_f32 v[228:229], v[60:61], v[236:237], v[228:229] op_sel_hi:[0,1,1]
	v_pk_fma_f32 v[230:231], v[60:61], v[238:239], v[230:231] op_sel_hi:[0,1,1]
	s_waitcnt vmcnt(22)
	v_cvt_pk_f32_fp8_e32 v[232:233], v120
	v_cvt_pk_f32_fp8_sdwa v[234:235], v120 src0_sel:WORD_1
	v_pk_fma_f32 v[216:217], v[60:61], v[232:233], v[216:217] op_sel:[1,0,0]
	v_pk_fma_f32 v[218:219], v[60:61], v[234:235], v[218:219] op_sel:[1,0,0]
	v_cvt_pk_f32_fp8_e32 v[236:237], v121
	v_cvt_pk_f32_fp8_sdwa v[238:239], v121 src0_sel:WORD_1
	v_pk_fma_f32 v[220:221], v[60:61], v[236:237], v[220:221] op_sel:[1,0,0]
	v_pk_fma_f32 v[222:223], v[60:61], v[238:239], v[222:223] op_sel:[1,0,0]
	v_cvt_pk_f32_fp8_e32 v[232:233], v122
	v_cvt_pk_f32_fp8_sdwa v[234:235], v122 src0_sel:WORD_1
	v_pk_fma_f32 v[224:225], v[60:61], v[232:233], v[224:225] op_sel:[1,0,0]
	v_pk_fma_f32 v[226:227], v[60:61], v[234:235], v[226:227] op_sel:[1,0,0]
	v_cvt_pk_f32_fp8_e32 v[236:237], v123
	v_cvt_pk_f32_fp8_sdwa v[238:239], v123 src0_sel:WORD_1
	v_pk_fma_f32 v[228:229], v[60:61], v[236:237], v[228:229] op_sel:[1,0,0]
	v_pk_fma_f32 v[230:231], v[60:61], v[238:239], v[230:231] op_sel:[1,0,0]
	s_waitcnt vmcnt(21)
	v_cvt_pk_f32_fp8_e32 v[232:233], v124
	v_cvt_pk_f32_fp8_sdwa v[234:235], v124 src0_sel:WORD_1
	v_pk_fma_f32 v[216:217], v[62:63], v[232:233], v[216:217] op_sel_hi:[0,1,1]
	v_pk_fma_f32 v[218:219], v[62:63], v[234:235], v[218:219] op_sel_hi:[0,1,1]
	v_cvt_pk_f32_fp8_e32 v[236:237], v125
	v_cvt_pk_f32_fp8_sdwa v[238:239], v125 src0_sel:WORD_1
	v_pk_fma_f32 v[220:221], v[62:63], v[236:237], v[220:221] op_sel_hi:[0,1,1]
	v_pk_fma_f32 v[222:223], v[62:63], v[238:239], v[222:223] op_sel_hi:[0,1,1]
	v_cvt_pk_f32_fp8_e32 v[232:233], v126
	v_cvt_pk_f32_fp8_sdwa v[234:235], v126 src0_sel:WORD_1
	v_pk_fma_f32 v[224:225], v[62:63], v[232:233], v[224:225] op_sel_hi:[0,1,1]
	v_pk_fma_f32 v[226:227], v[62:63], v[234:235], v[226:227] op_sel_hi:[0,1,1]
	v_cvt_pk_f32_fp8_e32 v[236:237], v127
	v_cvt_pk_f32_fp8_sdwa v[238:239], v127 src0_sel:WORD_1
	v_pk_fma_f32 v[228:229], v[62:63], v[236:237], v[228:229] op_sel_hi:[0,1,1]
	v_pk_fma_f32 v[230:231], v[62:63], v[238:239], v[230:231] op_sel_hi:[0,1,1]
	s_waitcnt vmcnt(20)
	v_cvt_pk_f32_fp8_e32 v[232:233], v128
	v_cvt_pk_f32_fp8_sdwa v[234:235], v128 src0_sel:WORD_1
	v_pk_fma_f32 v[216:217], v[62:63], v[232:233], v[216:217] op_sel:[1,0,0]
	v_pk_fma_f32 v[218:219], v[62:63], v[234:235], v[218:219] op_sel:[1,0,0]
	v_cvt_pk_f32_fp8_e32 v[236:237], v129
	v_cvt_pk_f32_fp8_sdwa v[238:239], v129 src0_sel:WORD_1
	v_pk_fma_f32 v[220:221], v[62:63], v[236:237], v[220:221] op_sel:[1,0,0]
	v_pk_fma_f32 v[222:223], v[62:63], v[238:239], v[222:223] op_sel:[1,0,0]
	v_cvt_pk_f32_fp8_e32 v[232:233], v130
	v_cvt_pk_f32_fp8_sdwa v[234:235], v130 src0_sel:WORD_1
	v_pk_fma_f32 v[224:225], v[62:63], v[232:233], v[224:225] op_sel:[1,0,0]
	v_pk_fma_f32 v[226:227], v[62:63], v[234:235], v[226:227] op_sel:[1,0,0]
	v_cvt_pk_f32_fp8_e32 v[236:237], v131
	v_cvt_pk_f32_fp8_sdwa v[238:239], v131 src0_sel:WORD_1
	v_pk_fma_f32 v[228:229], v[62:63], v[236:237], v[228:229] op_sel:[1,0,0]
	v_pk_fma_f32 v[230:231], v[62:63], v[238:239], v[230:231] op_sel:[1,0,0]
	s_waitcnt vmcnt(19)
; DI f2_t cvt8lo(unsigned w) { return __builtin_amdgcn_cvt_pk_f32_fp8(w, false); }
; DI f2_t cvt8hi(unsigned w) { return __builtin_amdgcn_cvt_pk_f32_fp8(w, true); }
; DI void wave_lds_sync() { asm volatile("s_waitcnt lgkmcnt(0)" ::: "memory"); __builtin_amdgcn_wave_barrier(); }
; DI void phase11(const Params& p, char* smem, int rep) {
;     ...
;       lw[(lane & 3) * 32 + (lane >> 2)] = i0; lw[(lane & 3) * 32 + 16 + (lane >> 2)] = i1;
;       lf[(lane & 3) * 32 + (lane >> 2)] = a0; lf[(lane & 3) * 32 + 16 + (lane >> 2)] = a1;
;       wave_lds_sync();
;       f2_t o[8];
; #pragma unroll
;       for (int i = 0; i < 8; ++i) o[i] = f2_t{0.f, 0.f};
;       const unsigned char* vb = V8 + s * 256 + l15 * 16;
; #pragma unroll
;       for (int batch = 0; batch < 2; ++batch) {
;         int ida[16]; float aa[16];
; #pragma unroll
;         for (int q = 0; q < 4; ++q) {
;           const int4 v = *(const int4*)(lw + g * 32 + batch * 16 + q * 4); ida[q * 4] = v.x; ida[q * 4 + 1] = v.y; ida[q * 4 + 2] = v.z; ida[q * 4 + 3] = v.w;
;           const float4 f = *(const float4*)(lf + g * 32 + batch * 16 + q * 4); aa[q * 4] = f.x; aa[q * 4 + 1] = f.y; aa[q * 4 + 2] = f.z; aa[q * 4 + 3] = f.w;
;         }
;         u32x4 rows[16];
; #pragma unroll
;         for (int k = 0; k < 16; ++k) rows[k] = *(const u32x4*)(vb + (size_t)ida[k] * 2048);
; #pragma unroll
;         for (int k = 0; k < 16; ++k) {
;           const f2_t a2 = {aa[k], aa[k]};
; #pragma unroll
;           for (int d = 0; d < 4; ++d) { const unsigned ww = rows[k][d]; o[2 * d] += a2 * cvt8lo(ww); o[2 * d + 1] += a2 * cvt8hi(ww); }
;         }
	v_cvt_pk_f32_fp8_e32 v[232:233], v132
	v_cvt_pk_f32_fp8_sdwa v[234:235], v132 src0_sel:WORD_1
	v_pk_fma_f32 v[216:217], v[64:65], v[232:233], v[216:217] op_sel_hi:[0,1,1]
	v_pk_fma_f32 v[218:219], v[64:65], v[234:235], v[218:219] op_sel_hi:[0,1,1]
	v_cvt_pk_f32_fp8_e32 v[236:237], v133
	v_cvt_pk_f32_fp8_sdwa v[238:239], v133 src0_sel:WORD_1
	v_pk_fma_f32 v[220:221], v[64:65], v[236:237], v[220:221] op_sel_hi:[0,1,1]
	v_pk_fma_f32 v[222:223], v[64:65], v[238:239], v[222:223] op_sel_hi:[0,1,1]
	v_cvt_pk_f32_fp8_e32 v[232:233], v134
	v_cvt_pk_f32_fp8_sdwa v[234:235], v134 src0_sel:WORD_1
	v_pk_fma_f32 v[224:225], v[64:65], v[232:233], v[224:225] op_sel_hi:[0,1,1]
	v_pk_fma_f32 v[226:227], v[64:65], v[234:235], v[226:227] op_sel_hi:[0,1,1]
	v_cvt_pk_f32_fp8_e32 v[236:237], v135
	v_cvt_pk_f32_fp8_sdwa v[238:239], v135 src0_sel:WORD_1
	v_pk_fma_f32 v[228:229], v[64:65], v[236:237], v[228:229] op_sel_hi:[0,1,1]
	v_pk_fma_f32 v[230:231], v[64:65], v[238:239], v[230:231] op_sel_hi:[0,1,1]
	s_waitcnt vmcnt(18)
	v_cvt_pk_f32_fp8_e32 v[232:233], v136
	v_cvt_pk_f32_fp8_sdwa v[234:235], v136 src0_sel:WORD_1
	v_pk_fma_f32 v[216:217], v[64:65], v[232:233], v[216:217] op_sel:[1,0,0]
	v_pk_fma_f32 v[218:219], v[64:65], v[234:235], v[218:219] op_sel:[1,0,0]
	v_cvt_pk_f32_fp8_e32 v[236:237], v137
	v_cvt_pk_f32_fp8_sdwa v[238:239], v137 src0_sel:WORD_1
	v_pk_fma_f32 v[220:221], v[64:65], v[236:237], v[220:221] op_sel:[1,0,0]
	v_pk_fma_f32 v[222:223], v[64:65], v[238:239], v[222:223] op_sel:[1,0,0]
	v_cvt_pk_f32_fp8_e32 v[232:233], v138
	v_cvt_pk_f32_fp8_sdwa v[234:235], v138 src0_sel:WORD_1
	v_pk_fma_f32 v[224:225], v[64:65], v[232:233], v[224:225] op_sel:[1,0,0]
	v_pk_fma_f32 v[226:227], v[64:65], v[234:235], v[226:227] op_sel:[1,0,0]
	v_cvt_pk_f32_fp8_e32 v[236:237], v139
	v_cvt_pk_f32_fp8_sdwa v[238:239], v139 src0_sel:WORD_1
	v_pk_fma_f32 v[228:229], v[64:65], v[236:237], v[228:229] op_sel:[1,0,0]
	v_pk_fma_f32 v[230:231], v[64:65], v[238:239], v[230:231] op_sel:[1,0,0]
	s_waitcnt vmcnt(17)
	v_cvt_pk_f32_fp8_e32 v[232:233], v140
	v_cvt_pk_f32_fp8_sdwa v[234:235], v140 src0_sel:WORD_1
	v_pk_fma_f32 v[216:217], v[66:67], v[232:233], v[216:217] op_sel_hi:[0,1,1]
	v_pk_fma_f32 v[218:219], v[66:67], v[234:235], v[218:219] op_sel_hi:[0,1,1]
	v_cvt_pk_f32_fp8_e32 v[236:237], v141
	v_cvt_pk_f32_fp8_sdwa v[238:239], v141 src0_sel:WORD_1
	v_pk_fma_f32 v[220:221], v[66:67], v[236:237], v[220:221] op_sel_hi:[0,1,1]
	v_pk_fma_f32 v[222:223], v[66:67], v[238:239], v[222:223] op_sel_hi:[0,1,1]
	v_cvt_pk_f32_fp8_e32 v[232:233], v142
	v_cvt_pk_f32_fp8_sdwa v[234:235], v142 src0_sel:WORD_1
	v_pk_fma_f32 v[224:225], v[66:67], v[232:233], v[224:225] op_sel_hi:[0,1,1]
	v_pk_fma_f32 v[226:227], v[66:67], v[234:235], v[226:227] op_sel_hi:[0,1,1]
	v_cvt_pk_f32_fp8_e32 v[236:237], v143
	v_cvt_pk_f32_fp8_sdwa v[238:239], v143 src0_sel:WORD_1
	v_pk_fma_f32 v[228:229], v[66:67], v[236:237], v[228:229] op_sel_hi:[0,1,1]
	v_pk_fma_f32 v[230:231], v[66:67], v[238:239], v[230:231] op_sel_hi:[0,1,1]
	s_waitcnt vmcnt(16)
	v_cvt_pk_f32_fp8_e32 v[232:233], v144
	v_cvt_pk_f32_fp8_sdwa v[234:235], v144 src0_sel:WORD_1
	v_pk_fma_f32 v[216:217], v[66:67], v[232:233], v[216:217] op_sel:[1,0,0]
	v_pk_fma_f32 v[218:219], v[66:67], v[234:235], v[218:219] op_sel:[1,0,0]
	v_cvt_pk_f32_fp8_e32 v[236:237], v145
	v_cvt_pk_f32_fp8_sdwa v[238:239], v145 src0_sel:WORD_1
	v_pk_fma_f32 v[220:221], v[66:67], v[236:237], v[220:221] op_sel:[1,0,0]
	v_pk_fma_f32 v[222:223], v[66:67], v[238:239], v[222:223] op_sel:[1,0,0]
	v_cvt_pk_f32_fp8_e32 v[232:233], v146
	v_cvt_pk_f32_fp8_sdwa v[234:235], v146 src0_sel:WORD_1
	v_pk_fma_f32 v[224:225], v[66:67], v[232:233], v[224:225] op_sel:[1,0,0]
	v_pk_fma_f32 v[226:227], v[66:67], v[234:235], v[226:227] op_sel:[1,0,0]
	v_cvt_pk_f32_fp8_e32 v[236:237], v147
	v_cvt_pk_f32_fp8_sdwa v[238:239], v147 src0_sel:WORD_1
	v_pk_fma_f32 v[228:229], v[66:67], v[236:237], v[228:229] op_sel:[1,0,0]
	v_pk_fma_f32 v[230:231], v[66:67], v[238:239], v[230:231] op_sel:[1,0,0]
	ds_write2_b32 v5, v10, v11 offset0:4 offset1:20
	ds_write2_b32 v5, v12, v13 offset0:132 offset1:148
	s_waitcnt lgkmcnt(0)
	ds_read_b128 v[20:23], v6 offset:16
	ds_read_b128 v[24:27], v6 offset:32
	ds_read_b128 v[28:31], v6 offset:48
	ds_read_b128 v[32:35], v6 offset:64
	ds_read_b128 v[36:39], v6 offset:80
	ds_read_b128 v[40:43], v6 offset:96
	ds_read_b128 v[44:47], v6 offset:112
	ds_read_b128 v[48:51], v6 offset:128
	s_waitcnt vmcnt(15)
	v_cvt_pk_f32_fp8_e32 v[232:233], v148
	v_cvt_pk_f32_fp8_sdwa v[234:235], v148 src0_sel:WORD_1
	v_pk_fma_f32 v[216:217], v[68:69], v[232:233], v[216:217] op_sel_hi:[0,1,1]
	v_pk_fma_f32 v[218:219], v[68:69], v[234:235], v[218:219] op_sel_hi:[0,1,1]
	v_cvt_pk_f32_fp8_e32 v[236:237], v149
	v_cvt_pk_f32_fp8_sdwa v[238:239], v149 src0_sel:WORD_1
	v_pk_fma_f32 v[220:221], v[68:69], v[236:237], v[220:221] op_sel_hi:[0,1,1]
	v_pk_fma_f32 v[222:223], v[68:69], v[238:239], v[222:223] op_sel_hi:[0,1,1]
	v_cvt_pk_f32_fp8_e32 v[232:233], v150
	v_cvt_pk_f32_fp8_sdwa v[234:235], v150 src0_sel:WORD_1
	v_pk_fma_f32 v[224:225], v[68:69], v[232:233], v[224:225] op_sel_hi:[0,1,1]
	v_pk_fma_f32 v[226:227], v[68:69], v[234:235], v[226:227] op_sel_hi:[0,1,1]
	v_cvt_pk_f32_fp8_e32 v[236:237], v151
	v_cvt_pk_f32_fp8_sdwa v[238:239], v151 src0_sel:WORD_1
	v_pk_fma_f32 v[228:229], v[68:69], v[236:237], v[228:229] op_sel_hi:[0,1,1]
	v_pk_fma_f32 v[230:231], v[68:69], v[238:239], v[230:231] op_sel_hi:[0,1,1]
	s_waitcnt vmcnt(14)
; DI f2_t cvt8lo(unsigned w) { return __builtin_amdgcn_cvt_pk_f32_fp8(w, false); }
; DI f2_t cvt8hi(unsigned w) { return __builtin_amdgcn_cvt_pk_f32_fp8(w, true); }
; DI void phase11(const Params& p, char* smem, int rep) {
;     ...
;         for (int k = 0; k < 16; ++k) rows[k] = *(const u32x4*)(vb + (size_t)ida[k] * 2048);
; #pragma unroll
;         for (int k = 0; k < 16; ++k) {
;           const f2_t a2 = {aa[k], aa[k]};
; #pragma unroll
;           for (int d = 0; d < 4; ++d) { const unsigned ww = rows[k][d]; o[2 * d] += a2 * cvt8lo(ww); o[2 * d + 1] += a2 * cvt8hi(ww); }
;         }
	v_cvt_pk_f32_fp8_e32 v[232:233], v152
	v_cvt_pk_f32_fp8_sdwa v[234:235], v152 src0_sel:WORD_1
	v_pk_fma_f32 v[216:217], v[68:69], v[232:233], v[216:217] op_sel:[1,0,0]
	v_pk_fma_f32 v[218:219], v[68:69], v[234:235], v[218:219] op_sel:[1,0,0]
	v_cvt_pk_f32_fp8_e32 v[236:237], v153
	v_cvt_pk_f32_fp8_sdwa v[238:239], v153 src0_sel:WORD_1
	v_pk_fma_f32 v[220:221], v[68:69], v[236:237], v[220:221] op_sel:[1,0,0]
	v_pk_fma_f32 v[222:223], v[68:69], v[238:239], v[222:223] op_sel:[1,0,0]
	v_cvt_pk_f32_fp8_e32 v[232:233], v154
	v_cvt_pk_f32_fp8_sdwa v[234:235], v154 src0_sel:WORD_1
	v_pk_fma_f32 v[224:225], v[68:69], v[232:233], v[224:225] op_sel:[1,0,0]
	v_pk_fma_f32 v[226:227], v[68:69], v[234:235], v[226:227] op_sel:[1,0,0]
	v_cvt_pk_f32_fp8_e32 v[236:237], v155
	v_cvt_pk_f32_fp8_sdwa v[238:239], v155 src0_sel:WORD_1
	v_pk_fma_f32 v[228:229], v[68:69], v[236:237], v[228:229] op_sel:[1,0,0]
	v_pk_fma_f32 v[230:231], v[68:69], v[238:239], v[230:231] op_sel:[1,0,0]
	s_waitcnt vmcnt(13)
	v_cvt_pk_f32_fp8_e32 v[232:233], v156
	v_cvt_pk_f32_fp8_sdwa v[234:235], v156 src0_sel:WORD_1
	v_pk_fma_f32 v[216:217], v[70:71], v[232:233], v[216:217] op_sel_hi:[0,1,1]
	v_pk_fma_f32 v[218:219], v[70:71], v[234:235], v[218:219] op_sel_hi:[0,1,1]
	v_cvt_pk_f32_fp8_e32 v[236:237], v157
	v_cvt_pk_f32_fp8_sdwa v[238:239], v157 src0_sel:WORD_1
	v_pk_fma_f32 v[220:221], v[70:71], v[236:237], v[220:221] op_sel_hi:[0,1,1]
	v_pk_fma_f32 v[222:223], v[70:71], v[238:239], v[222:223] op_sel_hi:[0,1,1]
	v_cvt_pk_f32_fp8_e32 v[232:233], v158
	v_cvt_pk_f32_fp8_sdwa v[234:235], v158 src0_sel:WORD_1
	v_pk_fma_f32 v[224:225], v[70:71], v[232:233], v[224:225] op_sel_hi:[0,1,1]
	v_pk_fma_f32 v[226:227], v[70:71], v[234:235], v[226:227] op_sel_hi:[0,1,1]
	v_cvt_pk_f32_fp8_e32 v[236:237], v159
	v_cvt_pk_f32_fp8_sdwa v[238:239], v159 src0_sel:WORD_1
	v_pk_fma_f32 v[228:229], v[70:71], v[236:237], v[228:229] op_sel_hi:[0,1,1]
	v_pk_fma_f32 v[230:231], v[70:71], v[238:239], v[230:231] op_sel_hi:[0,1,1]
	s_waitcnt vmcnt(12)
	v_cvt_pk_f32_fp8_e32 v[232:233], v160
	v_cvt_pk_f32_fp8_sdwa v[234:235], v160 src0_sel:WORD_1
	v_pk_fma_f32 v[216:217], v[70:71], v[232:233], v[216:217] op_sel:[1,0,0]
	v_pk_fma_f32 v[218:219], v[70:71], v[234:235], v[218:219] op_sel:[1,0,0]
	v_cvt_pk_f32_fp8_e32 v[236:237], v161
	v_cvt_pk_f32_fp8_sdwa v[238:239], v161 src0_sel:WORD_1
	v_pk_fma_f32 v[220:221], v[70:71], v[236:237], v[220:221] op_sel:[1,0,0]
	v_pk_fma_f32 v[222:223], v[70:71], v[238:239], v[222:223] op_sel:[1,0,0]
	v_cvt_pk_f32_fp8_e32 v[232:233], v162
	v_cvt_pk_f32_fp8_sdwa v[234:235], v162 src0_sel:WORD_1
	v_pk_fma_f32 v[224:225], v[70:71], v[232:233], v[224:225] op_sel:[1,0,0]
	v_pk_fma_f32 v[226:227], v[70:71], v[234:235], v[226:227] op_sel:[1,0,0]
	v_cvt_pk_f32_fp8_e32 v[236:237], v163
	v_cvt_pk_f32_fp8_sdwa v[238:239], v163 src0_sel:WORD_1
	v_pk_fma_f32 v[228:229], v[70:71], v[236:237], v[228:229] op_sel:[1,0,0]
	v_pk_fma_f32 v[230:231], v[70:71], v[238:239], v[230:231] op_sel:[1,0,0]
	s_waitcnt vmcnt(11)
	v_cvt_pk_f32_fp8_e32 v[232:233], v164
	v_cvt_pk_f32_fp8_sdwa v[234:235], v164 src0_sel:WORD_1
	v_pk_fma_f32 v[216:217], v[72:73], v[232:233], v[216:217] op_sel_hi:[0,1,1]
	v_pk_fma_f32 v[218:219], v[72:73], v[234:235], v[218:219] op_sel_hi:[0,1,1]
	v_cvt_pk_f32_fp8_e32 v[236:237], v165
	v_cvt_pk_f32_fp8_sdwa v[238:239], v165 src0_sel:WORD_1
	v_pk_fma_f32 v[220:221], v[72:73], v[236:237], v[220:221] op_sel_hi:[0,1,1]
	v_pk_fma_f32 v[222:223], v[72:73], v[238:239], v[222:223] op_sel_hi:[0,1,1]
	v_cvt_pk_f32_fp8_e32 v[232:233], v166
	v_cvt_pk_f32_fp8_sdwa v[234:235], v166 src0_sel:WORD_1
	v_pk_fma_f32 v[224:225], v[72:73], v[232:233], v[224:225] op_sel_hi:[0,1,1]
	v_pk_fma_f32 v[226:227], v[72:73], v[234:235], v[226:227] op_sel_hi:[0,1,1]
	v_cvt_pk_f32_fp8_e32 v[236:237], v167
	v_cvt_pk_f32_fp8_sdwa v[238:239], v167 src0_sel:WORD_1
	v_pk_fma_f32 v[228:229], v[72:73], v[236:237], v[228:229] op_sel_hi:[0,1,1]
	v_pk_fma_f32 v[230:231], v[72:73], v[238:239], v[230:231] op_sel_hi:[0,1,1]
	s_waitcnt vmcnt(10)
	v_cvt_pk_f32_fp8_e32 v[232:233], v168
	v_cvt_pk_f32_fp8_sdwa v[234:235], v168 src0_sel:WORD_1
	v_pk_fma_f32 v[216:217], v[72:73], v[232:233], v[216:217] op_sel:[1,0,0]
	v_pk_fma_f32 v[218:219], v[72:73], v[234:235], v[218:219] op_sel:[1,0,0]
	v_cvt_pk_f32_fp8_e32 v[236:237], v169
	v_cvt_pk_f32_fp8_sdwa v[238:239], v169 src0_sel:WORD_1
	v_pk_fma_f32 v[220:221], v[72:73], v[236:237], v[220:221] op_sel:[1,0,0]
	v_pk_fma_f32 v[222:223], v[72:73], v[238:239], v[222:223] op_sel:[1,0,0]
	v_cvt_pk_f32_fp8_e32 v[232:233], v170
	v_cvt_pk_f32_fp8_sdwa v[234:235], v170 src0_sel:WORD_1
	v_pk_fma_f32 v[224:225], v[72:73], v[232:233], v[224:225] op_sel:[1,0,0]
	v_pk_fma_f32 v[226:227], v[72:73], v[234:235], v[226:227] op_sel:[1,0,0]
	v_cvt_pk_f32_fp8_e32 v[236:237], v171
	v_cvt_pk_f32_fp8_sdwa v[238:239], v171 src0_sel:WORD_1
	v_pk_fma_f32 v[228:229], v[72:73], v[236:237], v[228:229] op_sel:[1,0,0]
	v_pk_fma_f32 v[230:231], v[72:73], v[238:239], v[230:231] op_sel:[1,0,0]
	s_waitcnt vmcnt(9)
	v_cvt_pk_f32_fp8_e32 v[232:233], v172
	v_cvt_pk_f32_fp8_sdwa v[234:235], v172 src0_sel:WORD_1
	v_pk_fma_f32 v[216:217], v[74:75], v[232:233], v[216:217] op_sel_hi:[0,1,1]
	v_pk_fma_f32 v[218:219], v[74:75], v[234:235], v[218:219] op_sel_hi:[0,1,1]
	v_cvt_pk_f32_fp8_e32 v[236:237], v173
	v_cvt_pk_f32_fp8_sdwa v[238:239], v173 src0_sel:WORD_1
	v_pk_fma_f32 v[220:221], v[74:75], v[236:237], v[220:221] op_sel_hi:[0,1,1]
	v_pk_fma_f32 v[222:223], v[74:75], v[238:239], v[222:223] op_sel_hi:[0,1,1]
	v_cvt_pk_f32_fp8_e32 v[232:233], v174
	v_cvt_pk_f32_fp8_sdwa v[234:235], v174 src0_sel:WORD_1
	v_pk_fma_f32 v[224:225], v[74:75], v[232:233], v[224:225] op_sel_hi:[0,1,1]
	v_pk_fma_f32 v[226:227], v[74:75], v[234:235], v[226:227] op_sel_hi:[0,1,1]
	v_cvt_pk_f32_fp8_e32 v[236:237], v175
	v_cvt_pk_f32_fp8_sdwa v[238:239], v175 src0_sel:WORD_1
	v_pk_fma_f32 v[228:229], v[74:75], v[236:237], v[228:229] op_sel_hi:[0,1,1]
	v_pk_fma_f32 v[230:231], v[74:75], v[238:239], v[230:231] op_sel_hi:[0,1,1]
	s_waitcnt vmcnt(8)
; DI f2_t cvt8lo(unsigned w) { return __builtin_amdgcn_cvt_pk_f32_fp8(w, false); }
; DI f2_t cvt8hi(unsigned w) { return __builtin_amdgcn_cvt_pk_f32_fp8(w, true); }
; DI void phase11(const Params& p, char* smem, int rep) {
;     ...
;         for (int k = 0; k < 16; ++k) rows[k] = *(const u32x4*)(vb + (size_t)ida[k] * 2048);
; #pragma unroll
;         for (int k = 0; k < 16; ++k) {
;           const f2_t a2 = {aa[k], aa[k]};
; #pragma unroll
;           for (int d = 0; d < 4; ++d) { const unsigned ww = rows[k][d]; o[2 * d] += a2 * cvt8lo(ww); o[2 * d + 1] += a2 * cvt8hi(ww); }
;         }
	v_cvt_pk_f32_fp8_e32 v[232:233], v176
	v_cvt_pk_f32_fp8_sdwa v[234:235], v176 src0_sel:WORD_1
	v_pk_fma_f32 v[216:217], v[74:75], v[232:233], v[216:217] op_sel:[1,0,0]
	v_pk_fma_f32 v[218:219], v[74:75], v[234:235], v[218:219] op_sel:[1,0,0]
	v_cvt_pk_f32_fp8_e32 v[236:237], v177
	v_cvt_pk_f32_fp8_sdwa v[238:239], v177 src0_sel:WORD_1
	v_pk_fma_f32 v[220:221], v[74:75], v[236:237], v[220:221] op_sel:[1,0,0]
	v_pk_fma_f32 v[222:223], v[74:75], v[238:239], v[222:223] op_sel:[1,0,0]
	v_cvt_pk_f32_fp8_e32 v[232:233], v178
	v_cvt_pk_f32_fp8_sdwa v[234:235], v178 src0_sel:WORD_1
	v_pk_fma_f32 v[224:225], v[74:75], v[232:233], v[224:225] op_sel:[1,0,0]
	v_pk_fma_f32 v[226:227], v[74:75], v[234:235], v[226:227] op_sel:[1,0,0]
	v_cvt_pk_f32_fp8_e32 v[236:237], v179
	v_cvt_pk_f32_fp8_sdwa v[238:239], v179 src0_sel:WORD_1
	v_pk_fma_f32 v[228:229], v[74:75], v[236:237], v[228:229] op_sel:[1,0,0]
	v_pk_fma_f32 v[230:231], v[74:75], v[238:239], v[230:231] op_sel:[1,0,0]
	s_waitcnt vmcnt(7)
	v_cvt_pk_f32_fp8_e32 v[232:233], v180
	v_cvt_pk_f32_fp8_sdwa v[234:235], v180 src0_sel:WORD_1
	v_pk_fma_f32 v[216:217], v[76:77], v[232:233], v[216:217] op_sel_hi:[0,1,1]
	v_pk_fma_f32 v[218:219], v[76:77], v[234:235], v[218:219] op_sel_hi:[0,1,1]
	v_cvt_pk_f32_fp8_e32 v[236:237], v181
	v_cvt_pk_f32_fp8_sdwa v[238:239], v181 src0_sel:WORD_1
	v_pk_fma_f32 v[220:221], v[76:77], v[236:237], v[220:221] op_sel_hi:[0,1,1]
	v_pk_fma_f32 v[222:223], v[76:77], v[238:239], v[222:223] op_sel_hi:[0,1,1]
	v_cvt_pk_f32_fp8_e32 v[232:233], v182
	v_cvt_pk_f32_fp8_sdwa v[234:235], v182 src0_sel:WORD_1
	v_pk_fma_f32 v[224:225], v[76:77], v[232:233], v[224:225] op_sel_hi:[0,1,1]
	v_pk_fma_f32 v[226:227], v[76:77], v[234:235], v[226:227] op_sel_hi:[0,1,1]
	v_cvt_pk_f32_fp8_e32 v[236:237], v183
	v_cvt_pk_f32_fp8_sdwa v[238:239], v183 src0_sel:WORD_1
	v_pk_fma_f32 v[228:229], v[76:77], v[236:237], v[228:229] op_sel_hi:[0,1,1]
	v_pk_fma_f32 v[230:231], v[76:77], v[238:239], v[230:231] op_sel_hi:[0,1,1]
	s_waitcnt vmcnt(6)
	v_cvt_pk_f32_fp8_e32 v[232:233], v184
	v_cvt_pk_f32_fp8_sdwa v[234:235], v184 src0_sel:WORD_1
	v_pk_fma_f32 v[216:217], v[76:77], v[232:233], v[216:217] op_sel:[1,0,0]
	v_pk_fma_f32 v[218:219], v[76:77], v[234:235], v[218:219] op_sel:[1,0,0]
	v_cvt_pk_f32_fp8_e32 v[236:237], v185
	v_cvt_pk_f32_fp8_sdwa v[238:239], v185 src0_sel:WORD_1
	v_pk_fma_f32 v[220:221], v[76:77], v[236:237], v[220:221] op_sel:[1,0,0]
	v_pk_fma_f32 v[222:223], v[76:77], v[238:239], v[222:223] op_sel:[1,0,0]
	v_cvt_pk_f32_fp8_e32 v[232:233], v186
	v_cvt_pk_f32_fp8_sdwa v[234:235], v186 src0_sel:WORD_1
	v_pk_fma_f32 v[224:225], v[76:77], v[232:233], v[224:225] op_sel:[1,0,0]
	v_pk_fma_f32 v[226:227], v[76:77], v[234:235], v[226:227] op_sel:[1,0,0]
	v_cvt_pk_f32_fp8_e32 v[236:237], v187
	v_cvt_pk_f32_fp8_sdwa v[238:239], v187 src0_sel:WORD_1
	v_pk_fma_f32 v[228:229], v[76:77], v[236:237], v[228:229] op_sel:[1,0,0]
	v_pk_fma_f32 v[230:231], v[76:77], v[238:239], v[230:231] op_sel:[1,0,0]
	s_waitcnt vmcnt(5)
	v_cvt_pk_f32_fp8_e32 v[232:233], v190
	v_cvt_pk_f32_fp8_sdwa v[234:235], v190 src0_sel:WORD_1
	v_pk_fma_f32 v[216:217], v[78:79], v[232:233], v[216:217] op_sel_hi:[0,1,1]
	v_pk_fma_f32 v[218:219], v[78:79], v[234:235], v[218:219] op_sel_hi:[0,1,1]
	v_cvt_pk_f32_fp8_e32 v[236:237], v191
	v_cvt_pk_f32_fp8_sdwa v[238:239], v191 src0_sel:WORD_1
	v_pk_fma_f32 v[220:221], v[78:79], v[236:237], v[220:221] op_sel_hi:[0,1,1]
	v_pk_fma_f32 v[222:223], v[78:79], v[238:239], v[222:223] op_sel_hi:[0,1,1]
	v_cvt_pk_f32_fp8_e32 v[232:233], v192
	v_cvt_pk_f32_fp8_sdwa v[234:235], v192 src0_sel:WORD_1
	v_pk_fma_f32 v[224:225], v[78:79], v[232:233], v[224:225] op_sel_hi:[0,1,1]
	v_pk_fma_f32 v[226:227], v[78:79], v[234:235], v[226:227] op_sel_hi:[0,1,1]
	v_cvt_pk_f32_fp8_e32 v[236:237], v193
	v_cvt_pk_f32_fp8_sdwa v[238:239], v193 src0_sel:WORD_1
	v_pk_fma_f32 v[228:229], v[78:79], v[236:237], v[228:229] op_sel_hi:[0,1,1]
	v_pk_fma_f32 v[230:231], v[78:79], v[238:239], v[230:231] op_sel_hi:[0,1,1]
	s_waitcnt vmcnt(4)
	v_cvt_pk_f32_fp8_e32 v[232:233], v194
	v_cvt_pk_f32_fp8_sdwa v[234:235], v194 src0_sel:WORD_1
	v_pk_fma_f32 v[216:217], v[78:79], v[232:233], v[216:217] op_sel:[1,0,0]
	v_pk_fma_f32 v[218:219], v[78:79], v[234:235], v[218:219] op_sel:[1,0,0]
	v_cvt_pk_f32_fp8_e32 v[236:237], v195
	v_cvt_pk_f32_fp8_sdwa v[238:239], v195 src0_sel:WORD_1
	v_pk_fma_f32 v[220:221], v[78:79], v[236:237], v[220:221] op_sel:[1,0,0]
	v_pk_fma_f32 v[222:223], v[78:79], v[238:239], v[222:223] op_sel:[1,0,0]
	v_cvt_pk_f32_fp8_e32 v[232:233], v196
	v_cvt_pk_f32_fp8_sdwa v[234:235], v196 src0_sel:WORD_1
	v_pk_fma_f32 v[224:225], v[78:79], v[232:233], v[224:225] op_sel:[1,0,0]
	v_pk_fma_f32 v[226:227], v[78:79], v[234:235], v[226:227] op_sel:[1,0,0]
	v_cvt_pk_f32_fp8_e32 v[236:237], v197
	v_cvt_pk_f32_fp8_sdwa v[238:239], v197 src0_sel:WORD_1
	v_pk_fma_f32 v[228:229], v[78:79], v[236:237], v[228:229] op_sel:[1,0,0]
	v_pk_fma_f32 v[230:231], v[78:79], v[238:239], v[230:231] op_sel:[1,0,0]
	s_waitcnt vmcnt(3)
; DI unsigned pk2(float a, float b) { f2_t v = {a, b}; bf2_t r = __builtin_convertvector(v, bf2_t); return __builtin_bit_cast(unsigned, r); }
; DI f2_t cvt8lo(unsigned w) { return __builtin_amdgcn_cvt_pk_f32_fp8(w, false); }
; DI f2_t cvt8hi(unsigned w) { return __builtin_amdgcn_cvt_pk_f32_fp8(w, true); }
; DI void phase11(const Params& p, char* smem, int rep) {
;     ...
;   xcd_queue((unsigned*)(p.ws + WS_BAR) + CTR_VQ + rep * 8, 512, smem, [&](int s, int c) __attribute__((always_inline)) {
; #pragma unroll 1
;     for (int t = 0; t < 4; ++t) {
;       const int tok = __builtin_amdgcn_readfirstlane(c * 16 + w * 4 + t);
;     ...
;           for (int d = 0; d < 4; ++d) { const unsigned ww = rows[k][d]; o[2 * d] += a2 * cvt8lo(ww); o[2 * d + 1] += a2 * cvt8hi(ww); }
;         }
;       }
;       float ov[16];
; #pragma unroll
;       for (int d = 0; d < 4; ++d) { ov[4 * d] = o[2 * d].x; ov[4 * d + 1] = o[2 * d].y; ov[4 * d + 2] = o[2 * d + 1].x; ov[4 * d + 3] = o[2 * d + 1].y; }
;       float q8[8], q4[4];
; #pragma unroll
;       for (int k = 0; k < 8; ++k) q8[k] = (b5 ? ov[8 + k] : ov[k]) + __shfl_xor(b5 ? ov[k] : ov[8 + k], 32);
; #pragma unroll
;       for (int k = 0; k < 4; ++k) q4[k] = (b4 ? q8[4 + k] : q8[k]) + __shfl_xor(b4 ? q8[k] : q8[4 + k], 16);
;       *(uint2*)(OUTP + (size_t)tok * D_ + s * 256 + l15 * 16 + 8 * b5 + 4 * b4) = make_uint2(pk2(q4[0], q4[1]), pk2(q4[2], q4[3]));
;     }
	v_cvt_pk_f32_fp8_e32 v[232:233], v198
	v_cvt_pk_f32_fp8_sdwa v[234:235], v198 src0_sel:WORD_1
	v_pk_fma_f32 v[216:217], v[80:81], v[232:233], v[216:217] op_sel_hi:[0,1,1]
	v_pk_fma_f32 v[218:219], v[80:81], v[234:235], v[218:219] op_sel_hi:[0,1,1]
	v_cvt_pk_f32_fp8_e32 v[236:237], v199
	v_cvt_pk_f32_fp8_sdwa v[238:239], v199 src0_sel:WORD_1
	v_pk_fma_f32 v[220:221], v[80:81], v[236:237], v[220:221] op_sel_hi:[0,1,1]
	v_pk_fma_f32 v[222:223], v[80:81], v[238:239], v[222:223] op_sel_hi:[0,1,1]
	v_cvt_pk_f32_fp8_e32 v[232:233], v200
	v_cvt_pk_f32_fp8_sdwa v[234:235], v200 src0_sel:WORD_1
	v_pk_fma_f32 v[224:225], v[80:81], v[232:233], v[224:225] op_sel_hi:[0,1,1]
	v_pk_fma_f32 v[226:227], v[80:81], v[234:235], v[226:227] op_sel_hi:[0,1,1]
	v_cvt_pk_f32_fp8_e32 v[236:237], v201
	v_cvt_pk_f32_fp8_sdwa v[238:239], v201 src0_sel:WORD_1
	v_pk_fma_f32 v[228:229], v[80:81], v[236:237], v[228:229] op_sel_hi:[0,1,1]
	v_pk_fma_f32 v[230:231], v[80:81], v[238:239], v[230:231] op_sel_hi:[0,1,1]
	s_waitcnt vmcnt(2)
	v_cvt_pk_f32_fp8_e32 v[232:233], v202
	v_cvt_pk_f32_fp8_sdwa v[234:235], v202 src0_sel:WORD_1
	v_pk_fma_f32 v[216:217], v[80:81], v[232:233], v[216:217] op_sel:[1,0,0]
	v_pk_fma_f32 v[218:219], v[80:81], v[234:235], v[218:219] op_sel:[1,0,0]
	v_cvt_pk_f32_fp8_e32 v[236:237], v203
	v_cvt_pk_f32_fp8_sdwa v[238:239], v203 src0_sel:WORD_1
	v_pk_fma_f32 v[220:221], v[80:81], v[236:237], v[220:221] op_sel:[1,0,0]
	v_pk_fma_f32 v[222:223], v[80:81], v[238:239], v[222:223] op_sel:[1,0,0]
	v_cvt_pk_f32_fp8_e32 v[232:233], v204
	v_cvt_pk_f32_fp8_sdwa v[234:235], v204 src0_sel:WORD_1
	v_pk_fma_f32 v[224:225], v[80:81], v[232:233], v[224:225] op_sel:[1,0,0]
	v_pk_fma_f32 v[226:227], v[80:81], v[234:235], v[226:227] op_sel:[1,0,0]
	v_cvt_pk_f32_fp8_e32 v[236:237], v205
	v_cvt_pk_f32_fp8_sdwa v[238:239], v205 src0_sel:WORD_1
	v_pk_fma_f32 v[228:229], v[80:81], v[236:237], v[228:229] op_sel:[1,0,0]
	v_pk_fma_f32 v[230:231], v[80:81], v[238:239], v[230:231] op_sel:[1,0,0]
	s_waitcnt vmcnt(1)
	v_cvt_pk_f32_fp8_e32 v[232:233], v206
	v_cvt_pk_f32_fp8_sdwa v[234:235], v206 src0_sel:WORD_1
	v_pk_fma_f32 v[216:217], v[82:83], v[232:233], v[216:217] op_sel_hi:[0,1,1]
	v_pk_fma_f32 v[218:219], v[82:83], v[234:235], v[218:219] op_sel_hi:[0,1,1]
	v_cvt_pk_f32_fp8_e32 v[236:237], v207
	v_cvt_pk_f32_fp8_sdwa v[238:239], v207 src0_sel:WORD_1
	v_pk_fma_f32 v[220:221], v[82:83], v[236:237], v[220:221] op_sel_hi:[0,1,1]
	v_pk_fma_f32 v[222:223], v[82:83], v[238:239], v[222:223] op_sel_hi:[0,1,1]
	v_cvt_pk_f32_fp8_e32 v[232:233], v208
	v_cvt_pk_f32_fp8_sdwa v[234:235], v208 src0_sel:WORD_1
	v_pk_fma_f32 v[224:225], v[82:83], v[232:233], v[224:225] op_sel_hi:[0,1,1]
	v_pk_fma_f32 v[226:227], v[82:83], v[234:235], v[226:227] op_sel_hi:[0,1,1]
	v_cvt_pk_f32_fp8_e32 v[236:237], v209
	v_cvt_pk_f32_fp8_sdwa v[238:239], v209 src0_sel:WORD_1
	v_pk_fma_f32 v[228:229], v[82:83], v[236:237], v[228:229] op_sel_hi:[0,1,1]
	v_pk_fma_f32 v[230:231], v[82:83], v[238:239], v[230:231] op_sel_hi:[0,1,1]
	s_waitcnt vmcnt(0)
	v_cvt_pk_f32_fp8_e32 v[232:233], v210
	v_cvt_pk_f32_fp8_sdwa v[234:235], v210 src0_sel:WORD_1
	v_pk_fma_f32 v[216:217], v[82:83], v[232:233], v[216:217] op_sel:[1,0,0]
	v_pk_fma_f32 v[218:219], v[82:83], v[234:235], v[218:219] op_sel:[1,0,0]
	v_cvt_pk_f32_fp8_e32 v[236:237], v211
	v_cvt_pk_f32_fp8_sdwa v[238:239], v211 src0_sel:WORD_1
	v_pk_fma_f32 v[220:221], v[82:83], v[236:237], v[220:221] op_sel:[1,0,0]
	v_pk_fma_f32 v[222:223], v[82:83], v[238:239], v[222:223] op_sel:[1,0,0]
	v_cvt_pk_f32_fp8_e32 v[232:233], v212
	v_cvt_pk_f32_fp8_sdwa v[234:235], v212 src0_sel:WORD_1
	v_pk_fma_f32 v[224:225], v[82:83], v[232:233], v[224:225] op_sel:[1,0,0]
	v_pk_fma_f32 v[226:227], v[82:83], v[234:235], v[226:227] op_sel:[1,0,0]
	v_cvt_pk_f32_fp8_e32 v[236:237], v213
	v_cvt_pk_f32_fp8_sdwa v[238:239], v213 src0_sel:WORD_1
	v_pk_fma_f32 v[228:229], v[82:83], v[236:237], v[228:229] op_sel:[1,0,0]
	v_pk_fma_f32 v[230:231], v[82:83], v[238:239], v[230:231] op_sel:[1,0,0]
	ds_read_b128 v[52:55], v6 offset:528
	ds_read_b128 v[56:59], v6 offset:544
	ds_read_b128 v[60:63], v6 offset:560
	ds_read_b128 v[64:67], v6 offset:576
	ds_read_b128 v[68:71], v6 offset:592
	ds_read_b128 v[72:75], v6 offset:608
	ds_read_b128 v[76:79], v6 offset:624
	ds_read_b128 v[80:83], v6 offset:640
	v_add_u32_e32 v214, s46, v4
	s_nop 0
	v_permlane32_swap_b32_e32 v216, v224
	v_permlane32_swap_b32_e32 v217, v225
	v_permlane32_swap_b32_e32 v218, v226
	v_permlane32_swap_b32_e32 v219, v227
	v_permlane32_swap_b32_e32 v220, v228
	v_permlane32_swap_b32_e32 v221, v229
	v_permlane32_swap_b32_e32 v222, v230
	v_permlane32_swap_b32_e32 v223, v231
	v_add_f32_e32 v216, v216, v224
	v_add_f32_e32 v217, v217, v225
	v_add_f32_e32 v218, v218, v226
	v_add_f32_e32 v219, v219, v227
	v_add_f32_e32 v220, v220, v228
	v_add_f32_e32 v221, v221, v229
	v_add_f32_e32 v222, v222, v230
	v_add_f32_e32 v223, v223, v231
	s_nop 1
	v_permlane16_swap_b32_e32 v216, v220
	v_permlane16_swap_b32_e32 v217, v221
	v_permlane16_swap_b32_e32 v218, v222
	v_permlane16_swap_b32_e32 v219, v223
	v_add_f32_e32 v216, v216, v220
	v_add_f32_e32 v217, v217, v221
	v_add_f32_e32 v218, v218, v222
	v_add_f32_e32 v219, v219, v223
	v_cvt_pk_bf16_f32 v232, v216, v217
	v_cvt_pk_bf16_f32 v233, v218, v219
	global_store_dwordx2 v214, v[232:233], s[14:15] nt
	s_add_i32 s48, s48, 1
	s_add_i32 s34, s34, 4
	s_cmp_lt_u32 s48, s49
	s_cbranch_scc0 .Lp11_chunk_done
	s_cmp_lt_u32 s34, 8192
	s_cbranch_scc1 .Lp11_body
	s_branch .Lp11_slice_next

; DI float bflo(unsigned u) { return __uint_as_float(u << 16); }
; DI float bfhi(unsigned u) { return __uint_as_float(u & 0xffff0000u); }
; DI void phase12(const Params& p) {
;     ...
;   for (int row = blockIdx.x * 4 + w; row < T_; row += gridDim.x * 4) {
;     const float* gt = mod + (row >> 11) * 12288 + 5 * 2048;
;     float4 v[8];
;     float ss = 0.f;
; #pragma unroll
;     for (int j = 0; j < 8; ++j) {
;       const int d = j * 256 + lane * 4;
;       const uint2 xb2 = *(const uint2*)(X1 + (size_t)row * D_ + d);
;       const float4 xv = make_float4(bflo(xb2.x), bfhi(xb2.x), bflo(xb2.y), bfhi(xb2.y)), gv = *(const float4*)(gt + d);
;       const uint2 ob = *(const uint2*)(OUTP + (size_t)row * D_ + d);
;       const float4 ov = make_float4(bflo(ob.x), bfhi(ob.x), bflo(ob.y), bfhi(ob.y));
;       v[j] = make_float4(xv.x + gv.x * ov.x, xv.y + gv.y * ov.y, xv.z + gv.z * ov.z, xv.w + gv.w * ov.w);
;       ss += v[j].x * v[j].x + v[j].y * v[j].y + v[j].z * v[j].z + v[j].w * v[j].w;
;     }
.LBB0_1325:
	v_ashrrev_i32_e32 v36, 11, v4
	v_ashrrev_i32_e32 v5, 31, v4
	v_mul_i32_i24_e32 v38, 0x3000, v36
	v_lshlrev_b64 v[36:37], 12, v[4:5]
	v_lshlrev_b64 v[48:49], 13, v[4:5]
	v_ashrrev_i32_e32 v39, 31, v38
	v_lshl_add_u64 v[50:51], v[18:19], 0, v[36:37]
	v_lshl_add_u64 v[52:53], v[20:21], 0, v[36:37]
	v_lshl_add_u64 v[36:37], s[80:81], 0, v[48:49]
	v_lshl_add_u64 v[48:49], v[38:39], 2, s[82:83]
	global_load_dwordx4 v[0:3], v[8:9], off
	global_load_dwordx2 v[80:81], v[50:51], off nt
	global_load_dwordx2 v[82:83], v[52:53], off nt
	global_load_dwordx2 v[84:85], v[50:51], off offset:512 nt
	global_load_dwordx2 v[86:87], v[52:53], off offset:512 nt
	global_load_dwordx2 v[88:89], v[50:51], off offset:1024 nt
	global_load_dwordx2 v[90:91], v[52:53], off offset:1024 nt
	global_load_dwordx2 v[92:93], v[50:51], off offset:1536 nt
	global_load_dwordx2 v[94:95], v[52:53], off offset:1536 nt
	global_load_dwordx2 v[96:97], v[50:51], off offset:2048 nt
	global_load_dwordx2 v[98:99], v[52:53], off offset:2048 nt
	global_load_dwordx2 v[100:101], v[50:51], off offset:2560 nt
	global_load_dwordx2 v[102:103], v[52:53], off offset:2560 nt
	global_load_dwordx2 v[104:105], v[50:51], off offset:3072 nt
	v_lshl_add_u64 v[48:49], v[48:49], 0, s[2:3]
	global_load_dwordx2 v[106:107], v[50:51], off offset:3584 nt
	global_load_dwordx2 v[108:109], v[52:53], off offset:3072 nt
	global_load_dwordx2 v[110:111], v[52:53], off offset:3584 nt
	s_waitcnt vmcnt(37)
	v_lshl_add_u64 v[112:113], v[48:49], 0, v[22:23]
	s_waitcnt vmcnt(17)
	v_lshl_add_u64 v[114:115], v[48:49], 0, v[24:25]
	v_lshl_add_u64 v[116:117], v[48:49], 0, v[26:27]
	v_lshl_add_u64 v[118:119], v[48:49], 0, v[28:29]
	v_lshl_add_u64 v[120:121], v[48:49], 0, v[6:7]
	v_lshl_add_u64 v[122:123], v[48:49], 0, v[30:31]
	v_lshl_add_u64 v[124:125], v[48:49], 0, v[32:33]
	v_lshl_add_u64 v[126:127], v[48:49], 0, v[34:35]
	global_load_dwordx4 v[48:51], v[112:113], off
	global_load_dwordx4 v[52:55], v[114:115], off
	global_load_dwordx4 v[56:59], v[116:117], off
	global_load_dwordx4 v[60:63], v[118:119], off
	global_load_dwordx4 v[64:67], v[120:121], off
	global_load_dwordx4 v[68:71], v[122:123], off
	global_load_dwordx4 v[72:75], v[124:125], off
	global_load_dwordx4 v[76:79], v[126:127], off
	v_lshl_add_u64 v[38:39], v[36:37], 0, v[22:23]
	v_add_u32_e32 v4, s4, v4
	s_waitcnt vmcnt(23)
	v_lshlrev_b32_e32 v112, 16, v80
	v_and_b32_e32 v113, 0xffff0000, v80
	s_waitcnt vmcnt(22)
	v_lshlrev_b32_e32 v114, 16, v82
	v_and_b32_e32 v115, 0xffff0000, v82
	s_waitcnt vmcnt(21)
	v_lshlrev_b32_e32 v116, 16, v84
	v_and_b32_e32 v117, 0xffff0000, v84
	s_waitcnt vmcnt(20)
	v_lshlrev_b32_e32 v118, 16, v86
	v_and_b32_e32 v119, 0xffff0000, v86
	v_lshlrev_b32_e32 v80, 16, v81
	v_and_b32_e32 v81, 0xffff0000, v81
	v_lshlrev_b32_e32 v82, 16, v83
	v_and_b32_e32 v83, 0xffff0000, v83
	v_lshlrev_b32_e32 v84, 16, v85
	v_and_b32_e32 v85, 0xffff0000, v85
	v_lshlrev_b32_e32 v86, 16, v87
	v_and_b32_e32 v87, 0xffff0000, v87
	s_waitcnt vmcnt(19)
	v_lshlrev_b32_e32 v120, 16, v88
	v_and_b32_e32 v121, 0xffff0000, v88
	s_waitcnt vmcnt(18)
	v_lshlrev_b32_e32 v122, 16, v90
	v_and_b32_e32 v123, 0xffff0000, v90
	s_waitcnt vmcnt(7)
	v_pk_fma_f32 v[48:49], v[48:49], v[114:115], v[112:113]
	s_waitcnt vmcnt(6)
	v_pk_fma_f32 v[52:53], v[52:53], v[118:119], v[116:117]
	v_lshlrev_b32_e32 v88, 16, v89
	v_and_b32_e32 v89, 0xffff0000, v89
	v_lshlrev_b32_e32 v90, 16, v91
	v_and_b32_e32 v91, 0xffff0000, v91
	v_lshlrev_b32_e32 v124, 16, v92
	v_and_b32_e32 v125, 0xffff0000, v92
	v_lshlrev_b32_e32 v126, 16, v94
	v_and_b32_e32 v127, 0xffff0000, v94
	v_lshlrev_b32_e32 v128, 16, v96
	v_and_b32_e32 v129, 0xffff0000, v96
	v_lshlrev_b32_e32 v130, 16, v98
	v_and_b32_e32 v131, 0xffff0000, v98
	v_lshlrev_b32_e32 v132, 16, v100
	v_and_b32_e32 v133, 0xffff0000, v100
	v_lshlrev_b32_e32 v134, 16, v102
	v_and_b32_e32 v135, 0xffff0000, v102
	v_pk_fma_f32 v[50:51], v[50:51], v[82:83], v[80:81]
	v_pk_fma_f32 v[54:55], v[54:55], v[86:87], v[84:85]
	s_waitcnt vmcnt(5)
	v_pk_fma_f32 v[56:57], v[56:57], v[122:123], v[120:121]
	v_pk_mul_f32 v[80:81], v[48:49], v[48:49]
	v_pk_mul_f32 v[84:85], v[52:53], v[52:53]
	v_lshlrev_b32_e32 v92, 16, v93
	v_and_b32_e32 v93, 0xffff0000, v93
	v_lshlrev_b32_e32 v94, 16, v95
	v_and_b32_e32 v95, 0xffff0000, v95
	v_lshlrev_b32_e32 v96, 16, v97
	v_and_b32_e32 v97, 0xffff0000, v97
	v_lshlrev_b32_e32 v98, 16, v99
	v_and_b32_e32 v99, 0xffff0000, v99
	v_pk_fma_f32 v[58:59], v[58:59], v[90:91], v[88:89]
	s_waitcnt vmcnt(4)
	v_pk_fma_f32 v[60:61], v[60:61], v[126:127], v[124:125]
	s_waitcnt vmcnt(3)
	v_pk_fma_f32 v[64:65], v[64:65], v[130:131], v[128:129]
	s_waitcnt vmcnt(2)
	v_pk_fma_f32 v[68:69], v[68:69], v[134:135], v[132:133]
	v_pk_mul_f32 v[82:83], v[50:51], v[50:51]
	v_pk_mul_f32 v[86:87], v[54:55], v[54:55]
	v_pk_mul_f32 v[88:89], v[56:57], v[56:57]
	v_add_f32_e32 v5, v84, v85
	v_add_f32_e32 v47, v80, v81
	v_lshlrev_b32_e32 v100, 16, v101
	v_and_b32_e32 v101, 0xffff0000, v101
	v_lshlrev_b32_e32 v102, 16, v103
	v_and_b32_e32 v103, 0xffff0000, v103
	v_lshlrev_b32_e32 v136, 16, v104
	v_and_b32_e32 v137, 0xffff0000, v104
	v_lshlrev_b32_e32 v138, 16, v108
	v_and_b32_e32 v139, 0xffff0000, v108
	v_lshlrev_b32_e32 v140, 16, v106
	v_and_b32_e32 v141, 0xffff0000, v106
	v_lshlrev_b32_e32 v142, 16, v110
	v_and_b32_e32 v143, 0xffff0000, v110
	v_pk_fma_f32 v[62:63], v[62:63], v[94:95], v[92:93]
	v_pk_fma_f32 v[66:67], v[66:67], v[98:99], v[96:97]
	v_pk_mul_f32 v[90:91], v[58:59], v[58:59]
	v_pk_mul_f32 v[92:93], v[60:61], v[60:61]
	v_mov_b32_e32 v98, v65
	v_mov_b32_e32 v99, v69
	v_add_f32_e32 v88, v88, v89
	v_add_f32_e32 v5, v5, v86
	v_add_f32_e32 v47, v47, v82
	v_lshlrev_b32_e32 v106, 16, v107
	v_and_b32_e32 v107, 0xffff0000, v107
	v_lshlrev_b32_e32 v110, 16, v111
	v_and_b32_e32 v111, 0xffff0000, v111
	v_pk_fma_f32 v[70:71], v[70:71], v[102:103], v[100:101]
	s_waitcnt vmcnt(1)
; DI void phase12(const Params& p) {
;     ...
;       ss += v[j].x * v[j].x + v[j].y * v[j].y + v[j].z * v[j].z + v[j].w * v[j].w;
;     }
;     ss = wave_sum(ss);
;     const float rstd = rsqrtf(ss * (1.f / D_) + EPS);
; #pragma unroll
;     for (int j = 0; j < 8; ++j) {
;       const int d = j * 256 + lane * 4;
;       const float4 gv = *(const float4*)(gfin + d);
;       { const f32x4v t = {v[j].x * rstd * gv.x, v[j].y * rstd * gv.y, v[j].z * rstd * gv.z, v[j].w * rstd * gv.w}; __builtin_nontemporal_store(t, (f32x4v*)(p.out + (size_t)row * D_ + d)); }
;     }
;   }
	v_pk_fma_f32 v[72:73], v[72:73], v[138:139], v[136:137]
	s_waitcnt vmcnt(0)
	v_pk_fma_f32 v[76:77], v[76:77], v[142:143], v[140:141]
	v_pk_mul_f32 v[94:95], v[62:63], v[62:63]
	v_mov_b32_e32 v96, v64
	v_mov_b32_e32 v97, v68
	v_pk_mul_f32 v[98:99], v[98:99], v[98:99]
	v_add_f32_e32 v89, v92, v93
	v_add_f32_e32 v82, v88, v90
	v_add_f32_e32 v5, v87, v5
	v_add_f32_e32 v47, v83, v47
	v_lshlrev_b32_e32 v104, 16, v105
	v_and_b32_e32 v105, 0xffff0000, v105
	v_lshlrev_b32_e32 v108, 16, v109
	v_and_b32_e32 v109, 0xffff0000, v109
	v_pk_fma_f32 v[78:79], v[78:79], v[110:111], v[106:107]
	v_mov_b32_e32 v100, v66
	v_mov_b32_e32 v101, v70
	v_mov_b32_e32 v106, v73
	v_mov_b32_e32 v107, v77
	v_pk_fma_f32 v[80:81], v[96:97], v[96:97], v[98:99]
	v_add_f32_e32 v86, v89, v94
	v_add_f32_e32 v87, v91, v82
	v_add_f32_e32 v5, v47, v5
	v_pk_fma_f32 v[74:75], v[74:75], v[108:109], v[104:105]
	v_mov_b32_e32 v102, v67
	v_mov_b32_e32 v103, v71
	v_mov_b32_e32 v104, v72
	v_mov_b32_e32 v105, v76
	v_pk_mul_f32 v[106:107], v[106:107], v[106:107]
	v_pk_fma_f32 v[80:81], v[100:101], v[100:101], v[80:81]
	v_add_f32_e32 v86, v95, v86
	v_add_f32_e32 v5, v5, v87
	v_mov_b32_e32 v108, v74
	v_mov_b32_e32 v109, v78
	v_pk_fma_f32 v[84:85], v[104:105], v[104:105], v[106:107]
	v_pk_fma_f32 v[80:81], v[102:103], v[102:103], v[80:81]
	v_add_f32_e32 v5, v5, v86
	v_mov_b32_e32 v110, v75
	v_mov_b32_e32 v111, v79
	v_pk_fma_f32 v[84:85], v[108:109], v[108:109], v[84:85]
	v_add_f32_e32 v5, v5, v80
	v_pk_fma_f32 v[82:83], v[110:111], v[110:111], v[84:85]
	v_add_f32_e32 v5, v5, v81
	v_add_f32_e32 v5, v5, v82
	v_add_f32_e32 v5, v5, v83
	ds_bpermute_b32 v47, v40, v5
	s_waitcnt lgkmcnt(0)
	v_add_f32_e32 v5, v5, v47
	ds_bpermute_b32 v47, v41, v5
	s_waitcnt lgkmcnt(0)
	v_add_f32_e32 v5, v5, v47
	ds_bpermute_b32 v47, v42, v5
	s_waitcnt lgkmcnt(0)
	v_add_f32_e32 v5, v5, v47
	ds_bpermute_b32 v47, v43, v5
	s_waitcnt lgkmcnt(0)
	v_add_f32_e32 v5, v5, v47
	ds_bpermute_b32 v47, v44, v5
	s_waitcnt lgkmcnt(0)
	v_add_f32_e32 v5, v5, v47
	ds_bpermute_b32 v47, v45, v5
	s_waitcnt lgkmcnt(0)
	v_add_f32_e32 v5, v5, v47
	v_fmamk_f32 v5, v5, 0x3a000000, v46
	v_mul_f32_e32 v47, 0x4b800000, v5
	v_cmp_gt_f32_e32 vcc, s5, v5
	s_nop 1
	v_cndmask_b32_e32 v5, v5, v47, vcc
	v_rsq_f32_e32 v5, v5
	s_nop 0
	v_mul_f32_e32 v47, 0x45800000, v5
	v_cndmask_b32_e32 v80, v5, v47, vcc
	v_pk_mul_f32 v[48:49], v[48:49], v[80:81] op_sel_hi:[1,0]
	v_pk_mul_f32 v[50:51], v[50:51], v[80:81] op_sel_hi:[1,0]
	v_pk_mul_f32 v[0:1], v[0:1], v[48:49]
	v_pk_mul_f32 v[2:3], v[2:3], v[50:51]
	global_store_dwordx4 v[38:39], v[0:3], off nt
	global_load_dwordx4 v[0:3], v[8:9], off offset:1024
	v_pk_mul_f32 v[48:49], v[54:55], v[80:81] op_sel_hi:[1,0]
	v_pk_mul_f32 v[50:51], v[52:53], v[80:81] op_sel_hi:[1,0]
	v_cmp_lt_i32_e32 vcc, s6, v4
	s_or_b64 s[0:1], vcc, s[0:1]
	s_waitcnt vmcnt(0)
	v_pk_mul_f32 v[0:1], v[0:1], v[50:51]
	v_pk_mul_f32 v[2:3], v[2:3], v[48:49]
	global_store_dwordx4 v[38:39], v[0:3], off offset:1024 nt
	global_load_dwordx4 v[0:3], v[8:9], off offset:2048
	v_pk_mul_f32 v[48:49], v[58:59], v[80:81] op_sel_hi:[1,0]
	v_pk_mul_f32 v[50:51], v[56:57], v[80:81] op_sel_hi:[1,0]
	s_waitcnt vmcnt(0)
	v_pk_mul_f32 v[2:3], v[2:3], v[48:49]
	v_pk_mul_f32 v[0:1], v[0:1], v[50:51]
	global_store_dwordx4 v[38:39], v[0:3], off offset:2048 nt
	global_load_dwordx4 v[0:3], v[8:9], off offset:3072
	v_pk_mul_f32 v[48:49], v[60:61], v[80:81] op_sel_hi:[1,0]
	v_pk_mul_f32 v[50:51], v[62:63], v[80:81] op_sel_hi:[1,0]
	s_waitcnt vmcnt(0)
	v_pk_mul_f32 v[0:1], v[0:1], v[48:49]
	v_pk_mul_f32 v[2:3], v[50:51], v[2:3]
	global_store_dwordx4 v[38:39], v[0:3], off offset:3072 nt
	global_load_dwordx4 v[0:3], v[10:11], off
	v_pk_mul_f32 v[48:49], v[66:67], v[80:81] op_sel_hi:[1,0]
	v_pk_mul_f32 v[50:51], v[64:65], v[80:81] op_sel_hi:[1,0]
	v_lshl_add_u64 v[38:39], v[36:37], 0, v[6:7]
	s_waitcnt vmcnt(0)
	v_pk_mul_f32 v[0:1], v[50:51], v[0:1]
	v_pk_mul_f32 v[2:3], v[48:49], v[2:3]
	global_store_dwordx4 v[38:39], v[0:3], off nt
	global_load_dwordx4 v[0:3], v[12:13], off
	v_pk_mul_f32 v[48:49], v[70:71], v[80:81] op_sel_hi:[1,0]
	v_pk_mul_f32 v[50:51], v[68:69], v[80:81] op_sel_hi:[1,0]
	v_lshl_add_u64 v[38:39], v[36:37], 0, v[30:31]
	s_waitcnt vmcnt(0)
	v_pk_mul_f32 v[0:1], v[50:51], v[0:1]
	v_pk_mul_f32 v[2:3], v[48:49], v[2:3]
	global_store_dwordx4 v[38:39], v[0:3], off nt
	global_load_dwordx4 v[0:3], v[14:15], off
	v_pk_mul_f32 v[48:49], v[74:75], v[80:81] op_sel_hi:[1,0]
	v_pk_mul_f32 v[50:51], v[72:73], v[80:81] op_sel_hi:[1,0]
	v_lshl_add_u64 v[38:39], v[36:37], 0, v[32:33]
	v_lshl_add_u64 v[36:37], v[36:37], 0, v[34:35]
	s_waitcnt vmcnt(0)
	v_pk_mul_f32 v[0:1], v[50:51], v[0:1]
	v_pk_mul_f32 v[2:3], v[48:49], v[2:3]
	global_store_dwordx4 v[38:39], v[0:3], off nt
	global_load_dwordx4 v[0:3], v[16:17], off
	v_pk_mul_f32 v[38:39], v[78:79], v[80:81] op_sel_hi:[1,0]
	v_pk_mul_f32 v[48:49], v[76:77], v[80:81] op_sel_hi:[1,0]
	s_waitcnt vmcnt(0)
	v_pk_mul_f32 v[2:3], v[38:39], v[2:3]
	v_pk_mul_f32 v[0:1], v[48:49], v[0:1]
	global_store_dwordx4 v[36:37], v[0:3], off nt
	s_andn2_b64 exec, exec, s[0:1]
	s_cbranch_execnz .LBB0_1325
